# GEMM K loops software-pipelined: LDS fragment reads half a step ahead, LDS-DMA issue interleaved with MFMAs, all 5 big GEMM sites
# speedup vs baseline: 1.0806x; 1.0306x over previous
; #define LAS __attribute__((address_space(3)))
;   int tid = tid_in; asm volatile("" : "+v"(tid));
;   const int lane = tid & 63, wid = __builtin_amdgcn_readfirstlane(tid >> 6), wr = wid >> 1, wc = wid & 1;
;   const int m0 = mt * 128, n0 = nt * 256;
;   const int r = lane & 31, h = lane >> 5, key = (r >> 2) & 3;
;   constexpr int STG = 24576;
;   const int rowl = lane >> 2, cch = (lane & 3) ^ ((lane >> 4) & 3);
;   const unsigned voffA = (unsigned)(rowl * lda * 2 + cch * 16), voffB = (unsigned)(rowl * K * 2 + cch * 16);
;   const char* Abase = (const char*)(A + (size_t)m0 * lda) + (size_t)(wid * 2) * 32 * lda;
;   const char* Bbase = (const char*)(Bt + (size_t)n0 * K) + (size_t)(wid * 4) * 32 * K;
;   const size_t ablk = (size_t)32 * lda, bblk = (size_t)32 * K;
;   LAS char* lds = (LAS char*)smem;
;   LAS char* ldsA = lds + (wid * 2) * 1024;
;   LAS char* ldsB = lds + 8192 + (wid * 4) * 1024;
;     ...
;   const int x0 = ((0 + h) ^ key) * 16, x1 = ((2 + h) ^ key) * 16;
;   const int a_rd = (wr * 64 + r) * 64, b_rd = 8192 + (wc * 128 + r) * 64;
;   f32x16 acc[2][4];
; #pragma unroll
;   for (int i = 0; i < 2; ++i)
; #pragma unroll
;     for (int j = 0; j < 4; ++j)
; #pragma unroll
;       for (int e = 0; e < 16; ++e) acc[i][j][e] = 0.f;
;   const int nk = K >> 5;
;   DMA_STEP_(0, 0);
;   DMA_STEP_(1, STG);
;   asm volatile("s_waitcnt vmcnt(6)" ::: "memory");
;   __builtin_amdgcn_s_barrier();
;   asm volatile("" ::: "memory");
;   int s0 = 0, s2 = 2 * STG;
.LBB0_20:
	s_ashr_i32 s10, s23, 31
	s_lshr_b32 s10, s10, 27
	s_add_i32 s10, s23, s10
	s_ashr_i32 s10, s10, 5
	v_readlane_b32 s11, v252, 18
	v_mov_b32_e32 v189, v188
	s_lshl_b32 s11, s10, s11
	v_readlane_b32 s12, v252, 41
	s_add_i32 s11, s11, s12
	v_readfirstlane_b32 s44, v189
	s_ashr_i32 s46, s44, 6
	s_lshl_b32 s12, s23, 7
	s_lshl_b32 s11, s11, 10
	s_and_b32 s12, s12, 0x380
	s_lshl_b32 s28, s46, 1
	s_or_b32 s12, s11, s12
	s_lshl_b32 s10, s10, 10
	s_lshl_b32 s11, s23, 5
	s_ashr_i32 s29, s28, 31
	s_sub_i32 s10, s11, s10
	s_lshl_b64 s[40:41], s[28:29], 15
	s_lshl_b32 s28, s46, 2
	s_ashr_i32 s11, s44, 1
	s_and_b32 s14, s10, 0xffffff00
	v_and_b32_e32 v0, 31, v189
	s_ashr_i32 s29, s28, 31
	s_lshl_b32 s10, s46, 12
	s_andn2_b32 s11, s11, 63
	v_lshlrev_b32_e32 v2, 4, v189
	s_ashr_i32 s13, s12, 31
	s_lshl_b64 s[42:43], s[28:29], 10
	s_add_i32 s29, s10, 16
	v_or_b32_e32 v197, s11, v0
	s_lshl_b32 s11, s46, 7
	v_bitop3_b32 v2, v2, 48, v189 bitop3:0x48
	v_lshlrev_b32_e32 v3, 9, v189
	s_ashr_i32 s15, s14, 31
	s_add_i32 s10, s29, 0x2000
	s_and_b32 s28, s11, 0x80
	s_movk_i32 s11, 0x7800
	s_lshl_b64 s[44:45], s[12:13], 11
	v_or_b32_e32 v4, s28, v0
	v_and_or_b32 v0, v3, s11, v2
	v_lshlrev_b32_e32 v10, 4, v189
	v_and_b32_e32 v10, 0x3c0, v10
	v_or_b32_e32 v10, v10, v2
	v_mov_b32_e32 v11, 0
	s_add_u32 s11, s21, s44
	s_addc_u32 s13, s22, s45
	s_add_u32 s40, s11, s40
	s_addc_u32 s41, s13, s41
	s_lshl_b64 s[44:45], s[14:15], 6
	s_add_u32 s11, s17, s44
	s_addc_u32 s13, s18, s45
	s_add_u32 s42, s11, s42
	s_addc_u32 s43, s13, s43
	s_lshl_b32 s11, s46, 11
	s_sub_i32 s13, s29, s11
	v_lshl_add_u64 v[192:193], s[40:41], 0, v[0:1]
	s_mov_b32 m0, s13
	v_lshl_add_u64 v[2:3], v[192:193], 0, s[72:73]
	global_load_lds_dwordx4 v0, s[40:41]
	s_add_i32 m0, s13, 0x400
	v_lshl_add_u64 v[194:195], s[42:43], 0, v[10:11]
	global_load_lds_dwordx4 v[2:3], off
	s_mov_b32 m0, s10
	s_nop 0
	global_load_lds_dwordx4 v[194:195], off
	global_load_lds_dwordx4 v[194:195], off offset:1024
	global_load_lds_dwordx4 v[194:195], off offset:2048
	global_load_lds_dwordx4 v[194:195], off offset:3072
	s_mov_b64 s[10:11], 0x10000
	s_mov_b64 s[10:11], 0x18000
	s_mov_b64 s[10:11], 0x8040
	s_add_i32 m0, s13, 0x6000
	v_lshl_add_u64 v[2:3], v[192:193], 0, 64
	global_load_lds_dwordx4 v[2:3], off
	v_lshl_add_u64 v[2:3], v[192:193], 0, s[10:11]
	s_add_i32 m0, s13, 0x6400
	v_bfe_u32 v196, v189, 5, 1
	global_load_lds_dwordx4 v[2:3], off
	s_add_i32 m0, s29, 0x8000
	s_mov_b32 s100, 0x10000
	v_lshl_add_u64 v[2:3], v[194:195], 0, s[100:101]
	global_load_lds_dwordx4 v[2:3], off
	global_load_lds_dwordx4 v[2:3], off offset:1024
	global_load_lds_dwordx4 v[2:3], off offset:2048
	global_load_lds_dwordx4 v[2:3], off offset:3072
	s_mov_b64 s[10:11], 0x10040
	s_mov_b64 s[10:11], 0x18040
	v_lshlrev_b32_e32 v218, 6, v4
	v_bfe_u32 v4, v189, 2, 2
	v_lshrrev_b32_e32 v5, 5, v189
	s_lshl_b32 s100, s100, 1
	v_lshl_add_u64 v[194:195], v[194:195], 0, s[100:101]
	s_waitcnt vmcnt(6)
	s_barrier
	v_bitop3_b32 v2, v196, v4, 2 bitop3:0x36
	v_bitop3_b32 v0, v5, v4, 1 bitop3:0x6c
	v_lshlrev_b32_e32 v220, 4, v2
	v_mov_b32_e32 v2, 0
	v_lshlrev_b32_e32 v219, 6, v197
	v_lshlrev_b32_e32 v0, 4, v0
	s_mov_b32 s41, 0xc000
	s_mov_b32 s40, 0
	s_mov_b32 s42, 0
	v_mov_b32_e32 v3, v2
	v_mov_b32_e32 v4, v2
	v_mov_b32_e32 v5, v2
	v_mov_b32_e32 v6, v2
	v_mov_b32_e32 v7, v2
	v_mov_b32_e32 v8, v2
	v_mov_b32_e32 v9, v2
	v_mov_b32_e32 v10, v2
	v_mov_b32_e32 v11, v2
	v_mov_b32_e32 v12, v2
	v_mov_b32_e32 v13, v2
	v_mov_b32_e32 v14, v2
	v_mov_b32_e32 v15, v2
	v_mov_b32_e32 v16, v2
	v_mov_b32_e32 v17, v2
	v_mov_b32_e32 v18, v2
	v_mov_b32_e32 v19, v2
	v_mov_b32_e32 v20, v2
	v_mov_b32_e32 v21, v2
	v_mov_b32_e32 v22, v2
	v_mov_b32_e32 v23, v2
	v_mov_b32_e32 v24, v2
	v_mov_b32_e32 v25, v2
	v_mov_b32_e32 v26, v2
	v_mov_b32_e32 v27, v2
	v_mov_b32_e32 v28, v2
	v_mov_b32_e32 v29, v2
	v_mov_b32_e32 v30, v2
	v_mov_b32_e32 v31, v2
	v_mov_b32_e32 v32, v2
	v_mov_b32_e32 v33, v2
	v_mov_b32_e32 v50, v2
	v_mov_b32_e32 v51, v2
	v_mov_b32_e32 v52, v2
	v_mov_b32_e32 v53, v2
	v_mov_b32_e32 v54, v2
	v_mov_b32_e32 v55, v2
	v_mov_b32_e32 v56, v2
	v_mov_b32_e32 v57, v2
	v_mov_b32_e32 v58, v2
	v_mov_b32_e32 v59, v2
	v_mov_b32_e32 v60, v2
	v_mov_b32_e32 v61, v2
	v_mov_b32_e32 v62, v2
	v_mov_b32_e32 v63, v2
	v_mov_b32_e32 v64, v2
	v_mov_b32_e32 v65, v2
	v_mov_b32_e32 v82, v2
	v_mov_b32_e32 v83, v2
	v_mov_b32_e32 v84, v2
	v_mov_b32_e32 v85, v2
	v_mov_b32_e32 v86, v2
	v_mov_b32_e32 v87, v2
	v_mov_b32_e32 v88, v2
	v_mov_b32_e32 v89, v2
	s_waitcnt vmcnt(0)
	v_mov_b32_e32 v90, v2
	v_mov_b32_e32 v91, v2
	v_mov_b32_e32 v92, v2
	v_mov_b32_e32 v93, v2
	v_mov_b32_e32 v94, v2
	v_mov_b32_e32 v95, v2
	v_mov_b32_e32 v96, v2
	v_mov_b32_e32 v97, v2
	v_mov_b32_e32 v34, v2
	v_mov_b32_e32 v35, v2
	v_mov_b32_e32 v36, v2
	v_mov_b32_e32 v37, v2
	v_mov_b32_e32 v38, v2
	v_mov_b32_e32 v39, v2
	v_mov_b32_e32 v40, v2
	v_mov_b32_e32 v41, v2
	v_mov_b32_e32 v42, v2
	v_mov_b32_e32 v43, v2
	v_mov_b32_e32 v44, v2
	v_mov_b32_e32 v45, v2
	v_mov_b32_e32 v46, v2
	v_mov_b32_e32 v47, v2
	v_mov_b32_e32 v48, v2
	v_mov_b32_e32 v49, v2
	v_mov_b32_e32 v66, v2
	v_mov_b32_e32 v67, v2
	v_mov_b32_e32 v68, v2
	v_mov_b32_e32 v69, v2
	v_mov_b32_e32 v70, v2
	v_mov_b32_e32 v71, v2
	v_mov_b32_e32 v72, v2
	v_mov_b32_e32 v73, v2
	v_mov_b32_e32 v74, v2
	v_mov_b32_e32 v75, v2
	v_mov_b32_e32 v76, v2
	v_mov_b32_e32 v77, v2
	v_mov_b32_e32 v78, v2
	v_mov_b32_e32 v79, v2
	v_mov_b32_e32 v80, v2
	v_mov_b32_e32 v81, v2
	v_mov_b32_e32 v98, v2
	v_mov_b32_e32 v99, v2
	v_mov_b32_e32 v100, v2
	v_mov_b32_e32 v101, v2
	v_mov_b32_e32 v102, v2
	v_mov_b32_e32 v103, v2
	v_mov_b32_e32 v104, v2
	v_mov_b32_e32 v105, v2
	v_mov_b32_e32 v106, v2
	v_mov_b32_e32 v107, v2
	v_mov_b32_e32 v108, v2
	v_mov_b32_e32 v109, v2
	v_mov_b32_e32 v110, v2
	v_mov_b32_e32 v111, v2
	v_mov_b32_e32 v112, v2
	v_mov_b32_e32 v113, v2
	v_mov_b32_e32 v114, v2
	v_mov_b32_e32 v115, v2
	v_mov_b32_e32 v116, v2
	v_mov_b32_e32 v117, v2
	v_mov_b32_e32 v118, v2
	v_mov_b32_e32 v119, v2
	v_mov_b32_e32 v120, v2
	v_mov_b32_e32 v121, v2
	v_mov_b32_e32 v122, v2
	v_mov_b32_e32 v123, v2
	v_mov_b32_e32 v124, v2
	v_mov_b32_e32 v125, v2
	v_mov_b32_e32 v126, v2
	v_mov_b32_e32 v127, v2
	v_mov_b32_e32 v128, v2
	v_mov_b32_e32 v129, v2
	v_add_u32_e32 v158, 16, v219
	v_add_u32_e32 v170, 16, v218
	v_add_u32_e32 v158, v158, v0
	v_add_u32_e32 v170, v170, v0
	ds_read_b128 v[154:157], v158
	ds_read_b128 v[182:185], v170 offset:8192
	ds_read_b128 v[178:181], v170 offset:10240
	ds_read_b128 v[158:161], v158 offset:2048
	ds_read_b128 v[174:177], v170 offset:12288
	ds_read_b128 v[170:173], v170 offset:14336
; #define LAS __attribute__((address_space(3)))
; DI f32x16 mfma32(bf16x8 a, bf16x8 b, f32x16 c) { return __builtin_amdgcn_mfma_f32_32x32x16_bf16(a, b, c, 0, 0, 0); }
;     ...
;   for (int kt = 0; kt < nk; ++kt) {
;     const int kn = (kt + 2 < nk) ? (kt + 2) : (nk - 1);
;     const LAS char* cur = lds + s0;
;     bf16x8 af[2][2], bfr[2][4];
; #pragma unroll
;     for (int kk = 0; kk < 2; ++kk) {
;       const int xo = kk ? x1 : x0;
;       af[kk][0] = *(const LAS bf16x8*)(cur + a_rd + xo);
;       bfr[kk][0] = *(const LAS bf16x8*)(cur + b_rd + xo);
;       bfr[kk][1] = *(const LAS bf16x8*)(cur + b_rd + 2048 + xo);
;       af[kk][1] = *(const LAS bf16x8*)(cur + a_rd + 2048 + xo);
;       bfr[kk][2] = *(const LAS bf16x8*)(cur + b_rd + 4096 + xo);
;       bfr[kk][3] = *(const LAS bf16x8*)(cur + b_rd + 6144 + xo);
;     }
;     DMA_STEP_(kn, s2);
; #pragma unroll
;     for (int kk = 0; kk < 2; ++kk) {
;       acc[0][0] = mfma32(bfr[kk][0], af[kk][0], acc[0][0]); acc[0][1] = mfma32(bfr[kk][1], af[kk][0], acc[0][1]);
;       acc[1][0] = mfma32(bfr[kk][0], af[kk][1], acc[1][0]); acc[1][1] = mfma32(bfr[kk][1], af[kk][1], acc[1][1]);
;       acc[0][2] = mfma32(bfr[kk][2], af[kk][0], acc[0][2]); acc[0][3] = mfma32(bfr[kk][3], af[kk][0], acc[0][3]);
;       acc[1][2] = mfma32(bfr[kk][2], af[kk][1], acc[1][2]); acc[1][3] = mfma32(bfr[kk][3], af[kk][1], acc[1][3]);
;     }
;     __builtin_amdgcn_sched_group_barrier(0x100, 12, 0);
;     __builtin_amdgcn_sched_group_barrier(0x010, 6, 0);
;     __builtin_amdgcn_sched_group_barrier(0x008, 16, 0);
;     asm volatile("s_waitcnt vmcnt(6) lgkmcnt(0)" ::: "memory");
;     __builtin_amdgcn_s_barrier();
;     asm volatile("" ::: "memory");
;     s0 = (s0 == 2 * STG) ? 0 : s0 + STG;
;     s2 = (s2 == 2 * STG) ? 0 : s2 + STG;
;   }
.LBB0_21:
	s_add_i32 s11, s42, 16
	s_mov_b32 s10, s40
	v_add_u32_e32 v142, s11, v219
	v_add_u32_e32 v150, s11, v218
	s_min_u32 s10, s10, 29
	v_add_u32_e32 v142, v142, v220
	v_add_u32_e32 v150, v150, v220
	s_lshl_b32 s70, s10, 6
	ds_read_b128 v[138:141], v142
	ds_read_b128 v[162:165], v150 offset:8192
	ds_read_b128 v[166:169], v150 offset:10240
	ds_read_b128 v[142:145], v142 offset:2048
	ds_read_b128 v[146:149], v150 offset:12288
	ds_read_b128 v[150:153], v150 offset:14336
	v_lshl_add_u64 v[222:223], v[192:193], 0, s[70:71]
	s_add_i32 s10, s13, s41
	v_lshl_add_u64 v[224:225], v[222:223], 0, s[24:25]
	s_mov_b32 m0, s10
	v_lshl_add_u64 v[222:223], v[222:223], 0, s[38:39]
	s_mul_i32 s100, s70, 0x400
	s_waitcnt lgkmcnt(6)
	v_mfma_f32_32x32x16_bf16 v[114:129], v[182:185], v[154:157], v[114:129]
	global_load_lds_dwordx4 v[224:225], off
	s_add_i32 m0, s10, 0x400
	v_mfma_f32_32x32x16_bf16 v[98:113], v[178:181], v[154:157], v[98:113]
	global_load_lds_dwordx4 v[222:223], off
	v_lshl_add_u64 v[224:225], v[194:195], 0, s[100:101]
	s_add_i32 s10, s29, s41
	s_add_i32 m0, s10, 0x2000
	v_mfma_f32_32x32x16_bf16 v[66:81], v[182:185], v[158:161], v[66:81]
	global_load_lds_dwordx4 v[224:225], off
	v_mfma_f32_32x32x16_bf16 v[34:49], v[178:181], v[158:161], v[34:49]
	global_load_lds_dwordx4 v[224:225], off offset:1024
	v_mfma_f32_32x32x16_bf16 v[82:97], v[174:177], v[154:157], v[82:97]
	global_load_lds_dwordx4 v[224:225], off offset:2048
	v_mfma_f32_32x32x16_bf16 v[50:65], v[170:173], v[154:157], v[50:65]
	global_load_lds_dwordx4 v[224:225], off offset:3072
	v_mfma_f32_32x32x16_bf16 v[18:33], v[174:177], v[158:161], v[18:33]
	s_add_i32 s10, s42, 0x6000
	s_cmpk_lg_u32 s42, 0xc000
	s_cselect_b32 s42, s10, 0
	s_add_i32 s10, s41, 0x6000
	s_cmpk_lg_u32 s41, 0xc000
	s_cselect_b32 s41, s10, 0
	v_mfma_f32_32x32x16_bf16 v[2:17], v[170:173], v[158:161], v[2:17]
	s_add_i32 s11, s42, 16
	s_waitcnt vmcnt(6) lgkmcnt(0)
	s_barrier
	v_add_u32_e32 v158, s11, v219
	v_add_u32_e32 v170, s11, v218
	v_add_u32_e32 v158, v158, v0
	v_add_u32_e32 v170, v170, v0
	ds_read_b128 v[154:157], v158
	ds_read_b128 v[182:185], v170 offset:8192
	ds_read_b128 v[178:181], v170 offset:10240
	ds_read_b128 v[158:161], v158 offset:2048
	ds_read_b128 v[174:177], v170 offset:12288
	ds_read_b128 v[170:173], v170 offset:14336
	v_mfma_f32_32x32x16_bf16 v[114:129], v[162:165], v[138:141], v[114:129]
	v_mfma_f32_32x32x16_bf16 v[98:113], v[166:169], v[138:141], v[98:113]
	v_mfma_f32_32x32x16_bf16 v[66:81], v[162:165], v[142:145], v[66:81]
	v_mfma_f32_32x32x16_bf16 v[34:49], v[166:169], v[142:145], v[34:49]
	v_mfma_f32_32x32x16_bf16 v[82:97], v[146:149], v[138:141], v[82:97]
	v_mfma_f32_32x32x16_bf16 v[50:65], v[150:153], v[138:141], v[50:65]
	v_mfma_f32_32x32x16_bf16 v[18:33], v[146:149], v[142:145], v[18:33]
	v_mfma_f32_32x32x16_bf16 v[2:17], v[150:153], v[142:145], v[2:17]
	s_add_i32 s11, s42, 16
	s_add_i32 s10, s40, 1
	v_add_u32_e32 v142, s11, v219
	v_add_u32_e32 v150, s11, v218
	s_min_u32 s10, s10, 29
	v_add_u32_e32 v142, v142, v220
	v_add_u32_e32 v150, v150, v220
	s_lshl_b32 s70, s10, 6
	ds_read_b128 v[138:141], v142
	ds_read_b128 v[162:165], v150 offset:8192
	ds_read_b128 v[166:169], v150 offset:10240
	ds_read_b128 v[142:145], v142 offset:2048
	ds_read_b128 v[146:149], v150 offset:12288
	ds_read_b128 v[150:153], v150 offset:14336
	v_lshl_add_u64 v[222:223], v[192:193], 0, s[70:71]
	s_add_i32 s10, s13, s41
	v_lshl_add_u64 v[224:225], v[222:223], 0, s[24:25]
	s_mov_b32 m0, s10
	v_lshl_add_u64 v[222:223], v[222:223], 0, s[38:39]
	s_mul_i32 s100, s70, 0x400
	s_waitcnt lgkmcnt(6)
	v_mfma_f32_32x32x16_bf16 v[114:129], v[182:185], v[154:157], v[114:129]
	global_load_lds_dwordx4 v[224:225], off
	s_add_i32 m0, s10, 0x400
	v_mfma_f32_32x32x16_bf16 v[98:113], v[178:181], v[154:157], v[98:113]
	global_load_lds_dwordx4 v[222:223], off
	v_lshl_add_u64 v[224:225], v[194:195], 0, s[100:101]
	s_add_i32 s10, s29, s41
	s_add_i32 m0, s10, 0x2000
	v_mfma_f32_32x32x16_bf16 v[66:81], v[182:185], v[158:161], v[66:81]
	global_load_lds_dwordx4 v[224:225], off
	v_mfma_f32_32x32x16_bf16 v[34:49], v[178:181], v[158:161], v[34:49]
	global_load_lds_dwordx4 v[224:225], off offset:1024
	v_mfma_f32_32x32x16_bf16 v[82:97], v[174:177], v[154:157], v[82:97]
	global_load_lds_dwordx4 v[224:225], off offset:2048
	v_mfma_f32_32x32x16_bf16 v[50:65], v[170:173], v[154:157], v[50:65]
	global_load_lds_dwordx4 v[224:225], off offset:3072
	v_mfma_f32_32x32x16_bf16 v[18:33], v[174:177], v[158:161], v[18:33]
	s_add_i32 s10, s42, 0x6000
	s_cmpk_lg_u32 s42, 0xc000
	s_cselect_b32 s42, s10, 0
	s_add_i32 s10, s41, 0x6000
	s_cmpk_lg_u32 s41, 0xc000
	s_cselect_b32 s41, s10, 0
	v_mfma_f32_32x32x16_bf16 v[2:17], v[170:173], v[158:161], v[2:17]
	s_add_i32 s11, s42, 16
	s_waitcnt vmcnt(6) lgkmcnt(0)
	s_barrier
	v_add_u32_e32 v158, s11, v219
	v_add_u32_e32 v170, s11, v218
	v_add_u32_e32 v158, v158, v0
	v_add_u32_e32 v170, v170, v0
	ds_read_b128 v[154:157], v158
	ds_read_b128 v[182:185], v170 offset:8192
	ds_read_b128 v[178:181], v170 offset:10240
	ds_read_b128 v[158:161], v158 offset:2048
	ds_read_b128 v[174:177], v170 offset:12288
	ds_read_b128 v[170:173], v170 offset:14336
	v_mfma_f32_32x32x16_bf16 v[114:129], v[162:165], v[138:141], v[114:129]
	v_mfma_f32_32x32x16_bf16 v[98:113], v[166:169], v[138:141], v[98:113]
	v_mfma_f32_32x32x16_bf16 v[66:81], v[162:165], v[142:145], v[66:81]
	v_mfma_f32_32x32x16_bf16 v[34:49], v[166:169], v[142:145], v[34:49]
	v_mfma_f32_32x32x16_bf16 v[82:97], v[146:149], v[138:141], v[82:97]
	v_mfma_f32_32x32x16_bf16 v[50:65], v[150:153], v[138:141], v[50:65]
	v_mfma_f32_32x32x16_bf16 v[18:33], v[146:149], v[142:145], v[18:33]
	v_mfma_f32_32x32x16_bf16 v[2:17], v[150:153], v[142:145], v[2:17]
	s_add_i32 s40, s40, 2
	s_cmp_lg_u32 s40, 32
	s_cbranch_scc1 .LBB0_21
; DI unsigned pk2(float a, float b) { f32x2 v = {a, b}; bf2_t r = __builtin_convertvector(v, bf2_t); return __builtin_bit_cast(unsigned, r); }
;     ...
;   asm volatile("s_waitcnt vmcnt(0)" ::: "memory");
;   __builtin_amdgcn_s_barrier();
;   asm volatile("" ::: "memory");
;     ...
;   {
;     const int h = lane >> 5, cl = lane & 31;
; #pragma unroll
;     for (int i = 0; i < 2; ++i)
; #pragma unroll
;       for (int j = 0; j < 4; ++j)
; #pragma unroll
;         for (int g = 0; g < 4; ++g) {
;           u32x2 w; w.x = pk2(acc[i][j][4 * g], acc[i][j][4 * g + 1]); w.y = pk2(acc[i][j][4 * g + 2], acc[i][j][4 * g + 3]);
;           *(u32x2*)(smem + (wr * 64 + i * 32 + cl) * 528 + (wc * 128 + j * 32 + 8 * g + 4 * h) * 2) = w;
;         }
;   }
;   __syncthreads();
	s_waitcnt lgkmcnt(0)
	v_mul_lo_u32 v0, v197, s55
	v_add_u32_e32 v0, 16, v0
	s_nop 1
	v_cvt_pk_bf16_f32 v114, v114, v115
	v_cvt_pk_bf16_f32 v115, v116, v117
	v_lshlrev_b32_e32 v116, 3, v196
	s_lshl_b32 s10, s28, 1
	v_add3_u32 v0, v0, v116, s10
	v_cvt_pk_bf16_f32 v116, v118, v119
	v_cvt_pk_bf16_f32 v117, v120, v121
	v_cvt_pk_bf16_f32 v98, v98, v99
	v_cvt_pk_bf16_f32 v99, v100, v101
	v_cvt_pk_bf16_f32 v100, v102, v103
	v_cvt_pk_bf16_f32 v101, v104, v105
	v_cvt_pk_bf16_f32 v82, v82, v83
	v_cvt_pk_bf16_f32 v83, v84, v85
	v_cvt_pk_bf16_f32 v84, v86, v87
	v_cvt_pk_bf16_f32 v85, v88, v89
	v_cvt_pk_bf16_f32 v50, v50, v51
	v_cvt_pk_bf16_f32 v51, v52, v53
	v_cvt_pk_bf16_f32 v52, v54, v55
	v_cvt_pk_bf16_f32 v53, v56, v57
	s_waitcnt vmcnt(0)
	s_barrier
	ds_write2_b64 v0, v[114:115], v[116:117] offset1:2
	v_cvt_pk_bf16_f32 v114, v122, v123
	v_cvt_pk_bf16_f32 v115, v124, v125
	v_cvt_pk_bf16_f32 v116, v126, v127
	v_cvt_pk_bf16_f32 v117, v128, v129
	ds_write2_b64 v0, v[98:99], v[100:101] offset0:8 offset1:10
	v_cvt_pk_bf16_f32 v98, v106, v107
	v_cvt_pk_bf16_f32 v99, v108, v109
	v_cvt_pk_bf16_f32 v100, v110, v111
	v_cvt_pk_bf16_f32 v101, v112, v113
	ds_write2_b64 v0, v[82:83], v[84:85] offset0:16 offset1:18
	v_cvt_pk_bf16_f32 v82, v90, v91
	v_cvt_pk_bf16_f32 v83, v92, v93
	v_cvt_pk_bf16_f32 v84, v94, v95
	v_cvt_pk_bf16_f32 v85, v96, v97
	ds_write2_b64 v0, v[50:51], v[52:53] offset0:24 offset1:26
	v_cvt_pk_bf16_f32 v50, v58, v59
	v_cvt_pk_bf16_f32 v51, v60, v61
	v_cvt_pk_bf16_f32 v52, v62, v63
	v_cvt_pk_bf16_f32 v53, v64, v65
	ds_write2_b64 v0, v[114:115], v[116:117] offset0:4 offset1:6
	ds_write2_b64 v0, v[98:99], v[100:101] offset0:12 offset1:14
	ds_write2_b64 v0, v[82:83], v[84:85] offset0:20 offset1:22
	ds_write2_b64 v0, v[50:51], v[52:53] offset0:28 offset1:30
	v_cvt_pk_bf16_f32 v50, v66, v67
	v_cvt_pk_bf16_f32 v51, v68, v69
	v_cvt_pk_bf16_f32 v52, v70, v71
	v_cvt_pk_bf16_f32 v53, v72, v73
	v_add_u32_e32 v0, 0x4000, v0
	v_cvt_pk_bf16_f32 v34, v34, v35
	v_cvt_pk_bf16_f32 v35, v36, v37
	v_cvt_pk_bf16_f32 v36, v38, v39
	v_cvt_pk_bf16_f32 v37, v40, v41
	v_cvt_pk_bf16_f32 v18, v18, v19
	v_cvt_pk_bf16_f32 v19, v20, v21
	v_cvt_pk_bf16_f32 v20, v22, v23
	v_cvt_pk_bf16_f32 v21, v24, v25
	v_cvt_pk_bf16_f32 v2, v2, v3
	v_cvt_pk_bf16_f32 v3, v4, v5
	v_cvt_pk_bf16_f32 v4, v6, v7
	v_cvt_pk_bf16_f32 v5, v8, v9
	ds_write2_b64 v0, v[50:51], v[52:53] offset0:64 offset1:66
	v_cvt_pk_bf16_f32 v50, v74, v75
	v_cvt_pk_bf16_f32 v51, v76, v77
	v_cvt_pk_bf16_f32 v52, v78, v79
	v_cvt_pk_bf16_f32 v53, v80, v81
	ds_write2_b64 v0, v[34:35], v[36:37] offset0:72 offset1:74
	v_cvt_pk_bf16_f32 v34, v42, v43
	v_cvt_pk_bf16_f32 v35, v44, v45
	v_cvt_pk_bf16_f32 v36, v46, v47
	v_cvt_pk_bf16_f32 v37, v48, v49
	ds_write2_b64 v0, v[18:19], v[20:21] offset0:80 offset1:82
	v_cvt_pk_bf16_f32 v18, v26, v27
	v_cvt_pk_bf16_f32 v19, v28, v29
	v_cvt_pk_bf16_f32 v20, v30, v31
	v_cvt_pk_bf16_f32 v21, v32, v33
	ds_write2_b64 v0, v[2:3], v[4:5] offset0:88 offset1:90
	v_cvt_pk_bf16_f32 v2, v10, v11
	v_cvt_pk_bf16_f32 v3, v12, v13
	v_cvt_pk_bf16_f32 v4, v14, v15
	v_cvt_pk_bf16_f32 v5, v16, v17
	s_lshl_b64 s[14:15], s[14:15], 1
	ds_write2_b64 v0, v[50:51], v[52:53] offset0:68 offset1:70
	ds_write2_b64 v0, v[34:35], v[36:37] offset0:76 offset1:78
	ds_write2_b64 v0, v[18:19], v[20:21] offset0:84 offset1:86
	ds_write2_b64 v0, v[2:3], v[4:5] offset0:92 offset1:94
	s_waitcnt vmcnt(0) lgkmcnt(0)
	s_barrier
; #define GAS __attribute__((address_space(1)))
;     ...
;   int tid2 = tid; asm volatile("" : "+v"(tid2));
;   if (EPI == 0) {
; #pragma unroll
;     for (int i = 0; i < 16; ++i) {
;       const int id = tid2 + 256 * i, r = id >> 5, c8 = (id & 31) * 8;
;       const u32x4 v = *(const u32x4*)(smem + r * 528 + c8 * 2);
;       *(GAS u32x4*)(ea.out + (size_t)(m0 + r) * ea.ldo + n0 + c8) = v;
;     }
	s_add_u32 s14, s19, s14
	v_lshlrev_b32_e32 v0, 4, v189
	v_and_b32_e32 v0, 0x1f0, v0
	s_addc_u32 s15, s20, s15
	v_add_u32_e32 v10, 16, v0
	v_lshl_add_u64 v[12:13], s[14:15], 0, v[0:1]
	v_ashrrev_i32_e32 v0, 5, v189
	v_mad_u64_u32 v[2:3], s[14:15], v0, s55, v[10:11]
	ds_read_b128 v[2:5], v2
	v_add_u32_e32 v6, s12, v0
	v_ashrrev_i32_e32 v7, 31, v6
	v_add_u32_e32 v0, 0x100, v189
	v_lshlrev_b64 v[6:7], 11, v[6:7]
	v_ashrrev_i32_e32 v0, 5, v0
	v_lshl_add_u64 v[14:15], v[12:13], 0, v[6:7]
	v_mad_u64_u32 v[6:7], s[14:15], v0, s55, v[10:11]
	ds_read_b128 v[6:9], v6
	s_waitcnt lgkmcnt(1)
	global_store_dwordx4 v[14:15], v[2:5], off
	v_readlane_b32 s10, v252, 12
	s_add_i32 s23, s23, s10
	v_add_u32_e32 v2, s12, v0
	v_ashrrev_i32_e32 v3, 31, v2
	v_lshlrev_b64 v[2:3], 11, v[2:3]
	v_add_u32_e32 v0, 0x200, v189
	v_lshl_add_u64 v[2:3], v[12:13], 0, v[2:3]
	v_ashrrev_i32_e32 v0, 5, v0
	s_waitcnt lgkmcnt(0)
	global_store_dwordx4 v[2:3], v[6:9], off
	v_mad_u64_u32 v[2:3], s[14:15], v0, s55, v[10:11]
	ds_read_b128 v[2:5], v2
	v_add_u32_e32 v6, s12, v0
	v_ashrrev_i32_e32 v7, 31, v6
	v_add_u32_e32 v0, 0x300, v189
	v_lshlrev_b64 v[6:7], 11, v[6:7]
	v_ashrrev_i32_e32 v0, 5, v0
	v_lshl_add_u64 v[14:15], v[12:13], 0, v[6:7]
	v_mad_u64_u32 v[6:7], s[14:15], v0, s55, v[10:11]
	ds_read_b128 v[6:9], v6
	s_waitcnt lgkmcnt(1)
	global_store_dwordx4 v[14:15], v[2:5], off
	s_cmp_ge_i32 s23, s16
	s_nop 0
	v_add_u32_e32 v2, s12, v0
	v_ashrrev_i32_e32 v3, 31, v2
	v_lshlrev_b64 v[2:3], 11, v[2:3]
	v_add_u32_e32 v0, 0x400, v189
	v_lshl_add_u64 v[2:3], v[12:13], 0, v[2:3]
	v_ashrrev_i32_e32 v0, 5, v0
	s_waitcnt lgkmcnt(0)
	global_store_dwordx4 v[2:3], v[6:9], off
	v_mad_u64_u32 v[2:3], s[14:15], v0, s55, v[10:11]
	ds_read_b128 v[2:5], v2
	v_add_u32_e32 v6, s12, v0
	v_ashrrev_i32_e32 v7, 31, v6
	v_add_u32_e32 v0, 0x500, v189
	v_lshlrev_b64 v[6:7], 11, v[6:7]
	v_ashrrev_i32_e32 v0, 5, v0
	v_lshl_add_u64 v[14:15], v[12:13], 0, v[6:7]
	v_mad_u64_u32 v[6:7], s[14:15], v0, s55, v[10:11]
	ds_read_b128 v[6:9], v6
	s_waitcnt lgkmcnt(1)
	global_store_dwordx4 v[14:15], v[2:5], off
	s_nop 1
	v_add_u32_e32 v2, s12, v0
	v_ashrrev_i32_e32 v3, 31, v2
	v_lshlrev_b64 v[2:3], 11, v[2:3]
	v_add_u32_e32 v0, 0x600, v189
	v_lshl_add_u64 v[2:3], v[12:13], 0, v[2:3]
	v_ashrrev_i32_e32 v0, 5, v0
	s_waitcnt lgkmcnt(0)
	global_store_dwordx4 v[2:3], v[6:9], off
	v_mad_u64_u32 v[2:3], s[14:15], v0, s55, v[10:11]
	ds_read_b128 v[2:5], v2
	v_add_u32_e32 v6, s12, v0
	v_ashrrev_i32_e32 v7, 31, v6
	v_add_u32_e32 v0, 0x700, v189
	v_lshlrev_b64 v[6:7], 11, v[6:7]
	v_ashrrev_i32_e32 v0, 5, v0
	v_lshl_add_u64 v[14:15], v[12:13], 0, v[6:7]
	v_mad_u64_u32 v[6:7], s[14:15], v0, s55, v[10:11]
	ds_read_b128 v[6:9], v6
	s_waitcnt lgkmcnt(1)
	global_store_dwordx4 v[14:15], v[2:5], off
	s_nop 1
	v_add_u32_e32 v2, s12, v0
	v_ashrrev_i32_e32 v3, 31, v2
	v_lshlrev_b64 v[2:3], 11, v[2:3]
	v_add_u32_e32 v0, 0x800, v189
	v_lshl_add_u64 v[2:3], v[12:13], 0, v[2:3]
	v_ashrrev_i32_e32 v0, 5, v0
	s_waitcnt lgkmcnt(0)
	global_store_dwordx4 v[2:3], v[6:9], off
	v_mad_u64_u32 v[2:3], s[14:15], v0, s55, v[10:11]
	ds_read_b128 v[2:5], v2
	v_add_u32_e32 v6, s12, v0
	v_ashrrev_i32_e32 v7, 31, v6
	v_add_u32_e32 v0, 0x900, v189
	v_lshlrev_b64 v[6:7], 11, v[6:7]
	v_ashrrev_i32_e32 v0, 5, v0
	v_lshl_add_u64 v[14:15], v[12:13], 0, v[6:7]
	v_mad_u64_u32 v[6:7], s[14:15], v0, s55, v[10:11]
	ds_read_b128 v[6:9], v6
	s_waitcnt lgkmcnt(1)
	global_store_dwordx4 v[14:15], v[2:5], off
	s_nop 1
	v_add_u32_e32 v2, s12, v0
	v_ashrrev_i32_e32 v3, 31, v2
	v_lshlrev_b64 v[2:3], 11, v[2:3]
	v_add_u32_e32 v0, 0xa00, v189
	v_lshl_add_u64 v[2:3], v[12:13], 0, v[2:3]
	v_ashrrev_i32_e32 v0, 5, v0
	s_waitcnt lgkmcnt(0)
	global_store_dwordx4 v[2:3], v[6:9], off
	v_mad_u64_u32 v[2:3], s[14:15], v0, s55, v[10:11]
	ds_read_b128 v[2:5], v2
	v_add_u32_e32 v6, s12, v0
	v_ashrrev_i32_e32 v7, 31, v6
	v_add_u32_e32 v0, 0xb00, v189
	v_lshlrev_b64 v[6:7], 11, v[6:7]
	v_ashrrev_i32_e32 v0, 5, v0
	v_lshl_add_u64 v[14:15], v[12:13], 0, v[6:7]
	v_mad_u64_u32 v[6:7], s[14:15], v0, s55, v[10:11]
	ds_read_b128 v[6:9], v6
	s_waitcnt lgkmcnt(1)
	global_store_dwordx4 v[14:15], v[2:5], off
	s_nop 1
	v_add_u32_e32 v2, s12, v0
	v_ashrrev_i32_e32 v3, 31, v2
	v_lshlrev_b64 v[2:3], 11, v[2:3]
	v_add_u32_e32 v0, 0xc00, v189
	v_lshl_add_u64 v[2:3], v[12:13], 0, v[2:3]
	v_ashrrev_i32_e32 v0, 5, v0
	s_waitcnt lgkmcnt(0)
	global_store_dwordx4 v[2:3], v[6:9], off
	v_mad_u64_u32 v[2:3], s[14:15], v0, s55, v[10:11]
	ds_read_b128 v[2:5], v2
	v_add_u32_e32 v6, s12, v0
	v_ashrrev_i32_e32 v7, 31, v6
	v_add_u32_e32 v0, 0xd00, v189
	v_lshlrev_b64 v[6:7], 11, v[6:7]
	v_ashrrev_i32_e32 v0, 5, v0
	v_lshl_add_u64 v[14:15], v[12:13], 0, v[6:7]
	v_mad_u64_u32 v[6:7], s[14:15], v0, s55, v[10:11]
	ds_read_b128 v[6:9], v6
	s_waitcnt lgkmcnt(1)
	global_store_dwordx4 v[14:15], v[2:5], off
	s_nop 1
	v_add_u32_e32 v2, s12, v0
	v_ashrrev_i32_e32 v3, 31, v2
	v_lshlrev_b64 v[2:3], 11, v[2:3]
	v_add_u32_e32 v0, 0xe00, v189
	v_lshl_add_u64 v[2:3], v[12:13], 0, v[2:3]
	v_ashrrev_i32_e32 v0, 5, v0
	s_waitcnt lgkmcnt(0)
	global_store_dwordx4 v[2:3], v[6:9], off
	v_mad_u64_u32 v[2:3], s[14:15], v0, s55, v[10:11]
	ds_read_b128 v[2:5], v2
	v_add_u32_e32 v6, s12, v0
	v_ashrrev_i32_e32 v7, 31, v6
	v_add_u32_e32 v0, 0xf00, v189
	v_lshlrev_b64 v[6:7], 11, v[6:7]
	v_ashrrev_i32_e32 v0, 5, v0
	v_lshl_add_u64 v[14:15], v[12:13], 0, v[6:7]
	v_mad_u64_u32 v[6:7], s[14:15], v0, s55, v[10:11]
	ds_read_b128 v[6:9], v6
	s_waitcnt lgkmcnt(1)
	global_store_dwordx4 v[14:15], v[2:5], off
	s_nop 1
	v_add_u32_e32 v2, s12, v0
	v_ashrrev_i32_e32 v3, 31, v2
	v_lshlrev_b64 v[2:3], 11, v[2:3]
	v_lshl_add_u64 v[2:3], v[12:13], 0, v[2:3]
	s_waitcnt lgkmcnt(0)
	global_store_dwordx4 v[2:3], v[6:9], off
	s_barrier
	s_cbranch_scc0 .LBB0_20

; #define LAS __attribute__((address_space(3)))
;   int tid = tid_in; asm volatile("" : "+v"(tid));
;   const int lane = tid & 63, wid = __builtin_amdgcn_readfirstlane(tid >> 6), wr = wid >> 1, wc = wid & 1;
;   const int m0 = mt * 128, n0 = nt * 256;
;   const int r = lane & 31, h = lane >> 5, key = (r >> 2) & 3;
;   constexpr int STG = 24576;
;   const int rowl = lane >> 2, cch = (lane & 3) ^ ((lane >> 4) & 3);
;   const unsigned voffA = (unsigned)(rowl * lda * 2 + cch * 16), voffB = (unsigned)(rowl * K * 2 + cch * 16);
;   const char* Abase = (const char*)(A + (size_t)m0 * lda) + (size_t)(wid * 2) * 32 * lda;
;   const char* Bbase = (const char*)(Bt + (size_t)n0 * K) + (size_t)(wid * 4) * 32 * K;
;   const size_t ablk = (size_t)32 * lda, bblk = (size_t)32 * K;
;   LAS char* lds = (LAS char*)smem;
;   LAS char* ldsA = lds + (wid * 2) * 1024;
;   LAS char* ldsB = lds + 8192 + (wid * 4) * 1024;
;     ...
;   const int x0 = ((0 + h) ^ key) * 16, x1 = ((2 + h) ^ key) * 16;
;   const int a_rd = (wr * 64 + r) * 64, b_rd = 8192 + (wc * 128 + r) * 64;
;   f32x16 acc[2][4];
; #pragma unroll
;   for (int i = 0; i < 2; ++i)
; #pragma unroll
;     for (int j = 0; j < 4; ++j)
; #pragma unroll
;       for (int e = 0; e < 16; ++e) acc[i][j][e] = 0.f;
;   const int nk = K >> 5;
;   DMA_STEP_(0, 0);
;   DMA_STEP_(1, STG);
;   asm volatile("s_waitcnt vmcnt(6)" ::: "memory");
;   __builtin_amdgcn_s_barrier();
;   asm volatile("" ::: "memory");
;   int s0 = 0, s2 = 2 * STG;
.LBB0_183:
	s_mul_hi_i32 s10, s20, 0x38e38e39
	s_lshr_b32 s11, s10, 31
	s_ashr_i32 s10, s10, 4
	v_mov_b32_e32 v189, v188
	s_add_i32 s10, s10, s11
	v_readlane_b32 s12, v252, 18
	s_mul_i32 s11, s10, 0xffffffb8
	v_readfirstlane_b32 s21, v189
	s_lshl_b32 s10, s10, s12
	v_readlane_b32 s12, v252, 41
	s_ashr_i32 s44, s21, 6
	s_add_i32 s10, s10, s12
	s_lshl_b32 s12, s20, 7
	s_lshl_b32 s22, s44, 1
	s_add_i32 s11, s11, s20
	s_lshl_b32 s10, s10, 10
	s_and_b32 s12, s12, 0x380
	s_ashr_i32 s23, s22, 31
	s_or_b32 s12, s10, s12
	s_lshl_b32 s10, s11, 5
	s_lshl_b64 s[28:29], s[22:23], 15
	s_lshl_b32 s22, s44, 2
	s_ashr_i32 s11, s21, 1
	s_and_b32 s14, s10, 0xffffff00
	v_and_b32_e32 v0, 31, v189
	s_ashr_i32 s23, s22, 31
	s_lshl_b32 s10, s44, 12
	s_andn2_b32 s11, s11, 63
	v_lshlrev_b32_e32 v2, 4, v189
	s_ashr_i32 s13, s12, 31
	s_lshl_b64 s[40:41], s[22:23], 10
	s_add_i32 s22, s10, 16
	v_or_b32_e32 v197, s11, v0
	s_lshl_b32 s11, s44, 7
	v_bitop3_b32 v2, v2, 48, v189 bitop3:0x48
	v_lshlrev_b32_e32 v3, 9, v189
	s_ashr_i32 s15, s14, 31
	s_add_i32 s10, s22, 0x2000
	s_and_b32 s21, s11, 0x80
	s_movk_i32 s11, 0x7800
	s_lshl_b64 s[42:43], s[12:13], 11
	v_or_b32_e32 v4, s21, v0
	v_and_or_b32 v0, v3, s11, v2
	v_lshlrev_b32_e32 v10, 4, v189
	v_and_b32_e32 v10, 0x3c0, v10
	v_or_b32_e32 v10, v10, v2
	v_mov_b32_e32 v11, 0
	s_add_u32 s11, s18, s42
	s_addc_u32 s13, s19, s43
	s_add_u32 s28, s11, s28
	s_addc_u32 s29, s13, s29
	s_lshl_b64 s[42:43], s[14:15], 6
	v_readlane_b32 s46, v250, 18
	v_readlane_b32 s47, v250, 19
	s_add_u32 s11, s46, s42
	s_addc_u32 s13, s47, s43
	s_add_u32 s40, s11, s40
	s_addc_u32 s41, s13, s41
	s_lshl_b32 s11, s44, 11
	s_sub_i32 s13, s22, s11
	v_lshl_add_u64 v[192:193], s[28:29], 0, v[0:1]
	s_mov_b32 m0, s13
	v_lshl_add_u64 v[2:3], v[192:193], 0, s[72:73]
	global_load_lds_dwordx4 v0, s[28:29]
	s_add_i32 m0, s13, 0x400
	v_lshl_add_u64 v[194:195], s[40:41], 0, v[10:11]
	global_load_lds_dwordx4 v[2:3], off
	s_mov_b32 m0, s10
	s_nop 0
	global_load_lds_dwordx4 v[194:195], off
	global_load_lds_dwordx4 v[194:195], off offset:1024
	global_load_lds_dwordx4 v[194:195], off offset:2048
	global_load_lds_dwordx4 v[194:195], off offset:3072
	s_mov_b64 s[10:11], 0x10000
	s_mov_b64 s[10:11], 0x18000
	s_mov_b64 s[10:11], 0x8040
	s_add_i32 m0, s13, 0x6000
	v_lshl_add_u64 v[2:3], v[192:193], 0, 64
	global_load_lds_dwordx4 v[2:3], off
	v_lshl_add_u64 v[2:3], v[192:193], 0, s[10:11]
	s_add_i32 m0, s13, 0x6400
	v_bfe_u32 v196, v189, 5, 1
	global_load_lds_dwordx4 v[2:3], off
	s_add_i32 m0, s22, 0x8000
	s_mov_b32 s100, 0x24000
	v_lshl_add_u64 v[2:3], v[194:195], 0, s[100:101]
	global_load_lds_dwordx4 v[2:3], off
	global_load_lds_dwordx4 v[2:3], off offset:1024
	global_load_lds_dwordx4 v[2:3], off offset:2048
	global_load_lds_dwordx4 v[2:3], off offset:3072
	s_mov_b64 s[10:11], 0x10040
	s_mov_b64 s[10:11], 0x18040
	v_lshlrev_b32_e32 v218, 6, v4
	v_bfe_u32 v4, v189, 2, 2
	v_lshrrev_b32_e32 v5, 5, v189
	s_lshl_b32 s100, s100, 1
	v_lshl_add_u64 v[194:195], v[194:195], 0, s[100:101]
	s_waitcnt vmcnt(6)
	s_barrier
	v_bitop3_b32 v2, v196, v4, 2 bitop3:0x36
	v_bitop3_b32 v0, v5, v4, 1 bitop3:0x6c
	v_lshlrev_b32_e32 v220, 4, v2
	v_mov_b32_e32 v2, 0
	v_lshlrev_b32_e32 v219, 6, v197
	v_lshlrev_b32_e32 v0, 4, v0
	s_mov_b32 s28, 0xc000
	s_mov_b32 s23, 0
	s_mov_b32 s29, 0
	v_mov_b32_e32 v3, v2
	v_mov_b32_e32 v4, v2
	v_mov_b32_e32 v5, v2
	v_mov_b32_e32 v6, v2
	v_mov_b32_e32 v7, v2
	v_mov_b32_e32 v8, v2
	v_mov_b32_e32 v9, v2
	v_mov_b32_e32 v10, v2
	v_mov_b32_e32 v11, v2
	v_mov_b32_e32 v12, v2
	v_mov_b32_e32 v13, v2
	v_mov_b32_e32 v14, v2
	v_mov_b32_e32 v15, v2
	v_mov_b32_e32 v16, v2
	v_mov_b32_e32 v17, v2
	v_mov_b32_e32 v18, v2
	v_mov_b32_e32 v19, v2
	v_mov_b32_e32 v20, v2
	v_mov_b32_e32 v21, v2
	v_mov_b32_e32 v22, v2
	v_mov_b32_e32 v23, v2
	v_mov_b32_e32 v24, v2
	v_mov_b32_e32 v25, v2
	v_mov_b32_e32 v26, v2
	v_mov_b32_e32 v27, v2
	v_mov_b32_e32 v28, v2
	v_mov_b32_e32 v29, v2
	v_mov_b32_e32 v30, v2
	v_mov_b32_e32 v31, v2
	v_mov_b32_e32 v32, v2
	v_mov_b32_e32 v33, v2
	v_mov_b32_e32 v50, v2
	v_mov_b32_e32 v51, v2
	v_mov_b32_e32 v52, v2
	v_mov_b32_e32 v53, v2
	v_mov_b32_e32 v54, v2
	v_mov_b32_e32 v55, v2
	v_mov_b32_e32 v56, v2
	v_mov_b32_e32 v57, v2
	v_mov_b32_e32 v58, v2
	v_mov_b32_e32 v59, v2
	v_mov_b32_e32 v60, v2
	v_mov_b32_e32 v61, v2
	v_mov_b32_e32 v62, v2
	v_mov_b32_e32 v63, v2
	v_mov_b32_e32 v64, v2
	v_mov_b32_e32 v65, v2
	v_mov_b32_e32 v82, v2
	v_mov_b32_e32 v83, v2
	v_mov_b32_e32 v84, v2
	v_mov_b32_e32 v85, v2
	v_mov_b32_e32 v86, v2
	v_mov_b32_e32 v87, v2
	v_mov_b32_e32 v88, v2
	v_mov_b32_e32 v89, v2
	v_mov_b32_e32 v90, v2
	v_mov_b32_e32 v91, v2
	v_mov_b32_e32 v92, v2
	v_mov_b32_e32 v93, v2
	v_mov_b32_e32 v94, v2
	v_mov_b32_e32 v95, v2
	v_mov_b32_e32 v96, v2
	v_mov_b32_e32 v97, v2
	v_mov_b32_e32 v34, v2
	v_mov_b32_e32 v35, v2
	v_mov_b32_e32 v36, v2
	v_mov_b32_e32 v37, v2
	v_mov_b32_e32 v38, v2
	v_mov_b32_e32 v39, v2
	v_mov_b32_e32 v40, v2
	v_mov_b32_e32 v41, v2
	v_mov_b32_e32 v42, v2
	v_mov_b32_e32 v43, v2
	v_mov_b32_e32 v44, v2
	v_mov_b32_e32 v45, v2
	v_mov_b32_e32 v46, v2
	v_mov_b32_e32 v47, v2
	v_mov_b32_e32 v48, v2
	v_mov_b32_e32 v49, v2
	v_mov_b32_e32 v66, v2
	v_mov_b32_e32 v67, v2
	v_mov_b32_e32 v68, v2
	v_mov_b32_e32 v69, v2
	v_mov_b32_e32 v70, v2
	v_mov_b32_e32 v71, v2
	v_mov_b32_e32 v72, v2
	v_mov_b32_e32 v73, v2
	v_mov_b32_e32 v74, v2
	v_mov_b32_e32 v75, v2
	v_mov_b32_e32 v76, v2
	v_mov_b32_e32 v77, v2
	v_mov_b32_e32 v78, v2
	v_mov_b32_e32 v79, v2
	v_mov_b32_e32 v80, v2
	v_mov_b32_e32 v81, v2
	v_mov_b32_e32 v98, v2
	v_mov_b32_e32 v99, v2
	v_mov_b32_e32 v100, v2
	v_mov_b32_e32 v101, v2
	v_mov_b32_e32 v102, v2
	v_mov_b32_e32 v103, v2
	v_mov_b32_e32 v104, v2
	v_mov_b32_e32 v105, v2
	v_mov_b32_e32 v106, v2
	v_mov_b32_e32 v107, v2
	v_mov_b32_e32 v108, v2
	v_mov_b32_e32 v109, v2
	v_mov_b32_e32 v110, v2
	v_mov_b32_e32 v111, v2
	v_mov_b32_e32 v112, v2
	v_mov_b32_e32 v113, v2
	v_mov_b32_e32 v114, v2
	v_mov_b32_e32 v115, v2
	v_mov_b32_e32 v116, v2
	v_mov_b32_e32 v117, v2
	v_mov_b32_e32 v118, v2
	v_mov_b32_e32 v119, v2
	v_mov_b32_e32 v120, v2
	v_mov_b32_e32 v121, v2
	v_mov_b32_e32 v122, v2
	v_mov_b32_e32 v123, v2
	v_mov_b32_e32 v124, v2
	v_mov_b32_e32 v125, v2
	v_mov_b32_e32 v126, v2
	v_mov_b32_e32 v127, v2
	v_mov_b32_e32 v128, v2
	v_mov_b32_e32 v129, v2
	v_add_u32_e32 v158, 16, v219
	v_add_u32_e32 v170, 16, v218
	v_add_u32_e32 v158, v158, v0
	v_add_u32_e32 v170, v170, v0
	ds_read_b128 v[154:157], v158
	ds_read_b128 v[182:185], v170 offset:8192
	ds_read_b128 v[178:181], v170 offset:10240
	ds_read_b128 v[158:161], v158 offset:2048
	ds_read_b128 v[174:177], v170 offset:12288
	ds_read_b128 v[170:173], v170 offset:14336
; #define LAS __attribute__((address_space(3)))
; DI f32x16 mfma32(bf16x8 a, bf16x8 b, f32x16 c) { return __builtin_amdgcn_mfma_f32_32x32x16_bf16(a, b, c, 0, 0, 0); }
;     ...
;   for (int kt = 0; kt < nk; ++kt) {
;     const int kn = (kt + 2 < nk) ? (kt + 2) : (nk - 1);
;     const LAS char* cur = lds + s0;
;     bf16x8 af[2][2], bfr[2][4];
; #pragma unroll
;     for (int kk = 0; kk < 2; ++kk) {
;       const int xo = kk ? x1 : x0;
;       af[kk][0] = *(const LAS bf16x8*)(cur + a_rd + xo);
;       bfr[kk][0] = *(const LAS bf16x8*)(cur + b_rd + xo);
;       bfr[kk][1] = *(const LAS bf16x8*)(cur + b_rd + 2048 + xo);
;       af[kk][1] = *(const LAS bf16x8*)(cur + a_rd + 2048 + xo);
;       bfr[kk][2] = *(const LAS bf16x8*)(cur + b_rd + 4096 + xo);
;       bfr[kk][3] = *(const LAS bf16x8*)(cur + b_rd + 6144 + xo);
;     }
;     DMA_STEP_(kn, s2);
; #pragma unroll
;     for (int kk = 0; kk < 2; ++kk) {
;       acc[0][0] = mfma32(bfr[kk][0], af[kk][0], acc[0][0]); acc[0][1] = mfma32(bfr[kk][1], af[kk][0], acc[0][1]);
;       acc[1][0] = mfma32(bfr[kk][0], af[kk][1], acc[1][0]); acc[1][1] = mfma32(bfr[kk][1], af[kk][1], acc[1][1]);
;       acc[0][2] = mfma32(bfr[kk][2], af[kk][0], acc[0][2]); acc[0][3] = mfma32(bfr[kk][3], af[kk][0], acc[0][3]);
;       acc[1][2] = mfma32(bfr[kk][2], af[kk][1], acc[1][2]); acc[1][3] = mfma32(bfr[kk][3], af[kk][1], acc[1][3]);
;     }
;     __builtin_amdgcn_sched_group_barrier(0x100, 12, 0);
;     __builtin_amdgcn_sched_group_barrier(0x010, 6, 0);
;     __builtin_amdgcn_sched_group_barrier(0x008, 16, 0);
;     asm volatile("s_waitcnt vmcnt(6) lgkmcnt(0)" ::: "memory");
;     __builtin_amdgcn_s_barrier();
;     asm volatile("" ::: "memory");
;     s0 = (s0 == 2 * STG) ? 0 : s0 + STG;
;     s2 = (s2 == 2 * STG) ? 0 : s2 + STG;
;   }
.LBB0_184:
	s_add_i32 s11, s29, 16
	s_mov_b32 s10, s23
	v_add_u32_e32 v142, s11, v219
	v_add_u32_e32 v150, s11, v218
	s_min_u32 s10, s10, 29
	v_add_u32_e32 v142, v142, v220
	v_add_u32_e32 v150, v150, v220
	s_lshl_b32 s70, s10, 6
	ds_read_b128 v[138:141], v142
	ds_read_b128 v[162:165], v150 offset:8192
	ds_read_b128 v[166:169], v150 offset:10240
	ds_read_b128 v[142:145], v142 offset:2048
	ds_read_b128 v[146:149], v150 offset:12288
	ds_read_b128 v[150:153], v150 offset:14336
	v_lshl_add_u64 v[222:223], v[192:193], 0, s[70:71]
	s_add_i32 s10, s13, s28
	v_lshl_add_u64 v[224:225], v[222:223], 0, s[24:25]
	s_mov_b32 m0, s10
	v_lshl_add_u64 v[222:223], v[222:223], 0, s[38:39]
	s_mul_i32 s100, s70, 0x900
	s_waitcnt lgkmcnt(6)
	v_mfma_f32_32x32x16_bf16 v[114:129], v[182:185], v[154:157], v[114:129]
	global_load_lds_dwordx4 v[224:225], off
	s_add_i32 m0, s10, 0x400
	v_mfma_f32_32x32x16_bf16 v[98:113], v[178:181], v[154:157], v[98:113]
	global_load_lds_dwordx4 v[222:223], off
	v_lshl_add_u64 v[224:225], v[194:195], 0, s[100:101]
	s_add_i32 s10, s22, s28
	s_add_i32 m0, s10, 0x2000
	v_mfma_f32_32x32x16_bf16 v[66:81], v[182:185], v[158:161], v[66:81]
	global_load_lds_dwordx4 v[224:225], off
	v_mfma_f32_32x32x16_bf16 v[34:49], v[178:181], v[158:161], v[34:49]
	global_load_lds_dwordx4 v[224:225], off offset:1024
	v_mfma_f32_32x32x16_bf16 v[82:97], v[174:177], v[154:157], v[82:97]
	global_load_lds_dwordx4 v[224:225], off offset:2048
	v_mfma_f32_32x32x16_bf16 v[50:65], v[170:173], v[154:157], v[50:65]
	global_load_lds_dwordx4 v[224:225], off offset:3072
	v_mfma_f32_32x32x16_bf16 v[18:33], v[174:177], v[158:161], v[18:33]
	s_add_i32 s10, s29, 0x6000
	s_cmpk_lg_u32 s29, 0xc000
	s_cselect_b32 s29, s10, 0
	s_add_i32 s10, s28, 0x6000
	s_cmpk_lg_u32 s28, 0xc000
	s_cselect_b32 s28, s10, 0
	v_mfma_f32_32x32x16_bf16 v[2:17], v[170:173], v[158:161], v[2:17]
	s_add_i32 s11, s29, 16
	s_waitcnt vmcnt(6) lgkmcnt(0)
	s_barrier
	v_add_u32_e32 v158, s11, v219
	v_add_u32_e32 v170, s11, v218
	v_add_u32_e32 v158, v158, v0
	v_add_u32_e32 v170, v170, v0
	ds_read_b128 v[154:157], v158
	ds_read_b128 v[182:185], v170 offset:8192
	ds_read_b128 v[178:181], v170 offset:10240
	ds_read_b128 v[158:161], v158 offset:2048
	ds_read_b128 v[174:177], v170 offset:12288
	ds_read_b128 v[170:173], v170 offset:14336
	v_mfma_f32_32x32x16_bf16 v[114:129], v[162:165], v[138:141], v[114:129]
	v_mfma_f32_32x32x16_bf16 v[98:113], v[166:169], v[138:141], v[98:113]
	v_mfma_f32_32x32x16_bf16 v[66:81], v[162:165], v[142:145], v[66:81]
	v_mfma_f32_32x32x16_bf16 v[34:49], v[166:169], v[142:145], v[34:49]
	v_mfma_f32_32x32x16_bf16 v[82:97], v[146:149], v[138:141], v[82:97]
	v_mfma_f32_32x32x16_bf16 v[50:65], v[150:153], v[138:141], v[50:65]
	v_mfma_f32_32x32x16_bf16 v[18:33], v[146:149], v[142:145], v[18:33]
	v_mfma_f32_32x32x16_bf16 v[2:17], v[150:153], v[142:145], v[2:17]
	s_add_i32 s11, s29, 16
	s_add_i32 s10, s23, 1
	v_add_u32_e32 v142, s11, v219
	v_add_u32_e32 v150, s11, v218
	s_min_u32 s10, s10, 29
	v_add_u32_e32 v142, v142, v220
	v_add_u32_e32 v150, v150, v220
	s_lshl_b32 s70, s10, 6
	ds_read_b128 v[138:141], v142
	ds_read_b128 v[162:165], v150 offset:8192
	ds_read_b128 v[166:169], v150 offset:10240
	ds_read_b128 v[142:145], v142 offset:2048
	ds_read_b128 v[146:149], v150 offset:12288
	ds_read_b128 v[150:153], v150 offset:14336
	v_lshl_add_u64 v[222:223], v[192:193], 0, s[70:71]
	s_add_i32 s10, s13, s28
	v_lshl_add_u64 v[224:225], v[222:223], 0, s[24:25]
	s_mov_b32 m0, s10
	v_lshl_add_u64 v[222:223], v[222:223], 0, s[38:39]
	s_mul_i32 s100, s70, 0x900
	s_waitcnt lgkmcnt(6)
	v_mfma_f32_32x32x16_bf16 v[114:129], v[182:185], v[154:157], v[114:129]
	global_load_lds_dwordx4 v[224:225], off
	s_add_i32 m0, s10, 0x400
	v_mfma_f32_32x32x16_bf16 v[98:113], v[178:181], v[154:157], v[98:113]
	global_load_lds_dwordx4 v[222:223], off
	v_lshl_add_u64 v[224:225], v[194:195], 0, s[100:101]
	s_add_i32 s10, s22, s28
	s_add_i32 m0, s10, 0x2000
	v_mfma_f32_32x32x16_bf16 v[66:81], v[182:185], v[158:161], v[66:81]
	global_load_lds_dwordx4 v[224:225], off
	v_mfma_f32_32x32x16_bf16 v[34:49], v[178:181], v[158:161], v[34:49]
	global_load_lds_dwordx4 v[224:225], off offset:1024
	v_mfma_f32_32x32x16_bf16 v[82:97], v[174:177], v[154:157], v[82:97]
	global_load_lds_dwordx4 v[224:225], off offset:2048
	v_mfma_f32_32x32x16_bf16 v[50:65], v[170:173], v[154:157], v[50:65]
	global_load_lds_dwordx4 v[224:225], off offset:3072
	v_mfma_f32_32x32x16_bf16 v[18:33], v[174:177], v[158:161], v[18:33]
	s_add_i32 s10, s29, 0x6000
	s_cmpk_lg_u32 s29, 0xc000
	s_cselect_b32 s29, s10, 0
	s_add_i32 s10, s28, 0x6000
	s_cmpk_lg_u32 s28, 0xc000
	s_cselect_b32 s28, s10, 0
	v_mfma_f32_32x32x16_bf16 v[2:17], v[170:173], v[158:161], v[2:17]
	s_add_i32 s11, s29, 16
	s_waitcnt vmcnt(6) lgkmcnt(0)
	s_barrier
	v_add_u32_e32 v158, s11, v219
	v_add_u32_e32 v170, s11, v218
	v_add_u32_e32 v158, v158, v0
	v_add_u32_e32 v170, v170, v0
	ds_read_b128 v[154:157], v158
	ds_read_b128 v[182:185], v170 offset:8192
	ds_read_b128 v[178:181], v170 offset:10240
	ds_read_b128 v[158:161], v158 offset:2048
	ds_read_b128 v[174:177], v170 offset:12288
	ds_read_b128 v[170:173], v170 offset:14336
	v_mfma_f32_32x32x16_bf16 v[114:129], v[162:165], v[138:141], v[114:129]
	v_mfma_f32_32x32x16_bf16 v[98:113], v[166:169], v[138:141], v[98:113]
	v_mfma_f32_32x32x16_bf16 v[66:81], v[162:165], v[142:145], v[66:81]
	v_mfma_f32_32x32x16_bf16 v[34:49], v[166:169], v[142:145], v[34:49]
	v_mfma_f32_32x32x16_bf16 v[82:97], v[146:149], v[138:141], v[82:97]
	v_mfma_f32_32x32x16_bf16 v[50:65], v[150:153], v[138:141], v[50:65]
	v_mfma_f32_32x32x16_bf16 v[18:33], v[146:149], v[142:145], v[18:33]
	v_mfma_f32_32x32x16_bf16 v[2:17], v[150:153], v[142:145], v[2:17]
	s_add_i32 s23, s23, 2
	s_cmp_lg_u32 s23, 32
	s_cbranch_scc1 .LBB0_184
; DI unsigned pk2(float a, float b) { f32x2 v = {a, b}; bf2_t r = __builtin_convertvector(v, bf2_t); return __builtin_bit_cast(unsigned, r); }
;     ...
;   asm volatile("s_waitcnt vmcnt(0)" ::: "memory");
;   __builtin_amdgcn_s_barrier();
;   asm volatile("" ::: "memory");
;     ...
;   {
;     const int h = lane >> 5, cl = lane & 31;
; #pragma unroll
;     for (int i = 0; i < 2; ++i)
; #pragma unroll
;       for (int j = 0; j < 4; ++j)
; #pragma unroll
;         for (int g = 0; g < 4; ++g) {
;           u32x2 w; w.x = pk2(acc[i][j][4 * g], acc[i][j][4 * g + 1]); w.y = pk2(acc[i][j][4 * g + 2], acc[i][j][4 * g + 3]);
;           *(u32x2*)(smem + (wr * 64 + i * 32 + cl) * 528 + (wc * 128 + j * 32 + 8 * g + 4 * h) * 2) = w;
;         }
;   }
;   __syncthreads();
	s_waitcnt lgkmcnt(0)
	v_mul_lo_u32 v0, v197, s55
	v_add_u32_e32 v0, 16, v0
	s_nop 1
	v_cvt_pk_bf16_f32 v114, v114, v115
	v_cvt_pk_bf16_f32 v115, v116, v117
	v_lshlrev_b32_e32 v116, 3, v196
	s_lshl_b32 s10, s21, 1
	v_add3_u32 v0, v0, v116, s10
	v_cvt_pk_bf16_f32 v116, v118, v119
	v_cvt_pk_bf16_f32 v117, v120, v121
	v_cvt_pk_bf16_f32 v98, v98, v99
	v_cvt_pk_bf16_f32 v99, v100, v101
	v_cvt_pk_bf16_f32 v100, v102, v103
	v_cvt_pk_bf16_f32 v101, v104, v105
	v_cvt_pk_bf16_f32 v82, v82, v83
	v_cvt_pk_bf16_f32 v83, v84, v85
	v_cvt_pk_bf16_f32 v84, v86, v87
	v_cvt_pk_bf16_f32 v85, v88, v89
	v_cvt_pk_bf16_f32 v50, v50, v51
	v_cvt_pk_bf16_f32 v51, v52, v53
	v_cvt_pk_bf16_f32 v52, v54, v55
	v_cvt_pk_bf16_f32 v53, v56, v57
	s_waitcnt vmcnt(0)
	s_barrier
	ds_write2_b64 v0, v[114:115], v[116:117] offset1:2
	v_cvt_pk_bf16_f32 v114, v122, v123
	v_cvt_pk_bf16_f32 v115, v124, v125
	v_cvt_pk_bf16_f32 v116, v126, v127
	v_cvt_pk_bf16_f32 v117, v128, v129
	ds_write2_b64 v0, v[98:99], v[100:101] offset0:8 offset1:10
	v_cvt_pk_bf16_f32 v98, v106, v107
	v_cvt_pk_bf16_f32 v99, v108, v109
	v_cvt_pk_bf16_f32 v100, v110, v111
	v_cvt_pk_bf16_f32 v101, v112, v113
	ds_write2_b64 v0, v[82:83], v[84:85] offset0:16 offset1:18
	v_cvt_pk_bf16_f32 v82, v90, v91
	v_cvt_pk_bf16_f32 v83, v92, v93
	v_cvt_pk_bf16_f32 v84, v94, v95
	v_cvt_pk_bf16_f32 v85, v96, v97
	ds_write2_b64 v0, v[50:51], v[52:53] offset0:24 offset1:26
	v_cvt_pk_bf16_f32 v50, v58, v59
	v_cvt_pk_bf16_f32 v51, v60, v61
	v_cvt_pk_bf16_f32 v52, v62, v63
	v_cvt_pk_bf16_f32 v53, v64, v65
	ds_write2_b64 v0, v[114:115], v[116:117] offset0:4 offset1:6
	ds_write2_b64 v0, v[98:99], v[100:101] offset0:12 offset1:14
	ds_write2_b64 v0, v[82:83], v[84:85] offset0:20 offset1:22
	ds_write2_b64 v0, v[50:51], v[52:53] offset0:28 offset1:30
	v_cvt_pk_bf16_f32 v50, v66, v67
	v_cvt_pk_bf16_f32 v51, v68, v69
	v_cvt_pk_bf16_f32 v52, v70, v71
	v_cvt_pk_bf16_f32 v53, v72, v73
	v_add_u32_e32 v0, 0x4000, v0
	v_cvt_pk_bf16_f32 v34, v34, v35
	v_cvt_pk_bf16_f32 v35, v36, v37
	v_cvt_pk_bf16_f32 v36, v38, v39
	v_cvt_pk_bf16_f32 v37, v40, v41
	v_cvt_pk_bf16_f32 v18, v18, v19
	v_cvt_pk_bf16_f32 v19, v20, v21
	v_cvt_pk_bf16_f32 v20, v22, v23
	v_cvt_pk_bf16_f32 v21, v24, v25
	v_cvt_pk_bf16_f32 v2, v2, v3
	v_cvt_pk_bf16_f32 v3, v4, v5
	v_cvt_pk_bf16_f32 v4, v6, v7
	v_cvt_pk_bf16_f32 v5, v8, v9
	ds_write2_b64 v0, v[50:51], v[52:53] offset0:64 offset1:66
	v_cvt_pk_bf16_f32 v50, v74, v75
	v_cvt_pk_bf16_f32 v51, v76, v77
	v_cvt_pk_bf16_f32 v52, v78, v79
	v_cvt_pk_bf16_f32 v53, v80, v81
	ds_write2_b64 v0, v[34:35], v[36:37] offset0:72 offset1:74
	v_cvt_pk_bf16_f32 v34, v42, v43
	v_cvt_pk_bf16_f32 v35, v44, v45
	v_cvt_pk_bf16_f32 v36, v46, v47
	v_cvt_pk_bf16_f32 v37, v48, v49
	ds_write2_b64 v0, v[18:19], v[20:21] offset0:80 offset1:82
	v_cvt_pk_bf16_f32 v18, v26, v27
	v_cvt_pk_bf16_f32 v19, v28, v29
	v_cvt_pk_bf16_f32 v20, v30, v31
	v_cvt_pk_bf16_f32 v21, v32, v33
	ds_write2_b64 v0, v[2:3], v[4:5] offset0:88 offset1:90
	v_cvt_pk_bf16_f32 v2, v10, v11
	v_cvt_pk_bf16_f32 v3, v12, v13
	v_cvt_pk_bf16_f32 v4, v14, v15
	v_cvt_pk_bf16_f32 v5, v16, v17
	s_lshl_b64 s[14:15], s[14:15], 1
	ds_write2_b64 v0, v[50:51], v[52:53] offset0:68 offset1:70
	ds_write2_b64 v0, v[34:35], v[36:37] offset0:76 offset1:78
	ds_write2_b64 v0, v[18:19], v[20:21] offset0:84 offset1:86
	ds_write2_b64 v0, v[2:3], v[4:5] offset0:92 offset1:94
	s_waitcnt vmcnt(0) lgkmcnt(0)
	s_barrier
; #define GAS __attribute__((address_space(1)))
;     ...
;   int tid2 = tid; asm volatile("" : "+v"(tid2));
;   if (EPI == 0) {
; #pragma unroll
;     for (int i = 0; i < 16; ++i) {
;       const int id = tid2 + 256 * i, r = id >> 5, c8 = (id & 31) * 8;
;       const u32x4 v = *(const u32x4*)(smem + r * 528 + c8 * 2);
;       *(GAS u32x4*)(ea.out + (size_t)(m0 + r) * ea.ldo + n0 + c8) = v;
;     }
	s_add_u32 s14, s16, s14
	v_lshlrev_b32_e32 v0, 4, v189
	v_and_b32_e32 v0, 0x1f0, v0
	s_addc_u32 s15, s17, s15
	v_add_u32_e32 v10, 16, v0
	v_lshl_add_u64 v[12:13], s[14:15], 0, v[0:1]
	v_ashrrev_i32_e32 v0, 5, v189
	v_mad_u64_u32 v[2:3], s[14:15], v0, s55, v[10:11]
	v_add_u32_e32 v0, s12, v0
	v_mad_i64_i32 v[14:15], s[14:15], v0, s35, v[12:13]
	v_add_u32_e32 v0, 0x100, v189
	ds_read_b128 v[2:5], v2
	v_ashrrev_i32_e32 v0, 5, v0
	v_mad_u64_u32 v[6:7], s[14:15], v0, s55, v[10:11]
	ds_read_b128 v[6:9], v6
	v_add_u32_e32 v0, s12, v0
	s_waitcnt lgkmcnt(1)
	global_store_dwordx4 v[14:15], v[2:5], off
	v_readlane_b32 s10, v252, 12
	s_add_i32 s20, s20, s10
	v_mad_i64_i32 v[2:3], s[14:15], v0, s35, v[12:13]
	v_add_u32_e32 v0, 0x200, v189
	v_ashrrev_i32_e32 v0, 5, v0
	s_waitcnt lgkmcnt(0)
	global_store_dwordx4 v[2:3], v[6:9], off
	v_mad_u64_u32 v[2:3], s[14:15], v0, s55, v[10:11]
	v_add_u32_e32 v0, s12, v0
	v_mad_i64_i32 v[14:15], s[14:15], v0, s35, v[12:13]
	v_add_u32_e32 v0, 0x300, v189
	ds_read_b128 v[2:5], v2
	v_ashrrev_i32_e32 v0, 5, v0
	v_mad_u64_u32 v[6:7], s[14:15], v0, s55, v[10:11]
	ds_read_b128 v[6:9], v6
	v_add_u32_e32 v0, s12, v0
	s_waitcnt lgkmcnt(1)
	global_store_dwordx4 v[14:15], v[2:5], off
	s_cmp_ge_i32 s20, s45
	s_nop 0
	v_mad_i64_i32 v[2:3], s[14:15], v0, s35, v[12:13]
	v_add_u32_e32 v0, 0x400, v189
	v_ashrrev_i32_e32 v0, 5, v0
	s_waitcnt lgkmcnt(0)
	global_store_dwordx4 v[2:3], v[6:9], off
	v_mad_u64_u32 v[2:3], s[14:15], v0, s55, v[10:11]
	v_add_u32_e32 v0, s12, v0
	v_mad_i64_i32 v[14:15], s[14:15], v0, s35, v[12:13]
	v_add_u32_e32 v0, 0x500, v189
	ds_read_b128 v[2:5], v2
	v_ashrrev_i32_e32 v0, 5, v0
	v_mad_u64_u32 v[6:7], s[14:15], v0, s55, v[10:11]
	ds_read_b128 v[6:9], v6
	v_add_u32_e32 v0, s12, v0
	s_waitcnt lgkmcnt(1)
	global_store_dwordx4 v[14:15], v[2:5], off
	s_nop 1
	v_mad_i64_i32 v[2:3], s[14:15], v0, s35, v[12:13]
	v_add_u32_e32 v0, 0x600, v189
	v_ashrrev_i32_e32 v0, 5, v0
	s_waitcnt lgkmcnt(0)
	global_store_dwordx4 v[2:3], v[6:9], off
	v_mad_u64_u32 v[2:3], s[14:15], v0, s55, v[10:11]
	v_add_u32_e32 v0, s12, v0
	v_mad_i64_i32 v[14:15], s[14:15], v0, s35, v[12:13]
	v_add_u32_e32 v0, 0x700, v189
	ds_read_b128 v[2:5], v2
	v_ashrrev_i32_e32 v0, 5, v0
	v_mad_u64_u32 v[6:7], s[14:15], v0, s55, v[10:11]
	ds_read_b128 v[6:9], v6
	v_add_u32_e32 v0, s12, v0
	s_waitcnt lgkmcnt(1)
	global_store_dwordx4 v[14:15], v[2:5], off
	s_nop 1
	v_mad_i64_i32 v[2:3], s[14:15], v0, s35, v[12:13]
	v_add_u32_e32 v0, 0x800, v189
	v_ashrrev_i32_e32 v0, 5, v0
	s_waitcnt lgkmcnt(0)
	global_store_dwordx4 v[2:3], v[6:9], off
	v_mad_u64_u32 v[2:3], s[14:15], v0, s55, v[10:11]
	v_add_u32_e32 v0, s12, v0
	v_mad_i64_i32 v[14:15], s[14:15], v0, s35, v[12:13]
	v_add_u32_e32 v0, 0x900, v189
	ds_read_b128 v[2:5], v2
	v_ashrrev_i32_e32 v0, 5, v0
	v_mad_u64_u32 v[6:7], s[14:15], v0, s55, v[10:11]
	ds_read_b128 v[6:9], v6
	v_add_u32_e32 v0, s12, v0
	s_waitcnt lgkmcnt(1)
	global_store_dwordx4 v[14:15], v[2:5], off
	s_nop 1
	v_mad_i64_i32 v[2:3], s[14:15], v0, s35, v[12:13]
	v_add_u32_e32 v0, 0xa00, v189
	v_ashrrev_i32_e32 v0, 5, v0
	s_waitcnt lgkmcnt(0)
	global_store_dwordx4 v[2:3], v[6:9], off
	v_mad_u64_u32 v[2:3], s[14:15], v0, s55, v[10:11]
	v_add_u32_e32 v0, s12, v0
	v_mad_i64_i32 v[14:15], s[14:15], v0, s35, v[12:13]
	v_add_u32_e32 v0, 0xb00, v189
	ds_read_b128 v[2:5], v2
	v_ashrrev_i32_e32 v0, 5, v0
	v_mad_u64_u32 v[6:7], s[14:15], v0, s55, v[10:11]
	ds_read_b128 v[6:9], v6
	v_add_u32_e32 v0, s12, v0
	s_waitcnt lgkmcnt(1)
	global_store_dwordx4 v[14:15], v[2:5], off
	s_nop 1
	v_mad_i64_i32 v[2:3], s[14:15], v0, s35, v[12:13]
	v_add_u32_e32 v0, 0xc00, v189
	v_ashrrev_i32_e32 v0, 5, v0
	s_waitcnt lgkmcnt(0)
	global_store_dwordx4 v[2:3], v[6:9], off
	v_mad_u64_u32 v[2:3], s[14:15], v0, s55, v[10:11]
	v_add_u32_e32 v0, s12, v0
	v_mad_i64_i32 v[14:15], s[14:15], v0, s35, v[12:13]
	v_add_u32_e32 v0, 0xd00, v189
	ds_read_b128 v[2:5], v2
	v_ashrrev_i32_e32 v0, 5, v0
	v_mad_u64_u32 v[6:7], s[14:15], v0, s55, v[10:11]
	ds_read_b128 v[6:9], v6
	v_add_u32_e32 v0, s12, v0
	s_waitcnt lgkmcnt(1)
	global_store_dwordx4 v[14:15], v[2:5], off
	s_nop 1
	v_mad_i64_i32 v[2:3], s[14:15], v0, s35, v[12:13]
	v_add_u32_e32 v0, 0xe00, v189
	v_ashrrev_i32_e32 v0, 5, v0
	s_waitcnt lgkmcnt(0)
	global_store_dwordx4 v[2:3], v[6:9], off
	v_mad_u64_u32 v[2:3], s[14:15], v0, s55, v[10:11]
	v_add_u32_e32 v0, s12, v0
	v_mad_i64_i32 v[14:15], s[14:15], v0, s35, v[12:13]
	v_add_u32_e32 v0, 0xf00, v189
	v_ashrrev_i32_e32 v0, 5, v0
	ds_read_b128 v[2:5], v2
	v_mad_u64_u32 v[6:7], s[14:15], v0, s55, v[10:11]
	ds_read_b128 v[6:9], v6
	v_add_u32_e32 v0, s12, v0
	s_waitcnt lgkmcnt(1)
	global_store_dwordx4 v[14:15], v[2:5], off
	s_nop 1
	v_mad_i64_i32 v[2:3], s[12:13], v0, s35, v[12:13]
	s_waitcnt lgkmcnt(0)
	global_store_dwordx4 v[2:3], v[6:9], off
	s_barrier
	s_cbranch_scc0 .LBB0_183
	v_mov_b64_e32 v[6:7], v[130:131]
	v_mov_b64_e32 v[2:3], v[134:135]
	v_mov_b32_e32 v31, v214
	v_mov_b32_e32 v30, v215
	v_mov_b32_e32 v29, v216
	v_mov_b32_e32 v28, v217
	v_mov_b64_e32 v[8:9], v[132:133]
	v_mov_b64_e32 v[4:5], v[136:137]
	v_readlane_b32 s44, v250, 17

; #define LAS __attribute__((address_space(3)))
;   int tid = tid_in; asm volatile("" : "+v"(tid));
;   const int lane = tid & 63, wid = __builtin_amdgcn_readfirstlane(tid >> 6), wr = wid >> 1, wc = wid & 1;
;   const int m0 = mt * 128, n0 = nt * 256;
;   const int r = lane & 31, h = lane >> 5, key = (r >> 2) & 3;
;   constexpr int STG = 24576;
;   const int rowl = lane >> 2, cch = (lane & 3) ^ ((lane >> 4) & 3);
;   const unsigned voffA = (unsigned)(rowl * lda * 2 + cch * 16), voffB = (unsigned)(rowl * K * 2 + cch * 16);
;   const char* Abase = (const char*)(A + (size_t)m0 * lda) + (size_t)(wid * 2) * 32 * lda;
;   const char* Bbase = (const char*)(Bt + (size_t)n0 * K) + (size_t)(wid * 4) * 32 * K;
;   const size_t ablk = (size_t)32 * lda, bblk = (size_t)32 * K;
;   LAS char* lds = (LAS char*)smem;
;   LAS char* ldsA = lds + (wid * 2) * 1024;
;   LAS char* ldsB = lds + 8192 + (wid * 4) * 1024;
;     ...
;   const int x0 = ((0 + h) ^ key) * 16, x1 = ((2 + h) ^ key) * 16;
;   const int a_rd = (wr * 64 + r) * 64, b_rd = 8192 + (wc * 128 + r) * 64;
;   f32x16 acc[2][4];
; #pragma unroll
;   for (int i = 0; i < 2; ++i)
; #pragma unroll
;     for (int j = 0; j < 4; ++j)
; #pragma unroll
;       for (int e = 0; e < 16; ++e) acc[i][j][e] = 0.f;
;   const int nk = K >> 5;
;   DMA_STEP_(0, 0);
;   DMA_STEP_(1, STG);
;   asm volatile("s_waitcnt vmcnt(6)" ::: "memory");
;   __builtin_amdgcn_s_barrier();
;   asm volatile("" ::: "memory");
;   int s0 = 0, s2 = 2 * STG;
.LBB0_234:
	v_mov_b32_e32 v189, v188
	s_lshl_b32 s12, s23, 7
	v_readfirstlane_b32 s42, v189
	s_ashr_i32 s44, s42, 6
	s_lshl_b32 s28, s44, 2
	s_ashr_i32 s29, s28, 31
	s_lshl_b32 s23, s44, 12
	s_lshl_b64 s[40:41], s[28:29], 10
	s_add_i32 s28, s23, 16
	s_ashr_i32 s23, s42, 1
	v_and_b32_e32 v0, 31, v189
	s_andn2_b32 s23, s23, 63
	v_lshlrev_b32_e32 v2, 4, v189
	s_lshl_b32 s10, s44, 1
	v_or_b32_e32 v197, s23, v0
	s_lshl_b32 s23, s44, 7
	v_bitop3_b32 v2, v2, 48, v189 bitop3:0x48
	v_lshlrev_b32_e32 v3, 9, v189
	s_ashr_i32 s13, s12, 31
	s_ashr_i32 s11, s10, 31
	s_and_b32 s23, s23, 0x80
	s_movk_i32 s42, 0x7800
	s_lshl_b64 s[10:11], s[10:11], 15
	s_add_i32 s29, s28, 0x2000
	v_or_b32_e32 v4, s23, v0
	v_and_or_b32 v0, v3, s42, v2
	v_lshlrev_b32_e32 v10, 4, v189
	v_and_b32_e32 v10, 0x3c0, v10
	v_or_b32_e32 v10, v10, v2
	v_mov_b32_e32 v11, 0
	s_lshl_b64 s[42:43], s[12:13], 11
	s_add_u32 s13, s18, s42
	s_addc_u32 s42, s19, s43
	s_add_u32 s10, s13, s10
	s_addc_u32 s11, s42, s11
	s_lshl_b64 s[42:43], s[14:15], 6
	s_add_u32 s13, s20, s42
	s_addc_u32 s42, s21, s43
	s_add_u32 s40, s13, s40
	s_addc_u32 s41, s42, s41
	s_lshl_b32 s13, s44, 11
	s_sub_i32 s13, s28, s13
	v_lshl_add_u64 v[192:193], s[10:11], 0, v[0:1]
	s_mov_b32 m0, s13
	v_lshl_add_u64 v[2:3], v[192:193], 0, s[72:73]
	global_load_lds_dwordx4 v0, s[10:11]
	s_add_i32 m0, s13, 0x400
	v_lshl_add_u64 v[194:195], s[40:41], 0, v[10:11]
	global_load_lds_dwordx4 v[2:3], off
	s_mov_b32 m0, s29
	s_nop 0
	global_load_lds_dwordx4 v[194:195], off
	global_load_lds_dwordx4 v[194:195], off offset:1024
	global_load_lds_dwordx4 v[194:195], off offset:2048
	global_load_lds_dwordx4 v[194:195], off offset:3072
	s_mov_b64 s[10:11], 0x10000
	s_mov_b64 s[10:11], 0x18000
	s_mov_b64 s[10:11], 0x8040
	s_add_i32 m0, s13, 0x6000
	v_lshl_add_u64 v[2:3], v[192:193], 0, 64
	global_load_lds_dwordx4 v[2:3], off
	v_lshl_add_u64 v[2:3], v[192:193], 0, s[10:11]
	s_add_i32 m0, s13, 0x6400
	v_bfe_u32 v196, v189, 5, 1
	global_load_lds_dwordx4 v[2:3], off
	s_add_i32 m0, s28, 0x8000
	s_mov_b32 s100, 0x24000
	v_lshl_add_u64 v[2:3], v[194:195], 0, s[100:101]
	global_load_lds_dwordx4 v[2:3], off
	global_load_lds_dwordx4 v[2:3], off offset:1024
	global_load_lds_dwordx4 v[2:3], off offset:2048
	global_load_lds_dwordx4 v[2:3], off offset:3072
	s_mov_b64 s[10:11], 0x10040
	s_mov_b64 s[10:11], 0x18040
	v_lshlrev_b32_e32 v218, 6, v4
	v_bfe_u32 v4, v189, 2, 2
	v_lshrrev_b32_e32 v5, 5, v189
	s_lshl_b32 s100, s100, 1
	v_lshl_add_u64 v[194:195], v[194:195], 0, s[100:101]
	s_waitcnt vmcnt(6)
	s_barrier
	v_bitop3_b32 v2, v196, v4, 2 bitop3:0x36
	v_bitop3_b32 v0, v5, v4, 1 bitop3:0x6c
	v_lshlrev_b32_e32 v220, 4, v2
	v_mov_b32_e32 v2, 0
	v_lshlrev_b32_e32 v219, 6, v197
	v_lshlrev_b32_e32 v0, 4, v0
	s_mov_b32 s40, 0xc000
	s_mov_b32 s29, 0
	s_mov_b32 s41, 0
	v_mov_b32_e32 v3, v2
	v_mov_b32_e32 v4, v2
	v_mov_b32_e32 v5, v2
	v_mov_b32_e32 v6, v2
	v_mov_b32_e32 v7, v2
	v_mov_b32_e32 v8, v2
	v_mov_b32_e32 v9, v2
	v_mov_b32_e32 v10, v2
	v_mov_b32_e32 v11, v2
	v_mov_b32_e32 v12, v2
	v_mov_b32_e32 v13, v2
	v_mov_b32_e32 v14, v2
	v_mov_b32_e32 v15, v2
	v_mov_b32_e32 v16, v2
	v_mov_b32_e32 v17, v2
	v_mov_b32_e32 v18, v2
	v_mov_b32_e32 v19, v2
	v_mov_b32_e32 v20, v2
	v_mov_b32_e32 v21, v2
	v_mov_b32_e32 v22, v2
	v_mov_b32_e32 v23, v2
	v_mov_b32_e32 v24, v2
	v_mov_b32_e32 v25, v2
	v_mov_b32_e32 v26, v2
	v_mov_b32_e32 v27, v2
	v_mov_b32_e32 v28, v2
	v_mov_b32_e32 v29, v2
	v_mov_b32_e32 v30, v2
	v_mov_b32_e32 v31, v2
	v_mov_b32_e32 v32, v2
	v_mov_b32_e32 v33, v2
	v_mov_b32_e32 v50, v2
	v_mov_b32_e32 v51, v2
	v_mov_b32_e32 v52, v2
	v_mov_b32_e32 v53, v2
	v_mov_b32_e32 v54, v2
	v_mov_b32_e32 v55, v2
	v_mov_b32_e32 v56, v2
	v_mov_b32_e32 v57, v2
	v_mov_b32_e32 v58, v2
	v_mov_b32_e32 v59, v2
	v_mov_b32_e32 v60, v2
	v_mov_b32_e32 v61, v2
	v_mov_b32_e32 v62, v2
	v_mov_b32_e32 v63, v2
	v_mov_b32_e32 v64, v2
	v_mov_b32_e32 v65, v2
	v_mov_b32_e32 v82, v2
	v_mov_b32_e32 v83, v2
	v_mov_b32_e32 v84, v2
	v_mov_b32_e32 v85, v2
	v_mov_b32_e32 v86, v2
	v_mov_b32_e32 v87, v2
	v_mov_b32_e32 v88, v2
	v_mov_b32_e32 v89, v2
	v_mov_b32_e32 v90, v2
	v_mov_b32_e32 v91, v2
	v_mov_b32_e32 v92, v2
	v_mov_b32_e32 v93, v2
	v_mov_b32_e32 v94, v2
	v_mov_b32_e32 v95, v2
	v_mov_b32_e32 v96, v2
	v_mov_b32_e32 v97, v2
	v_mov_b32_e32 v34, v2
	v_mov_b32_e32 v35, v2
	v_mov_b32_e32 v36, v2
	v_mov_b32_e32 v37, v2
	v_mov_b32_e32 v38, v2
	v_mov_b32_e32 v39, v2
	v_mov_b32_e32 v40, v2
	v_mov_b32_e32 v41, v2
	v_mov_b32_e32 v42, v2
	v_mov_b32_e32 v43, v2
	v_mov_b32_e32 v44, v2
	v_mov_b32_e32 v45, v2
	v_mov_b32_e32 v46, v2
	v_mov_b32_e32 v47, v2
	v_mov_b32_e32 v48, v2
	v_mov_b32_e32 v49, v2
	v_mov_b32_e32 v66, v2
	v_mov_b32_e32 v67, v2
	v_mov_b32_e32 v68, v2
	v_mov_b32_e32 v69, v2
	v_mov_b32_e32 v70, v2
	v_mov_b32_e32 v71, v2
	v_mov_b32_e32 v72, v2
	v_mov_b32_e32 v73, v2
	v_mov_b32_e32 v74, v2
	v_mov_b32_e32 v75, v2
	v_mov_b32_e32 v76, v2
	v_mov_b32_e32 v77, v2
	v_mov_b32_e32 v78, v2
	v_mov_b32_e32 v79, v2
	v_mov_b32_e32 v80, v2
	v_mov_b32_e32 v81, v2
	v_mov_b32_e32 v98, v2
	v_mov_b32_e32 v99, v2
	v_mov_b32_e32 v100, v2
	v_mov_b32_e32 v101, v2
	v_mov_b32_e32 v102, v2
	v_mov_b32_e32 v103, v2
	v_mov_b32_e32 v104, v2
	v_mov_b32_e32 v105, v2
	v_mov_b32_e32 v106, v2
	v_mov_b32_e32 v107, v2
	v_mov_b32_e32 v108, v2
	v_mov_b32_e32 v109, v2
	v_mov_b32_e32 v110, v2
	v_mov_b32_e32 v111, v2
	v_mov_b32_e32 v112, v2
	v_mov_b32_e32 v113, v2
	v_mov_b32_e32 v114, v2
	v_mov_b32_e32 v115, v2
	v_mov_b32_e32 v116, v2
	v_mov_b32_e32 v117, v2
	v_mov_b32_e32 v118, v2
	v_mov_b32_e32 v119, v2
	v_mov_b32_e32 v120, v2
	v_mov_b32_e32 v121, v2
	v_mov_b32_e32 v122, v2
	v_mov_b32_e32 v123, v2
	v_mov_b32_e32 v124, v2
	v_mov_b32_e32 v125, v2
	v_mov_b32_e32 v126, v2
	v_mov_b32_e32 v127, v2
	v_mov_b32_e32 v128, v2
	v_mov_b32_e32 v129, v2
	v_add_u32_e32 v158, 16, v219
	v_add_u32_e32 v170, 16, v218
	v_add_u32_e32 v158, v158, v0
	v_add_u32_e32 v170, v170, v0
	ds_read_b128 v[154:157], v158
	ds_read_b128 v[182:185], v170 offset:8192
	ds_read_b128 v[178:181], v170 offset:10240
	ds_read_b128 v[158:161], v158 offset:2048
	ds_read_b128 v[174:177], v170 offset:12288
	ds_read_b128 v[170:173], v170 offset:14336
; #define LAS __attribute__((address_space(3)))
; DI f32x16 mfma32(bf16x8 a, bf16x8 b, f32x16 c) { return __builtin_amdgcn_mfma_f32_32x32x16_bf16(a, b, c, 0, 0, 0); }
;     ...
;   for (int kt = 0; kt < nk; ++kt) {
;     const int kn = (kt + 2 < nk) ? (kt + 2) : (nk - 1);
;     const LAS char* cur = lds + s0;
;     bf16x8 af[2][2], bfr[2][4];
; #pragma unroll
;     for (int kk = 0; kk < 2; ++kk) {
;       const int xo = kk ? x1 : x0;
;       af[kk][0] = *(const LAS bf16x8*)(cur + a_rd + xo);
;       bfr[kk][0] = *(const LAS bf16x8*)(cur + b_rd + xo);
;       bfr[kk][1] = *(const LAS bf16x8*)(cur + b_rd + 2048 + xo);
;       af[kk][1] = *(const LAS bf16x8*)(cur + a_rd + 2048 + xo);
;       bfr[kk][2] = *(const LAS bf16x8*)(cur + b_rd + 4096 + xo);
;       bfr[kk][3] = *(const LAS bf16x8*)(cur + b_rd + 6144 + xo);
;     }
;     DMA_STEP_(kn, s2);
; #pragma unroll
;     for (int kk = 0; kk < 2; ++kk) {
;       acc[0][0] = mfma32(bfr[kk][0], af[kk][0], acc[0][0]); acc[0][1] = mfma32(bfr[kk][1], af[kk][0], acc[0][1]);
;       acc[1][0] = mfma32(bfr[kk][0], af[kk][1], acc[1][0]); acc[1][1] = mfma32(bfr[kk][1], af[kk][1], acc[1][1]);
;       acc[0][2] = mfma32(bfr[kk][2], af[kk][0], acc[0][2]); acc[0][3] = mfma32(bfr[kk][3], af[kk][0], acc[0][3]);
;       acc[1][2] = mfma32(bfr[kk][2], af[kk][1], acc[1][2]); acc[1][3] = mfma32(bfr[kk][3], af[kk][1], acc[1][3]);
;     }
;     __builtin_amdgcn_sched_group_barrier(0x100, 12, 0);
;     __builtin_amdgcn_sched_group_barrier(0x010, 6, 0);
;     __builtin_amdgcn_sched_group_barrier(0x008, 16, 0);
;     asm volatile("s_waitcnt vmcnt(6) lgkmcnt(0)" ::: "memory");
;     __builtin_amdgcn_s_barrier();
;     asm volatile("" ::: "memory");
;     s0 = (s0 == 2 * STG) ? 0 : s0 + STG;
;     s2 = (s2 == 2 * STG) ? 0 : s2 + STG;
;   }
.LBB0_235:
	s_add_i32 s11, s41, 16
	s_mov_b32 s10, s29
	v_add_u32_e32 v142, s11, v219
	v_add_u32_e32 v150, s11, v218
	s_min_u32 s10, s10, 29
	v_add_u32_e32 v142, v142, v220
	v_add_u32_e32 v150, v150, v220
	s_lshl_b32 s70, s10, 6
	ds_read_b128 v[138:141], v142
	ds_read_b128 v[162:165], v150 offset:8192
	ds_read_b128 v[166:169], v150 offset:10240
	ds_read_b128 v[142:145], v142 offset:2048
	ds_read_b128 v[146:149], v150 offset:12288
	ds_read_b128 v[150:153], v150 offset:14336
	v_lshl_add_u64 v[222:223], v[192:193], 0, s[70:71]
	s_add_i32 s10, s13, s40
	v_lshl_add_u64 v[224:225], v[222:223], 0, s[24:25]
	s_mov_b32 m0, s10
	v_lshl_add_u64 v[222:223], v[222:223], 0, s[38:39]
	s_mul_i32 s100, s70, 0x900
	s_waitcnt lgkmcnt(6)
	v_mfma_f32_32x32x16_bf16 v[114:129], v[182:185], v[154:157], v[114:129]
	global_load_lds_dwordx4 v[224:225], off
	s_add_i32 m0, s10, 0x400
	v_mfma_f32_32x32x16_bf16 v[98:113], v[178:181], v[154:157], v[98:113]
	global_load_lds_dwordx4 v[222:223], off
	v_lshl_add_u64 v[224:225], v[194:195], 0, s[100:101]
	s_add_i32 s10, s28, s40
	s_add_i32 m0, s10, 0x2000
	v_mfma_f32_32x32x16_bf16 v[66:81], v[182:185], v[158:161], v[66:81]
	global_load_lds_dwordx4 v[224:225], off
	v_mfma_f32_32x32x16_bf16 v[34:49], v[178:181], v[158:161], v[34:49]
	global_load_lds_dwordx4 v[224:225], off offset:1024
	v_mfma_f32_32x32x16_bf16 v[82:97], v[174:177], v[154:157], v[82:97]
	global_load_lds_dwordx4 v[224:225], off offset:2048
	v_mfma_f32_32x32x16_bf16 v[50:65], v[170:173], v[154:157], v[50:65]
	global_load_lds_dwordx4 v[224:225], off offset:3072
	v_mfma_f32_32x32x16_bf16 v[18:33], v[174:177], v[158:161], v[18:33]
	s_add_i32 s10, s41, 0x6000
	s_cmpk_lg_u32 s41, 0xc000
	s_cselect_b32 s41, s10, 0
	s_add_i32 s10, s40, 0x6000
	s_cmpk_lg_u32 s40, 0xc000
	s_cselect_b32 s40, s10, 0
	v_mfma_f32_32x32x16_bf16 v[2:17], v[170:173], v[158:161], v[2:17]
	s_add_i32 s11, s41, 16
	s_waitcnt vmcnt(6) lgkmcnt(0)
	s_barrier
	v_add_u32_e32 v158, s11, v219
	v_add_u32_e32 v170, s11, v218
	v_add_u32_e32 v158, v158, v0
	v_add_u32_e32 v170, v170, v0
	ds_read_b128 v[154:157], v158
	ds_read_b128 v[182:185], v170 offset:8192
	ds_read_b128 v[178:181], v170 offset:10240
	ds_read_b128 v[158:161], v158 offset:2048
	ds_read_b128 v[174:177], v170 offset:12288
	ds_read_b128 v[170:173], v170 offset:14336
	v_mfma_f32_32x32x16_bf16 v[114:129], v[162:165], v[138:141], v[114:129]
	v_mfma_f32_32x32x16_bf16 v[98:113], v[166:169], v[138:141], v[98:113]
	v_mfma_f32_32x32x16_bf16 v[66:81], v[162:165], v[142:145], v[66:81]
	v_mfma_f32_32x32x16_bf16 v[34:49], v[166:169], v[142:145], v[34:49]
	v_mfma_f32_32x32x16_bf16 v[82:97], v[146:149], v[138:141], v[82:97]
	v_mfma_f32_32x32x16_bf16 v[50:65], v[150:153], v[138:141], v[50:65]
	v_mfma_f32_32x32x16_bf16 v[18:33], v[146:149], v[142:145], v[18:33]
	v_mfma_f32_32x32x16_bf16 v[2:17], v[150:153], v[142:145], v[2:17]
	s_add_i32 s11, s41, 16
	s_add_i32 s10, s29, 1
	v_add_u32_e32 v142, s11, v219
	v_add_u32_e32 v150, s11, v218
	s_min_u32 s10, s10, 29
	v_add_u32_e32 v142, v142, v220
	v_add_u32_e32 v150, v150, v220
	s_lshl_b32 s70, s10, 6
	ds_read_b128 v[138:141], v142
	ds_read_b128 v[162:165], v150 offset:8192
	ds_read_b128 v[166:169], v150 offset:10240
	ds_read_b128 v[142:145], v142 offset:2048
	ds_read_b128 v[146:149], v150 offset:12288
	ds_read_b128 v[150:153], v150 offset:14336
	v_lshl_add_u64 v[222:223], v[192:193], 0, s[70:71]
	s_add_i32 s10, s13, s40
	v_lshl_add_u64 v[224:225], v[222:223], 0, s[24:25]
	s_mov_b32 m0, s10
	v_lshl_add_u64 v[222:223], v[222:223], 0, s[38:39]
	s_mul_i32 s100, s70, 0x900
	s_waitcnt lgkmcnt(6)
	v_mfma_f32_32x32x16_bf16 v[114:129], v[182:185], v[154:157], v[114:129]
	global_load_lds_dwordx4 v[224:225], off
	s_add_i32 m0, s10, 0x400
	v_mfma_f32_32x32x16_bf16 v[98:113], v[178:181], v[154:157], v[98:113]
	global_load_lds_dwordx4 v[222:223], off
	v_lshl_add_u64 v[224:225], v[194:195], 0, s[100:101]
	s_add_i32 s10, s28, s40
	s_add_i32 m0, s10, 0x2000
	v_mfma_f32_32x32x16_bf16 v[66:81], v[182:185], v[158:161], v[66:81]
	global_load_lds_dwordx4 v[224:225], off
	v_mfma_f32_32x32x16_bf16 v[34:49], v[178:181], v[158:161], v[34:49]
	global_load_lds_dwordx4 v[224:225], off offset:1024
	v_mfma_f32_32x32x16_bf16 v[82:97], v[174:177], v[154:157], v[82:97]
	global_load_lds_dwordx4 v[224:225], off offset:2048
	v_mfma_f32_32x32x16_bf16 v[50:65], v[170:173], v[154:157], v[50:65]
	global_load_lds_dwordx4 v[224:225], off offset:3072
	v_mfma_f32_32x32x16_bf16 v[18:33], v[174:177], v[158:161], v[18:33]
	s_add_i32 s10, s41, 0x6000
	s_cmpk_lg_u32 s41, 0xc000
	s_cselect_b32 s41, s10, 0
	s_add_i32 s10, s40, 0x6000
	s_cmpk_lg_u32 s40, 0xc000
	s_cselect_b32 s40, s10, 0
	v_mfma_f32_32x32x16_bf16 v[2:17], v[170:173], v[158:161], v[2:17]
	s_add_i32 s11, s41, 16
	s_waitcnt vmcnt(6) lgkmcnt(0)
	s_barrier
	v_add_u32_e32 v158, s11, v219
	v_add_u32_e32 v170, s11, v218
	v_add_u32_e32 v158, v158, v0
	v_add_u32_e32 v170, v170, v0
	ds_read_b128 v[154:157], v158
	ds_read_b128 v[182:185], v170 offset:8192
	ds_read_b128 v[178:181], v170 offset:10240
	ds_read_b128 v[158:161], v158 offset:2048
	ds_read_b128 v[174:177], v170 offset:12288
	ds_read_b128 v[170:173], v170 offset:14336
	v_mfma_f32_32x32x16_bf16 v[114:129], v[162:165], v[138:141], v[114:129]
	v_mfma_f32_32x32x16_bf16 v[98:113], v[166:169], v[138:141], v[98:113]
	v_mfma_f32_32x32x16_bf16 v[66:81], v[162:165], v[142:145], v[66:81]
	v_mfma_f32_32x32x16_bf16 v[34:49], v[166:169], v[142:145], v[34:49]
	v_mfma_f32_32x32x16_bf16 v[82:97], v[146:149], v[138:141], v[82:97]
	v_mfma_f32_32x32x16_bf16 v[50:65], v[150:153], v[138:141], v[50:65]
	v_mfma_f32_32x32x16_bf16 v[18:33], v[146:149], v[142:145], v[18:33]
	v_mfma_f32_32x32x16_bf16 v[2:17], v[150:153], v[142:145], v[2:17]
	s_add_i32 s29, s29, 2
	s_cmp_lg_u32 s29, 32
	s_cbranch_scc1 .LBB0_235
; DI unsigned pk2(float a, float b) { f32x2 v = {a, b}; bf2_t r = __builtin_convertvector(v, bf2_t); return __builtin_bit_cast(unsigned, r); }
;     ...
;   asm volatile("s_waitcnt vmcnt(0)" ::: "memory");
;   __builtin_amdgcn_s_barrier();
;   asm volatile("" ::: "memory");
;     ...
;   {
;     const int h = lane >> 5, cl = lane & 31;
; #pragma unroll
;     for (int i = 0; i < 2; ++i)
; #pragma unroll
;       for (int j = 0; j < 4; ++j)
; #pragma unroll
;         for (int g = 0; g < 4; ++g) {
;           u32x2 w; w.x = pk2(acc[i][j][4 * g], acc[i][j][4 * g + 1]); w.y = pk2(acc[i][j][4 * g + 2], acc[i][j][4 * g + 3]);
;           *(u32x2*)(smem + (wr * 64 + i * 32 + cl) * 528 + (wc * 128 + j * 32 + 8 * g + 4 * h) * 2) = w;
;         }
;   }
;   __syncthreads();
	s_waitcnt lgkmcnt(0)
	v_mul_lo_u32 v0, v197, s55
	v_add_u32_e32 v0, 16, v0
	s_nop 1
	v_cvt_pk_bf16_f32 v114, v114, v115
	v_cvt_pk_bf16_f32 v115, v116, v117
	v_lshlrev_b32_e32 v116, 3, v196
	s_lshl_b32 s10, s23, 1
	v_add3_u32 v0, v0, v116, s10
	v_cvt_pk_bf16_f32 v116, v118, v119
	v_cvt_pk_bf16_f32 v117, v120, v121
	v_cvt_pk_bf16_f32 v98, v98, v99
	v_cvt_pk_bf16_f32 v99, v100, v101
	v_cvt_pk_bf16_f32 v100, v102, v103
	v_cvt_pk_bf16_f32 v101, v104, v105
	v_cvt_pk_bf16_f32 v82, v82, v83
	v_cvt_pk_bf16_f32 v83, v84, v85
	v_cvt_pk_bf16_f32 v84, v86, v87
	v_cvt_pk_bf16_f32 v85, v88, v89
	v_cvt_pk_bf16_f32 v50, v50, v51
	v_cvt_pk_bf16_f32 v51, v52, v53
	v_cvt_pk_bf16_f32 v52, v54, v55
	v_cvt_pk_bf16_f32 v53, v56, v57
	s_waitcnt vmcnt(0)
	s_barrier
	ds_write2_b64 v0, v[114:115], v[116:117] offset1:2
	v_cvt_pk_bf16_f32 v114, v122, v123
	v_cvt_pk_bf16_f32 v115, v124, v125
	v_cvt_pk_bf16_f32 v116, v126, v127
	v_cvt_pk_bf16_f32 v117, v128, v129
	ds_write2_b64 v0, v[98:99], v[100:101] offset0:8 offset1:10
	v_cvt_pk_bf16_f32 v98, v106, v107
	v_cvt_pk_bf16_f32 v99, v108, v109
	v_cvt_pk_bf16_f32 v100, v110, v111
	v_cvt_pk_bf16_f32 v101, v112, v113
	ds_write2_b64 v0, v[82:83], v[84:85] offset0:16 offset1:18
	v_cvt_pk_bf16_f32 v82, v90, v91
	v_cvt_pk_bf16_f32 v83, v92, v93
	v_cvt_pk_bf16_f32 v84, v94, v95
	v_cvt_pk_bf16_f32 v85, v96, v97
	ds_write2_b64 v0, v[50:51], v[52:53] offset0:24 offset1:26
	v_cvt_pk_bf16_f32 v50, v58, v59
	v_cvt_pk_bf16_f32 v51, v60, v61
	v_cvt_pk_bf16_f32 v52, v62, v63
	v_cvt_pk_bf16_f32 v53, v64, v65
	ds_write2_b64 v0, v[114:115], v[116:117] offset0:4 offset1:6
	ds_write2_b64 v0, v[98:99], v[100:101] offset0:12 offset1:14
	ds_write2_b64 v0, v[82:83], v[84:85] offset0:20 offset1:22
	ds_write2_b64 v0, v[50:51], v[52:53] offset0:28 offset1:30
	v_cvt_pk_bf16_f32 v50, v66, v67
	v_cvt_pk_bf16_f32 v51, v68, v69
	v_cvt_pk_bf16_f32 v52, v70, v71
	v_cvt_pk_bf16_f32 v53, v72, v73
	v_add_u32_e32 v0, 0x4000, v0
	v_cvt_pk_bf16_f32 v34, v34, v35
	v_cvt_pk_bf16_f32 v35, v36, v37
	v_cvt_pk_bf16_f32 v36, v38, v39
	v_cvt_pk_bf16_f32 v37, v40, v41
	v_cvt_pk_bf16_f32 v18, v18, v19
	v_cvt_pk_bf16_f32 v19, v20, v21
	v_cvt_pk_bf16_f32 v20, v22, v23
	v_cvt_pk_bf16_f32 v21, v24, v25
	v_cvt_pk_bf16_f32 v2, v2, v3
	v_cvt_pk_bf16_f32 v3, v4, v5
	v_cvt_pk_bf16_f32 v4, v6, v7
	v_cvt_pk_bf16_f32 v5, v8, v9
	ds_write2_b64 v0, v[50:51], v[52:53] offset0:64 offset1:66
	v_cvt_pk_bf16_f32 v50, v74, v75
	v_cvt_pk_bf16_f32 v51, v76, v77
	v_cvt_pk_bf16_f32 v52, v78, v79
	v_cvt_pk_bf16_f32 v53, v80, v81
	ds_write2_b64 v0, v[34:35], v[36:37] offset0:72 offset1:74
	v_cvt_pk_bf16_f32 v34, v42, v43
	v_cvt_pk_bf16_f32 v35, v44, v45
	v_cvt_pk_bf16_f32 v36, v46, v47
	v_cvt_pk_bf16_f32 v37, v48, v49
	ds_write2_b64 v0, v[18:19], v[20:21] offset0:80 offset1:82
	v_cvt_pk_bf16_f32 v18, v26, v27
	v_cvt_pk_bf16_f32 v19, v28, v29
	v_cvt_pk_bf16_f32 v20, v30, v31
	v_cvt_pk_bf16_f32 v21, v32, v33
	ds_write2_b64 v0, v[2:3], v[4:5] offset0:88 offset1:90
	v_cvt_pk_bf16_f32 v2, v10, v11
	v_cvt_pk_bf16_f32 v3, v12, v13
	v_cvt_pk_bf16_f32 v4, v14, v15
	v_cvt_pk_bf16_f32 v5, v16, v17
	s_lshl_b64 s[10:11], s[14:15], 1
	ds_write2_b64 v0, v[50:51], v[52:53] offset0:68 offset1:70
	ds_write2_b64 v0, v[34:35], v[36:37] offset0:76 offset1:78
	ds_write2_b64 v0, v[18:19], v[20:21] offset0:84 offset1:86
	ds_write2_b64 v0, v[2:3], v[4:5] offset0:92 offset1:94
	s_waitcnt vmcnt(0) lgkmcnt(0)
	s_barrier
; #define GAS __attribute__((address_space(1)))
;     ...
;   int tid2 = tid; asm volatile("" : "+v"(tid2));
;   if (EPI == 0) {
; #pragma unroll
;     for (int i = 0; i < 16; ++i) {
;       const int id = tid2 + 256 * i, r = id >> 5, c8 = (id & 31) * 8;
;       const u32x4 v = *(const u32x4*)(smem + r * 528 + c8 * 2);
;       *(GAS u32x4*)(ea.out + (size_t)(m0 + r) * ea.ldo + n0 + c8) = v;
;     }
	s_add_u32 s10, s16, s10
	v_lshlrev_b32_e32 v0, 4, v189
	v_and_b32_e32 v0, 0x1f0, v0
	s_addc_u32 s11, s17, s11
	v_add_u32_e32 v10, 16, v0
	v_lshl_add_u64 v[12:13], s[10:11], 0, v[0:1]
	v_ashrrev_i32_e32 v0, 5, v189
	v_mad_u64_u32 v[2:3], s[10:11], v0, s55, v[10:11]
	v_add_u32_e32 v0, s12, v0
	v_mad_i64_i32 v[14:15], s[10:11], v0, s35, v[12:13]
	v_add_u32_e32 v0, 0x100, v189
	ds_read_b128 v[2:5], v2
	v_ashrrev_i32_e32 v0, 5, v0
	v_mad_u64_u32 v[6:7], s[10:11], v0, s55, v[10:11]
	ds_read_b128 v[6:9], v6
	v_add_u32_e32 v0, s12, v0
	s_waitcnt lgkmcnt(1)
	global_store_dwordx4 v[14:15], v[2:5], off
	s_nop 1
	v_mad_i64_i32 v[2:3], s[10:11], v0, s35, v[12:13]
	v_add_u32_e32 v0, 0x200, v189
	v_ashrrev_i32_e32 v0, 5, v0
	s_waitcnt lgkmcnt(0)
	global_store_dwordx4 v[2:3], v[6:9], off
	v_mad_u64_u32 v[2:3], s[10:11], v0, s55, v[10:11]
	v_add_u32_e32 v0, s12, v0
	v_mad_i64_i32 v[14:15], s[10:11], v0, s35, v[12:13]
	v_add_u32_e32 v0, 0x300, v189
	ds_read_b128 v[2:5], v2
	v_ashrrev_i32_e32 v0, 5, v0
	v_mad_u64_u32 v[6:7], s[10:11], v0, s55, v[10:11]
	ds_read_b128 v[6:9], v6
	v_add_u32_e32 v0, s12, v0
	s_waitcnt lgkmcnt(1)
	global_store_dwordx4 v[14:15], v[2:5], off
	s_nop 1
	v_mad_i64_i32 v[2:3], s[10:11], v0, s35, v[12:13]
	v_add_u32_e32 v0, 0x400, v189
	v_ashrrev_i32_e32 v0, 5, v0
	s_waitcnt lgkmcnt(0)
	global_store_dwordx4 v[2:3], v[6:9], off
	v_mad_u64_u32 v[2:3], s[10:11], v0, s55, v[10:11]
	v_add_u32_e32 v0, s12, v0
	v_mad_i64_i32 v[14:15], s[10:11], v0, s35, v[12:13]
	v_add_u32_e32 v0, 0x500, v189
	ds_read_b128 v[2:5], v2
	v_ashrrev_i32_e32 v0, 5, v0
	v_mad_u64_u32 v[6:7], s[10:11], v0, s55, v[10:11]
	ds_read_b128 v[6:9], v6
	v_add_u32_e32 v0, s12, v0
	s_waitcnt lgkmcnt(1)
	global_store_dwordx4 v[14:15], v[2:5], off
	s_nop 1
	v_mad_i64_i32 v[2:3], s[10:11], v0, s35, v[12:13]
	v_add_u32_e32 v0, 0x600, v189
	v_ashrrev_i32_e32 v0, 5, v0
	s_waitcnt lgkmcnt(0)
	global_store_dwordx4 v[2:3], v[6:9], off
	v_mad_u64_u32 v[2:3], s[10:11], v0, s55, v[10:11]
	v_add_u32_e32 v0, s12, v0
	v_mad_i64_i32 v[14:15], s[10:11], v0, s35, v[12:13]
	v_add_u32_e32 v0, 0x700, v189
	ds_read_b128 v[2:5], v2
	v_ashrrev_i32_e32 v0, 5, v0
	v_mad_u64_u32 v[6:7], s[10:11], v0, s55, v[10:11]
	ds_read_b128 v[6:9], v6
	v_add_u32_e32 v0, s12, v0
	s_waitcnt lgkmcnt(1)
	global_store_dwordx4 v[14:15], v[2:5], off
	s_nop 1
	v_mad_i64_i32 v[2:3], s[10:11], v0, s35, v[12:13]
	v_add_u32_e32 v0, 0x800, v189
	v_ashrrev_i32_e32 v0, 5, v0
	s_waitcnt lgkmcnt(0)
	global_store_dwordx4 v[2:3], v[6:9], off
	v_mad_u64_u32 v[2:3], s[10:11], v0, s55, v[10:11]
	v_add_u32_e32 v0, s12, v0
	v_mad_i64_i32 v[14:15], s[10:11], v0, s35, v[12:13]
	v_add_u32_e32 v0, 0x900, v189
	ds_read_b128 v[2:5], v2
	v_ashrrev_i32_e32 v0, 5, v0
	v_mad_u64_u32 v[6:7], s[10:11], v0, s55, v[10:11]
	ds_read_b128 v[6:9], v6
	v_add_u32_e32 v0, s12, v0
	s_waitcnt lgkmcnt(1)
	global_store_dwordx4 v[14:15], v[2:5], off
	s_nop 1
	v_mad_i64_i32 v[2:3], s[10:11], v0, s35, v[12:13]
	v_add_u32_e32 v0, 0xa00, v189
	v_ashrrev_i32_e32 v0, 5, v0
	s_waitcnt lgkmcnt(0)
	global_store_dwordx4 v[2:3], v[6:9], off
	v_mad_u64_u32 v[2:3], s[10:11], v0, s55, v[10:11]
	v_add_u32_e32 v0, s12, v0
	v_mad_i64_i32 v[14:15], s[10:11], v0, s35, v[12:13]
	v_add_u32_e32 v0, 0xb00, v189
	ds_read_b128 v[2:5], v2
	v_ashrrev_i32_e32 v0, 5, v0
	v_mad_u64_u32 v[6:7], s[10:11], v0, s55, v[10:11]
	ds_read_b128 v[6:9], v6
	v_add_u32_e32 v0, s12, v0
	s_waitcnt lgkmcnt(1)
	global_store_dwordx4 v[14:15], v[2:5], off
	s_nop 1
	v_mad_i64_i32 v[2:3], s[10:11], v0, s35, v[12:13]
	v_add_u32_e32 v0, 0xc00, v189
	v_ashrrev_i32_e32 v0, 5, v0
	s_waitcnt lgkmcnt(0)
	global_store_dwordx4 v[2:3], v[6:9], off
	v_mad_u64_u32 v[2:3], s[10:11], v0, s55, v[10:11]
	v_add_u32_e32 v0, s12, v0
	v_mad_i64_i32 v[14:15], s[10:11], v0, s35, v[12:13]
	v_add_u32_e32 v0, 0xd00, v189
	ds_read_b128 v[2:5], v2
	v_ashrrev_i32_e32 v0, 5, v0
	v_mad_u64_u32 v[6:7], s[10:11], v0, s55, v[10:11]
	ds_read_b128 v[6:9], v6
	v_add_u32_e32 v0, s12, v0
	s_waitcnt lgkmcnt(1)
	global_store_dwordx4 v[14:15], v[2:5], off
	s_nop 1
	v_mad_i64_i32 v[2:3], s[10:11], v0, s35, v[12:13]
	v_add_u32_e32 v0, 0xe00, v189
	v_ashrrev_i32_e32 v0, 5, v0
	s_waitcnt lgkmcnt(0)
	global_store_dwordx4 v[2:3], v[6:9], off
	v_mad_u64_u32 v[2:3], s[10:11], v0, s55, v[10:11]
	ds_read_b128 v[2:5], v2
	v_add_u32_e32 v0, s12, v0
	v_mad_i64_i32 v[14:15], s[10:11], v0, s35, v[12:13]
	v_add_u32_e32 v0, 0xf00, v189
	v_ashrrev_i32_e32 v0, 5, v0
	v_mad_u64_u32 v[6:7], s[10:11], v0, s55, v[10:11]
	ds_read_b128 v[6:9], v6
	v_add_u32_e32 v0, s12, v0
	s_waitcnt lgkmcnt(1)
	global_store_dwordx4 v[14:15], v[2:5], off
	s_nop 1
	v_mad_i64_i32 v[2:3], s[10:11], v0, s35, v[12:13]
	v_readlane_b32 s10, v252, 12
	s_add_i32 s22, s22, s10
	v_readlane_b32 s10, v252, 38
	s_cmp_ge_i32 s22, s10
	s_waitcnt lgkmcnt(0)
	global_store_dwordx4 v[2:3], v[6:9], off
	s_barrier
	s_cbranch_scc0 .LBB0_230

; #define LAS __attribute__((address_space(3)))
;   int tid = tid_in; asm volatile("" : "+v"(tid));
;   const int lane = tid & 63, wid = __builtin_amdgcn_readfirstlane(tid >> 6), wr = wid >> 1, wc = wid & 1;
;   const int m0 = mt * 128, n0 = nt * 256;
;   const int r = lane & 31, h = lane >> 5, key = (r >> 2) & 3;
;   constexpr int STG = 24576;
;   const int rowl = lane >> 2, cch = (lane & 3) ^ ((lane >> 4) & 3);
;   const unsigned voffA = (unsigned)(rowl * lda * 2 + cch * 16), voffB = (unsigned)(rowl * K * 2 + cch * 16);
;   const char* Abase = (const char*)(A + (size_t)m0 * lda) + (size_t)(wid * 2) * 32 * lda;
;   const char* Bbase = (const char*)(Bt + (size_t)n0 * K) + (size_t)(wid * 4) * 32 * K;
;   const size_t ablk = (size_t)32 * lda, bblk = (size_t)32 * K;
;   LAS char* lds = (LAS char*)smem;
;   LAS char* ldsA = lds + (wid * 2) * 1024;
;   LAS char* ldsB = lds + 8192 + (wid * 4) * 1024;
;     ...
;   const int x0 = ((0 + h) ^ key) * 16, x1 = ((2 + h) ^ key) * 16;
;   const int a_rd = (wr * 64 + r) * 64, b_rd = 8192 + (wc * 128 + r) * 64;
;   f32x16 acc[2][4];
; #pragma unroll
;   for (int i = 0; i < 2; ++i)
; #pragma unroll
;     for (int j = 0; j < 4; ++j)
; #pragma unroll
;       for (int e = 0; e < 16; ++e) acc[i][j][e] = 0.f;
;   const int nk = K >> 5;
;   DMA_STEP_(0, 0);
;   DMA_STEP_(1, STG);
;   asm volatile("s_waitcnt vmcnt(6)" ::: "memory");
;   __builtin_amdgcn_s_barrier();
;   asm volatile("" ::: "memory");
;   int s0 = 0, s2 = 2 * STG;
.LBB0_243:
	s_ashr_i32 s10, s29, 31
	s_lshr_b32 s10, s10, 27
	s_add_i32 s10, s29, s10
	s_ashr_i32 s10, s10, 5
	v_readlane_b32 s11, v252, 18
	s_lshl_b32 s11, s10, s11
	v_readlane_b32 s16, v252, 41
	s_add_i32 s11, s11, s16
	s_lshl_b32 s16, s29, 7
	v_mov_b32_e32 v189, v188
	s_lshl_b32 s11, s11, 10
	s_and_b32 s16, s16, 0x380
	s_or_b32 s40, s11, s16
	v_readfirstlane_b32 s42, v189
	s_lshl_b32 s10, s10, 10
	s_lshl_b32 s11, s29, 5
	s_ashr_i32 s44, s42, 6
	s_sub_i32 s10, s11, s10
	s_and_b32 s16, s10, 0xffffff00
	s_lshl_b32 s10, s44, 1
	s_mul_hi_i32 s45, s10, 0x16000
	s_lshl_b32 s10, s44, 2
	s_mov_b32 s47, 0
	s_lshl_b32 s10, s44, 12
	s_add_i32 s43, s10, 16
	s_ashr_i32 s10, s42, 1
	v_and_b32_e32 v0, 31, v189
	s_andn2_b32 s10, s10, 63
	v_or_b32_e32 v197, s10, v0
	s_lshl_b32 s10, s44, 7
	s_ashr_i32 s17, s16, 31
	s_add_i32 s56, s43, 0x2000
	s_and_b32 s42, s10, 0x80
	s_mul_i32 s57, s40, 0x1600
	s_mul_hi_i32 s10, s40, 0x1600
	s_add_u32 s57, s23, s57
	s_mul_i32 s11, s44, 0x2c000
	s_addc_u32 s58, s28, s10
	s_add_u32 s10, s57, s11
	s_addc_u32 s11, s58, s45
	s_mul_i32 s57, s16, 64
	s_mov_b32 s45, 0
	s_add_u32 s57, s19, s57
	s_mul_i32 s46, s44, 0x1000
	s_addc_u32 s45, s20, s45
	s_add_u32 s46, s57, s46
	v_bfe_u32 v2, v189, 2, 4
	v_lshlrev_b32_e32 v3, 4, v189
	s_addc_u32 s47, s45, s47
	s_lshl_b32 s44, s44, 11
	v_xor_b32_e32 v3, v3, v189
	v_mul_u32_u24_e32 v2, 0x1600, v2
	s_sub_i32 s44, s43, s44
	v_or_b32_e32 v5, s42, v0
	v_and_or_b32 v0, v3, 48, v2
	v_bfe_u32 v10, v189, 2, 4
	v_lshlrev_b32_e32 v10, 6, v10
	v_and_or_b32 v10, v3, 48, v10
	v_mov_b32_e32 v11, 0
	s_mov_b32 m0, s44
	v_lshl_add_u64 v[192:193], s[10:11], 0, v[0:1]
	global_load_lds_dwordx4 v0, s[10:11]
	s_mov_b64 s[10:11], 0x16000
	v_lshl_add_u64 v[2:3], v[192:193], 0, s[10:11]
	s_add_i32 m0, s44, 0x400
	v_lshl_add_u64 v[194:195], s[46:47], 0, v[10:11]
	global_load_lds_dwordx4 v[2:3], off
	s_mov_b32 m0, s56
	s_nop 0
	global_load_lds_dwordx4 v[194:195], off
	global_load_lds_dwordx4 v[194:195], off offset:1024
	global_load_lds_dwordx4 v[194:195], off offset:2048
	global_load_lds_dwordx4 v[194:195], off offset:3072
	s_mov_b64 s[10:11], 0x2c000
	s_mov_b64 s[10:11], 0x42000
	s_mov_b64 s[10:11], 0x16040
	s_add_i32 m0, s44, 0x6000
	v_lshl_add_u64 v[2:3], v[192:193], 0, 64
	global_load_lds_dwordx4 v[2:3], off
	v_lshl_add_u64 v[2:3], v[192:193], 0, s[10:11]
	s_add_i32 m0, s44, 0x6400
	v_bfe_u32 v196, v189, 5, 1
	global_load_lds_dwordx4 v[2:3], off
	s_add_i32 m0, s43, 0x8000
	s_mov_b32 s100, 0x10000
	v_lshl_add_u64 v[2:3], v[194:195], 0, s[100:101]
	global_load_lds_dwordx4 v[2:3], off
	global_load_lds_dwordx4 v[2:3], off offset:1024
	global_load_lds_dwordx4 v[2:3], off offset:2048
	global_load_lds_dwordx4 v[2:3], off offset:3072
	s_mov_b64 s[10:11], 0x2c040
	s_mov_b64 s[10:11], 0x42040
	v_lshlrev_b32_e32 v218, 6, v5
	v_bfe_u32 v5, v189, 2, 2
	v_lshrrev_b32_e32 v4, 2, v189
	s_lshl_b32 s100, s100, 1
	v_lshl_add_u64 v[194:195], v[194:195], 0, s[100:101]
	s_waitcnt vmcnt(6)
	s_barrier
	v_bitop3_b32 v2, v196, v5, 2 bitop3:0x36
	v_bitop3_b32 v0, v196, v4, 3 bitop3:0x78
	v_lshlrev_b32_e32 v220, 4, v2
	v_mov_b32_e32 v2, 0
	s_mov_b32 s41, 1
	v_lshlrev_b32_e32 v219, 6, v197
	v_lshlrev_b32_e32 v0, 4, v0
	s_mov_b32 s46, 0
	s_mov_b32 s45, 0xc000
	v_mov_b32_e32 v3, v2
	v_mov_b32_e32 v4, v2
	v_mov_b32_e32 v5, v2
	v_mov_b32_e32 v6, v2
	v_mov_b32_e32 v7, v2
	v_mov_b32_e32 v8, v2
	v_mov_b32_e32 v9, v2
	v_mov_b32_e32 v10, v2
	v_mov_b32_e32 v11, v2
	v_mov_b32_e32 v12, v2
	v_mov_b32_e32 v13, v2
	v_mov_b32_e32 v14, v2
	v_mov_b32_e32 v15, v2
	v_mov_b32_e32 v16, v2
	v_mov_b32_e32 v17, v2
	v_mov_b32_e32 v18, v2
	v_mov_b32_e32 v19, v2
	v_mov_b32_e32 v20, v2
	v_mov_b32_e32 v21, v2
	v_mov_b32_e32 v22, v2
	v_mov_b32_e32 v23, v2
	v_mov_b32_e32 v24, v2
	v_mov_b32_e32 v25, v2
	v_mov_b32_e32 v26, v2
	v_mov_b32_e32 v27, v2
	v_mov_b32_e32 v28, v2
	v_mov_b32_e32 v29, v2
	v_mov_b32_e32 v30, v2
	v_mov_b32_e32 v31, v2
	v_mov_b32_e32 v32, v2
	v_mov_b32_e32 v33, v2
	v_mov_b32_e32 v50, v2
	v_mov_b32_e32 v51, v2
	v_mov_b32_e32 v52, v2
	v_mov_b32_e32 v53, v2
	v_mov_b32_e32 v54, v2
	v_mov_b32_e32 v55, v2
	v_mov_b32_e32 v56, v2
	v_mov_b32_e32 v57, v2
	v_mov_b32_e32 v58, v2
	v_mov_b32_e32 v59, v2
	v_mov_b32_e32 v60, v2
	v_mov_b32_e32 v61, v2
	v_mov_b32_e32 v62, v2
	v_mov_b32_e32 v63, v2
	v_mov_b32_e32 v64, v2
	v_mov_b32_e32 v65, v2
	v_mov_b32_e32 v82, v2
	v_mov_b32_e32 v83, v2
	v_mov_b32_e32 v84, v2
	v_mov_b32_e32 v85, v2
	v_mov_b32_e32 v86, v2
	v_mov_b32_e32 v87, v2
	v_mov_b32_e32 v88, v2
	v_mov_b32_e32 v89, v2
	v_mov_b32_e32 v90, v2
	v_mov_b32_e32 v91, v2
	v_mov_b32_e32 v92, v2
	v_mov_b32_e32 v93, v2
	v_mov_b32_e32 v94, v2
	v_mov_b32_e32 v95, v2
	v_mov_b32_e32 v96, v2
	v_mov_b32_e32 v97, v2
	v_mov_b32_e32 v34, v2
	v_mov_b32_e32 v35, v2
	v_mov_b32_e32 v36, v2
	v_mov_b32_e32 v37, v2
	v_mov_b32_e32 v38, v2
	v_mov_b32_e32 v39, v2
	v_mov_b32_e32 v40, v2
	v_mov_b32_e32 v41, v2
	v_mov_b32_e32 v42, v2
	v_mov_b32_e32 v43, v2
	v_mov_b32_e32 v44, v2
	v_mov_b32_e32 v45, v2
	v_mov_b32_e32 v46, v2
	v_mov_b32_e32 v47, v2
	v_mov_b32_e32 v48, v2
	v_mov_b32_e32 v49, v2
	v_mov_b32_e32 v66, v2
	v_mov_b32_e32 v67, v2
	v_mov_b32_e32 v68, v2
	v_mov_b32_e32 v69, v2
	v_mov_b32_e32 v70, v2
	v_mov_b32_e32 v71, v2
	v_mov_b32_e32 v72, v2
	v_mov_b32_e32 v73, v2
	v_mov_b32_e32 v74, v2
	v_mov_b32_e32 v75, v2
	v_mov_b32_e32 v76, v2
	v_mov_b32_e32 v77, v2
	v_mov_b32_e32 v78, v2
	v_mov_b32_e32 v79, v2
	v_mov_b32_e32 v80, v2
	v_mov_b32_e32 v81, v2
	v_mov_b32_e32 v98, v2
	v_mov_b32_e32 v99, v2
	v_mov_b32_e32 v100, v2
	v_mov_b32_e32 v101, v2
	v_mov_b32_e32 v102, v2
	v_mov_b32_e32 v103, v2
	v_mov_b32_e32 v104, v2
	v_mov_b32_e32 v105, v2
	v_mov_b32_e32 v106, v2
	v_mov_b32_e32 v107, v2
	v_mov_b32_e32 v108, v2
	v_mov_b32_e32 v109, v2
	v_mov_b32_e32 v110, v2
	v_mov_b32_e32 v111, v2
	v_mov_b32_e32 v112, v2
	v_mov_b32_e32 v113, v2
	v_mov_b32_e32 v114, v2
	v_mov_b32_e32 v115, v2
	v_mov_b32_e32 v116, v2
	v_mov_b32_e32 v117, v2
	v_mov_b32_e32 v118, v2
	v_mov_b32_e32 v119, v2
	v_mov_b32_e32 v120, v2
	v_mov_b32_e32 v121, v2
	v_mov_b32_e32 v122, v2
	v_mov_b32_e32 v123, v2
	v_mov_b32_e32 v124, v2
	v_mov_b32_e32 v125, v2
	v_mov_b32_e32 v126, v2
	v_mov_b32_e32 v127, v2
	v_mov_b32_e32 v128, v2
	v_mov_b32_e32 v129, v2
	v_add_u32_e32 v162, 16, v219
	v_add_u32_e32 v170, 16, v218
	v_add_u32_e32 v162, v162, v0
	v_add_u32_e32 v170, v170, v0
	ds_read_b128 v[158:161], v162
	ds_read_b128 v[182:185], v170 offset:8192
	ds_read_b128 v[178:181], v170 offset:10240
	ds_read_b128 v[162:165], v162 offset:2048
	ds_read_b128 v[174:177], v170 offset:12288
	ds_read_b128 v[170:173], v170 offset:14336
; #define LAS __attribute__((address_space(3)))
; DI f32x16 mfma32(bf16x8 a, bf16x8 b, f32x16 c) { return __builtin_amdgcn_mfma_f32_32x32x16_bf16(a, b, c, 0, 0, 0); }
;     ...
;   for (int kt = 0; kt < nk; ++kt) {
;     const int kn = (kt + 2 < nk) ? (kt + 2) : (nk - 1);
;     const LAS char* cur = lds + s0;
;     bf16x8 af[2][2], bfr[2][4];
; #pragma unroll
;     for (int kk = 0; kk < 2; ++kk) {
;       const int xo = kk ? x1 : x0;
;       af[kk][0] = *(const LAS bf16x8*)(cur + a_rd + xo);
;       bfr[kk][0] = *(const LAS bf16x8*)(cur + b_rd + xo);
;       bfr[kk][1] = *(const LAS bf16x8*)(cur + b_rd + 2048 + xo);
;       af[kk][1] = *(const LAS bf16x8*)(cur + a_rd + 2048 + xo);
;       bfr[kk][2] = *(const LAS bf16x8*)(cur + b_rd + 4096 + xo);
;       bfr[kk][3] = *(const LAS bf16x8*)(cur + b_rd + 6144 + xo);
;     }
;     DMA_STEP_(kn, s2);
; #pragma unroll
;     for (int kk = 0; kk < 2; ++kk) {
;       acc[0][0] = mfma32(bfr[kk][0], af[kk][0], acc[0][0]); acc[0][1] = mfma32(bfr[kk][1], af[kk][0], acc[0][1]);
;       acc[1][0] = mfma32(bfr[kk][0], af[kk][1], acc[1][0]); acc[1][1] = mfma32(bfr[kk][1], af[kk][1], acc[1][1]);
;       acc[0][2] = mfma32(bfr[kk][2], af[kk][0], acc[0][2]); acc[0][3] = mfma32(bfr[kk][3], af[kk][0], acc[0][3]);
;       acc[1][2] = mfma32(bfr[kk][2], af[kk][1], acc[1][2]); acc[1][3] = mfma32(bfr[kk][3], af[kk][1], acc[1][3]);
;     }
;     __builtin_amdgcn_sched_group_barrier(0x100, 12, 0);
;     __builtin_amdgcn_sched_group_barrier(0x010, 6, 0);
;     __builtin_amdgcn_sched_group_barrier(0x008, 16, 0);
;     asm volatile("s_waitcnt vmcnt(6) lgkmcnt(0)" ::: "memory");
;     __builtin_amdgcn_s_barrier();
;     asm volatile("" ::: "memory");
;     s0 = (s0 == 2 * STG) ? 0 : s0 + STG;
;     s2 = (s2 == 2 * STG) ? 0 : s2 + STG;
;   }
.LBB0_244:
	s_add_i32 s11, s46, 16
	s_add_i32 s10, s41, -1
	v_add_u32_e32 v142, s11, v219
	v_add_u32_e32 v150, s11, v218
	s_min_u32 s10, s10, 0x55
	v_add_u32_e32 v142, v142, v220
	v_add_u32_e32 v150, v150, v220
	s_lshl_b32 s70, s10, 6
	ds_read_b128 v[138:141], v142
	ds_read_b128 v[166:169], v150 offset:8192
	ds_read_b128 v[154:157], v150 offset:10240
	ds_read_b128 v[142:145], v142 offset:2048
	ds_read_b128 v[146:149], v150 offset:12288
	ds_read_b128 v[150:153], v150 offset:14336
	v_lshl_add_u64 v[222:223], v[192:193], 0, s[70:71]
	s_add_i32 s10, s44, s45
	v_lshl_add_u64 v[224:225], v[222:223], 0, s[24:25]
	s_mov_b32 m0, s10
	v_lshl_add_u64 v[222:223], v[222:223], 0, s[98:99]
	s_mul_i32 s100, s70, 0x400
	s_waitcnt lgkmcnt(6)
	v_mfma_f32_32x32x16_bf16 v[114:129], v[182:185], v[158:161], v[114:129]
	global_load_lds_dwordx4 v[224:225], off
	s_add_i32 m0, s10, 0x400
	v_mfma_f32_32x32x16_bf16 v[98:113], v[178:181], v[158:161], v[98:113]
	global_load_lds_dwordx4 v[222:223], off
	v_lshl_add_u64 v[224:225], v[194:195], 0, s[100:101]
	s_add_i32 s10, s43, s45
	s_add_i32 m0, s10, 0x2000
	v_mfma_f32_32x32x16_bf16 v[66:81], v[182:185], v[162:165], v[66:81]
	global_load_lds_dwordx4 v[224:225], off
	v_mfma_f32_32x32x16_bf16 v[34:49], v[178:181], v[162:165], v[34:49]
	global_load_lds_dwordx4 v[224:225], off offset:1024
	v_mfma_f32_32x32x16_bf16 v[82:97], v[174:177], v[158:161], v[82:97]
	global_load_lds_dwordx4 v[224:225], off offset:2048
	v_mfma_f32_32x32x16_bf16 v[50:65], v[170:173], v[158:161], v[50:65]
	global_load_lds_dwordx4 v[224:225], off offset:3072
	v_mfma_f32_32x32x16_bf16 v[18:33], v[174:177], v[162:165], v[18:33]
	s_add_i32 s10, s46, 0x6000
	s_cmpk_lg_u32 s46, 0xc000
	s_cselect_b32 s46, s10, 0
	s_add_i32 s10, s45, 0x6000
	s_cmpk_lg_u32 s45, 0xc000
	s_cselect_b32 s45, s10, 0
	v_mfma_f32_32x32x16_bf16 v[2:17], v[170:173], v[162:165], v[2:17]
	s_add_i32 s11, s46, 16
	s_waitcnt vmcnt(6) lgkmcnt(0)
	s_barrier
	v_add_u32_e32 v162, s11, v219
	v_add_u32_e32 v170, s11, v218
	v_add_u32_e32 v162, v162, v0
	v_add_u32_e32 v170, v170, v0
	ds_read_b128 v[158:161], v162
	ds_read_b128 v[182:185], v170 offset:8192
	ds_read_b128 v[178:181], v170 offset:10240
	ds_read_b128 v[162:165], v162 offset:2048
	ds_read_b128 v[174:177], v170 offset:12288
	ds_read_b128 v[170:173], v170 offset:14336
	v_mfma_f32_32x32x16_bf16 v[114:129], v[166:169], v[138:141], v[114:129]
	v_mfma_f32_32x32x16_bf16 v[98:113], v[154:157], v[138:141], v[98:113]
	v_mfma_f32_32x32x16_bf16 v[66:81], v[166:169], v[142:145], v[66:81]
	v_mfma_f32_32x32x16_bf16 v[34:49], v[154:157], v[142:145], v[34:49]
	v_mfma_f32_32x32x16_bf16 v[82:97], v[146:149], v[138:141], v[82:97]
	v_mfma_f32_32x32x16_bf16 v[50:65], v[150:153], v[138:141], v[50:65]
	v_mfma_f32_32x32x16_bf16 v[18:33], v[146:149], v[142:145], v[18:33]
	v_mfma_f32_32x32x16_bf16 v[2:17], v[150:153], v[142:145], v[2:17]
	s_add_i32 s11, s46, 16
	s_mov_b32 s10, s41
	v_add_u32_e32 v142, s11, v219
	v_add_u32_e32 v150, s11, v218
	s_min_u32 s10, s10, 0x55
	v_add_u32_e32 v142, v142, v220
	v_add_u32_e32 v150, v150, v220
	s_lshl_b32 s70, s10, 6
	ds_read_b128 v[138:141], v142
	ds_read_b128 v[166:169], v150 offset:8192
	ds_read_b128 v[154:157], v150 offset:10240
	ds_read_b128 v[142:145], v142 offset:2048
	ds_read_b128 v[146:149], v150 offset:12288
	ds_read_b128 v[150:153], v150 offset:14336
	v_lshl_add_u64 v[222:223], v[192:193], 0, s[70:71]
	s_add_i32 s10, s44, s45
	v_lshl_add_u64 v[224:225], v[222:223], 0, s[24:25]
	s_mov_b32 m0, s10
	v_lshl_add_u64 v[222:223], v[222:223], 0, s[98:99]
	s_mul_i32 s100, s70, 0x400
	s_waitcnt lgkmcnt(6)
	v_mfma_f32_32x32x16_bf16 v[114:129], v[182:185], v[158:161], v[114:129]
	global_load_lds_dwordx4 v[224:225], off
	s_add_i32 m0, s10, 0x400
	v_mfma_f32_32x32x16_bf16 v[98:113], v[178:181], v[158:161], v[98:113]
	global_load_lds_dwordx4 v[222:223], off
	v_lshl_add_u64 v[224:225], v[194:195], 0, s[100:101]
	s_add_i32 s10, s43, s45
	s_add_i32 m0, s10, 0x2000
	v_mfma_f32_32x32x16_bf16 v[66:81], v[182:185], v[162:165], v[66:81]
	global_load_lds_dwordx4 v[224:225], off
	v_mfma_f32_32x32x16_bf16 v[34:49], v[178:181], v[162:165], v[34:49]
	global_load_lds_dwordx4 v[224:225], off offset:1024
	v_mfma_f32_32x32x16_bf16 v[82:97], v[174:177], v[158:161], v[82:97]
	global_load_lds_dwordx4 v[224:225], off offset:2048
	v_mfma_f32_32x32x16_bf16 v[50:65], v[170:173], v[158:161], v[50:65]
	global_load_lds_dwordx4 v[224:225], off offset:3072
	v_mfma_f32_32x32x16_bf16 v[18:33], v[174:177], v[162:165], v[18:33]
	s_add_i32 s10, s46, 0x6000
	s_cmpk_lg_u32 s46, 0xc000
	s_cselect_b32 s46, s10, 0
	s_add_i32 s10, s45, 0x6000
	s_cmpk_lg_u32 s45, 0xc000
	s_cselect_b32 s45, s10, 0
	v_mfma_f32_32x32x16_bf16 v[2:17], v[170:173], v[162:165], v[2:17]
	s_add_i32 s11, s46, 16
	s_waitcnt vmcnt(6) lgkmcnt(0)
	s_barrier
	v_add_u32_e32 v162, s11, v219
	v_add_u32_e32 v170, s11, v218
	v_add_u32_e32 v162, v162, v0
	v_add_u32_e32 v170, v170, v0
	ds_read_b128 v[158:161], v162
	ds_read_b128 v[182:185], v170 offset:8192
	ds_read_b128 v[178:181], v170 offset:10240
	ds_read_b128 v[162:165], v162 offset:2048
	ds_read_b128 v[174:177], v170 offset:12288
	ds_read_b128 v[170:173], v170 offset:14336
	v_mfma_f32_32x32x16_bf16 v[114:129], v[166:169], v[138:141], v[114:129]
	v_mfma_f32_32x32x16_bf16 v[98:113], v[154:157], v[138:141], v[98:113]
	v_mfma_f32_32x32x16_bf16 v[66:81], v[166:169], v[142:145], v[66:81]
	v_mfma_f32_32x32x16_bf16 v[34:49], v[154:157], v[142:145], v[34:49]
	v_mfma_f32_32x32x16_bf16 v[82:97], v[146:149], v[138:141], v[82:97]
	v_mfma_f32_32x32x16_bf16 v[50:65], v[150:153], v[138:141], v[50:65]
	v_mfma_f32_32x32x16_bf16 v[18:33], v[146:149], v[142:145], v[18:33]
	v_mfma_f32_32x32x16_bf16 v[2:17], v[150:153], v[142:145], v[2:17]
	s_add_i32 s41, s41, 2
	s_cmpk_lg_i32 s41, 0x59
	s_cbranch_scc1 .LBB0_244
; DI unsigned pk2(float a, float b) { f32x2 v = {a, b}; bf2_t r = __builtin_convertvector(v, bf2_t); return __builtin_bit_cast(unsigned, r); }
;     ...
;   asm volatile("s_waitcnt vmcnt(0)" ::: "memory");
;   __builtin_amdgcn_s_barrier();
;   asm volatile("" ::: "memory");
;     ...
;   {
;     const int h = lane >> 5, cl = lane & 31;
; #pragma unroll
;     for (int i = 0; i < 2; ++i)
; #pragma unroll
;       for (int j = 0; j < 4; ++j)
; #pragma unroll
;         for (int g = 0; g < 4; ++g) {
;           u32x2 w; w.x = pk2(acc[i][j][4 * g], acc[i][j][4 * g + 1]); w.y = pk2(acc[i][j][4 * g + 2], acc[i][j][4 * g + 3]);
;           *(u32x2*)(smem + (wr * 64 + i * 32 + cl) * 528 + (wc * 128 + j * 32 + 8 * g + 4 * h) * 2) = w;
;         }
;   }
;   __syncthreads();
	s_waitcnt lgkmcnt(0)
	v_mul_lo_u32 v0, v197, s55
	v_add_u32_e32 v0, 16, v0
	s_nop 1
	v_cvt_pk_bf16_f32 v114, v114, v115
	v_cvt_pk_bf16_f32 v115, v116, v117
	v_lshlrev_b32_e32 v116, 3, v196
	s_lshl_b32 s10, s42, 1
	v_add3_u32 v0, v0, v116, s10
	v_cvt_pk_bf16_f32 v116, v118, v119
	v_cvt_pk_bf16_f32 v117, v120, v121
	v_cvt_pk_bf16_f32 v98, v98, v99
	v_cvt_pk_bf16_f32 v99, v100, v101
	v_cvt_pk_bf16_f32 v100, v102, v103
	v_cvt_pk_bf16_f32 v101, v104, v105
	v_cvt_pk_bf16_f32 v82, v82, v83
	v_cvt_pk_bf16_f32 v83, v84, v85
	v_cvt_pk_bf16_f32 v84, v86, v87
	v_cvt_pk_bf16_f32 v85, v88, v89
	v_cvt_pk_bf16_f32 v50, v50, v51
	v_cvt_pk_bf16_f32 v51, v52, v53
	v_cvt_pk_bf16_f32 v52, v54, v55
	v_cvt_pk_bf16_f32 v53, v56, v57
	s_waitcnt vmcnt(0)
	s_barrier
	ds_write2_b64 v0, v[114:115], v[116:117] offset1:2
	v_cvt_pk_bf16_f32 v114, v122, v123
	v_cvt_pk_bf16_f32 v115, v124, v125
	v_cvt_pk_bf16_f32 v116, v126, v127
	v_cvt_pk_bf16_f32 v117, v128, v129
	ds_write2_b64 v0, v[98:99], v[100:101] offset0:8 offset1:10
	v_cvt_pk_bf16_f32 v98, v106, v107
	v_cvt_pk_bf16_f32 v99, v108, v109
	v_cvt_pk_bf16_f32 v100, v110, v111
	v_cvt_pk_bf16_f32 v101, v112, v113
	ds_write2_b64 v0, v[82:83], v[84:85] offset0:16 offset1:18
	v_cvt_pk_bf16_f32 v82, v90, v91
	v_cvt_pk_bf16_f32 v83, v92, v93
	v_cvt_pk_bf16_f32 v84, v94, v95
	v_cvt_pk_bf16_f32 v85, v96, v97
	ds_write2_b64 v0, v[50:51], v[52:53] offset0:24 offset1:26
	v_cvt_pk_bf16_f32 v50, v58, v59
	v_cvt_pk_bf16_f32 v51, v60, v61
	v_cvt_pk_bf16_f32 v52, v62, v63
	v_cvt_pk_bf16_f32 v53, v64, v65
	ds_write2_b64 v0, v[114:115], v[116:117] offset0:4 offset1:6
	ds_write2_b64 v0, v[98:99], v[100:101] offset0:12 offset1:14
	ds_write2_b64 v0, v[82:83], v[84:85] offset0:20 offset1:22
	ds_write2_b64 v0, v[50:51], v[52:53] offset0:28 offset1:30
	v_cvt_pk_bf16_f32 v50, v66, v67
	v_cvt_pk_bf16_f32 v51, v68, v69
	v_cvt_pk_bf16_f32 v52, v70, v71
	v_cvt_pk_bf16_f32 v53, v72, v73
	v_add_u32_e32 v0, 0x4000, v0
	v_cvt_pk_bf16_f32 v34, v34, v35
	v_cvt_pk_bf16_f32 v35, v36, v37
	v_cvt_pk_bf16_f32 v36, v38, v39
	v_cvt_pk_bf16_f32 v37, v40, v41
	v_cvt_pk_bf16_f32 v18, v18, v19
	v_cvt_pk_bf16_f32 v19, v20, v21
	v_cvt_pk_bf16_f32 v20, v22, v23
	v_cvt_pk_bf16_f32 v21, v24, v25
	v_cvt_pk_bf16_f32 v2, v2, v3
	v_cvt_pk_bf16_f32 v3, v4, v5
	v_cvt_pk_bf16_f32 v4, v6, v7
	v_cvt_pk_bf16_f32 v5, v8, v9
	ds_write2_b64 v0, v[50:51], v[52:53] offset0:64 offset1:66
	v_cvt_pk_bf16_f32 v50, v74, v75
	v_cvt_pk_bf16_f32 v51, v76, v77
	v_cvt_pk_bf16_f32 v52, v78, v79
	v_cvt_pk_bf16_f32 v53, v80, v81
	ds_write2_b64 v0, v[34:35], v[36:37] offset0:72 offset1:74
	v_cvt_pk_bf16_f32 v34, v42, v43
	v_cvt_pk_bf16_f32 v35, v44, v45
	v_cvt_pk_bf16_f32 v36, v46, v47
	v_cvt_pk_bf16_f32 v37, v48, v49
	ds_write2_b64 v0, v[18:19], v[20:21] offset0:80 offset1:82
	v_cvt_pk_bf16_f32 v18, v26, v27
	v_cvt_pk_bf16_f32 v19, v28, v29
	v_cvt_pk_bf16_f32 v20, v30, v31
	v_cvt_pk_bf16_f32 v21, v32, v33
	ds_write2_b64 v0, v[2:3], v[4:5] offset0:88 offset1:90
	v_cvt_pk_bf16_f32 v2, v10, v11
	v_cvt_pk_bf16_f32 v3, v12, v13
	v_cvt_pk_bf16_f32 v4, v14, v15
	v_cvt_pk_bf16_f32 v5, v16, v17
	s_lshl_b64 s[10:11], s[16:17], 1
	ds_write2_b64 v0, v[50:51], v[52:53] offset0:68 offset1:70
	ds_write2_b64 v0, v[34:35], v[36:37] offset0:76 offset1:78
	ds_write2_b64 v0, v[18:19], v[20:21] offset0:84 offset1:86
	ds_write2_b64 v0, v[2:3], v[4:5] offset0:92 offset1:94
	s_waitcnt vmcnt(0) lgkmcnt(0)
	s_barrier
; #define GAS __attribute__((address_space(1)))
;     ...
;   int tid2 = tid; asm volatile("" : "+v"(tid2));
;   if (EPI == 0) {
; #pragma unroll
;     for (int i = 0; i < 16; ++i) {
;       const int id = tid2 + 256 * i, r = id >> 5, c8 = (id & 31) * 8;
;       const u32x4 v = *(const u32x4*)(smem + r * 528 + c8 * 2);
;       *(GAS u32x4*)(ea.out + (size_t)(m0 + r) * ea.ldo + n0 + c8) = v;
;     }
	s_add_u32 s10, s21, s10
	v_lshlrev_b32_e32 v0, 4, v189
	v_and_b32_e32 v0, 0x1f0, v0
	s_addc_u32 s11, s22, s11
	v_add_u32_e32 v10, 16, v0
	v_lshl_add_u64 v[12:13], s[10:11], 0, v[0:1]
	v_ashrrev_i32_e32 v0, 5, v189
	v_mad_u64_u32 v[2:3], s[10:11], v0, s55, v[10:11]
	ds_read_b128 v[2:5], v2
	v_add_u32_e32 v6, s40, v0
	v_ashrrev_i32_e32 v7, 31, v6
	v_add_u32_e32 v0, 0x100, v189
	v_lshlrev_b64 v[6:7], 11, v[6:7]
	v_ashrrev_i32_e32 v0, 5, v0
	v_lshl_add_u64 v[14:15], v[12:13], 0, v[6:7]
	v_mad_u64_u32 v[6:7], s[10:11], v0, s55, v[10:11]
	ds_read_b128 v[6:9], v6
	s_waitcnt lgkmcnt(1)
	global_store_dwordx4 v[14:15], v[2:5], off
	s_nop 1
	v_add_u32_e32 v2, s40, v0
	v_ashrrev_i32_e32 v3, 31, v2
	v_lshlrev_b64 v[2:3], 11, v[2:3]
	v_add_u32_e32 v0, 0x200, v189
	v_lshl_add_u64 v[2:3], v[12:13], 0, v[2:3]
	v_ashrrev_i32_e32 v0, 5, v0
	s_waitcnt lgkmcnt(0)
	global_store_dwordx4 v[2:3], v[6:9], off
	v_mad_u64_u32 v[2:3], s[10:11], v0, s55, v[10:11]
	ds_read_b128 v[2:5], v2
	v_add_u32_e32 v6, s40, v0
	v_ashrrev_i32_e32 v7, 31, v6
	v_add_u32_e32 v0, 0x300, v189
	v_lshlrev_b64 v[6:7], 11, v[6:7]
	v_ashrrev_i32_e32 v0, 5, v0
	v_lshl_add_u64 v[14:15], v[12:13], 0, v[6:7]
	v_mad_u64_u32 v[6:7], s[10:11], v0, s55, v[10:11]
	ds_read_b128 v[6:9], v6
	s_waitcnt lgkmcnt(1)
	global_store_dwordx4 v[14:15], v[2:5], off
	s_nop 1
	v_add_u32_e32 v2, s40, v0
	v_ashrrev_i32_e32 v3, 31, v2
	v_lshlrev_b64 v[2:3], 11, v[2:3]
	v_add_u32_e32 v0, 0x400, v189
	v_lshl_add_u64 v[2:3], v[12:13], 0, v[2:3]
	v_ashrrev_i32_e32 v0, 5, v0
	s_waitcnt lgkmcnt(0)
	global_store_dwordx4 v[2:3], v[6:9], off
	v_mad_u64_u32 v[2:3], s[10:11], v0, s55, v[10:11]
	ds_read_b128 v[2:5], v2
	v_add_u32_e32 v6, s40, v0
	v_ashrrev_i32_e32 v7, 31, v6
	v_add_u32_e32 v0, 0x500, v189
	v_lshlrev_b64 v[6:7], 11, v[6:7]
	v_ashrrev_i32_e32 v0, 5, v0
	v_lshl_add_u64 v[14:15], v[12:13], 0, v[6:7]
	v_mad_u64_u32 v[6:7], s[10:11], v0, s55, v[10:11]
	ds_read_b128 v[6:9], v6
	s_waitcnt lgkmcnt(1)
	global_store_dwordx4 v[14:15], v[2:5], off
	s_nop 1
	v_add_u32_e32 v2, s40, v0
	v_ashrrev_i32_e32 v3, 31, v2
	v_lshlrev_b64 v[2:3], 11, v[2:3]
	v_add_u32_e32 v0, 0x600, v189
	v_lshl_add_u64 v[2:3], v[12:13], 0, v[2:3]
	v_ashrrev_i32_e32 v0, 5, v0
	s_waitcnt lgkmcnt(0)
	global_store_dwordx4 v[2:3], v[6:9], off
	v_mad_u64_u32 v[2:3], s[10:11], v0, s55, v[10:11]
	ds_read_b128 v[2:5], v2
	v_add_u32_e32 v6, s40, v0
	v_ashrrev_i32_e32 v7, 31, v6
	v_add_u32_e32 v0, 0x700, v189
	v_lshlrev_b64 v[6:7], 11, v[6:7]
	v_ashrrev_i32_e32 v0, 5, v0
	v_lshl_add_u64 v[14:15], v[12:13], 0, v[6:7]
	v_mad_u64_u32 v[6:7], s[10:11], v0, s55, v[10:11]
	ds_read_b128 v[6:9], v6
	s_waitcnt lgkmcnt(1)
	global_store_dwordx4 v[14:15], v[2:5], off
	s_nop 1
	v_add_u32_e32 v2, s40, v0
	v_ashrrev_i32_e32 v3, 31, v2
	v_lshlrev_b64 v[2:3], 11, v[2:3]
	v_add_u32_e32 v0, 0x800, v189
	v_lshl_add_u64 v[2:3], v[12:13], 0, v[2:3]
	v_ashrrev_i32_e32 v0, 5, v0
	s_waitcnt lgkmcnt(0)
	global_store_dwordx4 v[2:3], v[6:9], off
	v_mad_u64_u32 v[2:3], s[10:11], v0, s55, v[10:11]
	ds_read_b128 v[2:5], v2
	v_add_u32_e32 v6, s40, v0
	v_ashrrev_i32_e32 v7, 31, v6
	v_add_u32_e32 v0, 0x900, v189
	v_lshlrev_b64 v[6:7], 11, v[6:7]
	v_ashrrev_i32_e32 v0, 5, v0
	v_lshl_add_u64 v[14:15], v[12:13], 0, v[6:7]
	v_mad_u64_u32 v[6:7], s[10:11], v0, s55, v[10:11]
	ds_read_b128 v[6:9], v6
	s_waitcnt lgkmcnt(1)
	global_store_dwordx4 v[14:15], v[2:5], off
	s_nop 1
	v_add_u32_e32 v2, s40, v0
	v_ashrrev_i32_e32 v3, 31, v2
	v_lshlrev_b64 v[2:3], 11, v[2:3]
	v_add_u32_e32 v0, 0xa00, v189
	v_lshl_add_u64 v[2:3], v[12:13], 0, v[2:3]
	v_ashrrev_i32_e32 v0, 5, v0
	s_waitcnt lgkmcnt(0)
	global_store_dwordx4 v[2:3], v[6:9], off
	v_mad_u64_u32 v[2:3], s[10:11], v0, s55, v[10:11]
	ds_read_b128 v[2:5], v2
	v_add_u32_e32 v6, s40, v0
	v_ashrrev_i32_e32 v7, 31, v6
	v_add_u32_e32 v0, 0xb00, v189
	v_lshlrev_b64 v[6:7], 11, v[6:7]
	v_ashrrev_i32_e32 v0, 5, v0
	v_lshl_add_u64 v[14:15], v[12:13], 0, v[6:7]
	v_mad_u64_u32 v[6:7], s[10:11], v0, s55, v[10:11]
	ds_read_b128 v[6:9], v6
	s_waitcnt lgkmcnt(1)
	global_store_dwordx4 v[14:15], v[2:5], off
	s_nop 1
	v_add_u32_e32 v2, s40, v0
	v_ashrrev_i32_e32 v3, 31, v2
	v_lshlrev_b64 v[2:3], 11, v[2:3]
	v_add_u32_e32 v0, 0xc00, v189
	v_lshl_add_u64 v[2:3], v[12:13], 0, v[2:3]
	v_ashrrev_i32_e32 v0, 5, v0
	s_waitcnt lgkmcnt(0)
	global_store_dwordx4 v[2:3], v[6:9], off
	v_mad_u64_u32 v[2:3], s[10:11], v0, s55, v[10:11]
	ds_read_b128 v[2:5], v2
	v_add_u32_e32 v6, s40, v0
	v_ashrrev_i32_e32 v7, 31, v6
	v_add_u32_e32 v0, 0xd00, v189
	v_lshlrev_b64 v[6:7], 11, v[6:7]
	v_ashrrev_i32_e32 v0, 5, v0
	v_lshl_add_u64 v[14:15], v[12:13], 0, v[6:7]
	v_mad_u64_u32 v[6:7], s[10:11], v0, s55, v[10:11]
	ds_read_b128 v[6:9], v6
	s_waitcnt lgkmcnt(1)
	global_store_dwordx4 v[14:15], v[2:5], off
	s_nop 1
	v_add_u32_e32 v2, s40, v0
	v_ashrrev_i32_e32 v3, 31, v2
	v_lshlrev_b64 v[2:3], 11, v[2:3]
	v_add_u32_e32 v0, 0xe00, v189
	v_lshl_add_u64 v[2:3], v[12:13], 0, v[2:3]
	v_ashrrev_i32_e32 v0, 5, v0
	s_waitcnt lgkmcnt(0)
	global_store_dwordx4 v[2:3], v[6:9], off
	v_mad_u64_u32 v[2:3], s[10:11], v0, s55, v[10:11]
	ds_read_b128 v[2:5], v2
	v_add_u32_e32 v6, s40, v0
	v_ashrrev_i32_e32 v7, 31, v6
	v_add_u32_e32 v0, 0xf00, v189
	v_lshlrev_b64 v[6:7], 11, v[6:7]
	v_ashrrev_i32_e32 v0, 5, v0
	v_lshl_add_u64 v[14:15], v[12:13], 0, v[6:7]
	v_mad_u64_u32 v[6:7], s[10:11], v0, s55, v[10:11]
	ds_read_b128 v[6:9], v6
	s_waitcnt lgkmcnt(1)
	global_store_dwordx4 v[14:15], v[2:5], off
	v_readlane_b32 s10, v252, 12
	s_add_i32 s29, s29, s10
	v_add_u32_e32 v2, s40, v0
	v_ashrrev_i32_e32 v3, 31, v2
	v_lshlrev_b64 v[2:3], 11, v[2:3]
	v_lshl_add_u64 v[2:3], v[12:13], 0, v[2:3]
	s_cmp_ge_i32 s29, s18
	s_waitcnt lgkmcnt(0)
	global_store_dwordx4 v[2:3], v[6:9], off
	s_barrier
	s_cbranch_scc0 .LBB0_243

; #define LAS __attribute__((address_space(3)))
;   int tid = tid_in; asm volatile("" : "+v"(tid));
;   const int lane = tid & 63, wid = __builtin_amdgcn_readfirstlane(tid >> 6), wr = wid >> 1, wc = wid & 1;
;   const int m0 = mt * 128, n0 = nt * 256;
;   const int r = lane & 31, h = lane >> 5, key = (r >> 2) & 3;
;   constexpr int STG = 24576;
;   const int rowl = lane >> 2, cch = (lane & 3) ^ ((lane >> 4) & 3);
;   const unsigned voffA = (unsigned)(rowl * lda * 2 + cch * 16), voffB = (unsigned)(rowl * K * 2 + cch * 16);
;   const char* Abase = (const char*)(A + (size_t)m0 * lda) + (size_t)(wid * 2) * 32 * lda;
;   const char* Bbase = (const char*)(Bt + (size_t)n0 * K) + (size_t)(wid * 4) * 32 * K;
;   const size_t ablk = (size_t)32 * lda, bblk = (size_t)32 * K;
;   LAS char* lds = (LAS char*)smem;
;   LAS char* ldsA = lds + (wid * 2) * 1024;
;   LAS char* ldsB = lds + 8192 + (wid * 4) * 1024;
;     ...
;   const int x0 = ((0 + h) ^ key) * 16, x1 = ((2 + h) ^ key) * 16;
;   const int a_rd = (wr * 64 + r) * 64, b_rd = 8192 + (wc * 128 + r) * 64;
;   f32x16 acc[2][4];
; #pragma unroll
;   for (int i = 0; i < 2; ++i)
; #pragma unroll
;     for (int j = 0; j < 4; ++j)
; #pragma unroll
;       for (int e = 0; e < 16; ++e) acc[i][j][e] = 0.f;
;   const int nk = K >> 5;
;   DMA_STEP_(0, 0);
;   DMA_STEP_(1, STG);
;   asm volatile("s_waitcnt vmcnt(6)" ::: "memory");
;   __builtin_amdgcn_s_barrier();
;   asm volatile("" ::: "memory");
;   int s0 = 0, s2 = 2 * STG;
.LBB0_271:
	s_mul_hi_i32 s10, s14, 0x2e8ba2e9
	s_lshr_b32 s11, s10, 31
	s_ashr_i32 s10, s10, 4
	s_add_i32 s10, s10, s11
	v_readlane_b32 s15, v252, 18
	s_mul_i32 s11, s10, 0xffffffa8
	s_lshl_b32 s10, s10, s15
	v_readlane_b32 s15, v252, 41
	s_add_i32 s10, s10, s15
	s_lshr_b32 s15, s10, 31
	s_add_i32 s15, s10, s15
	s_and_b32 s18, s15, -2
	s_add_i32 s11, s11, s14
	s_sub_i32 s10, s10, s18
	s_mul_i32 s22, s10, 11
	s_ashr_i32 s10, s11, 3
	v_mov_b32_e32 v189, v188
	s_lshl_b32 s15, s15, 2
	s_add_i32 s22, s22, s10
	s_and_b32 s15, s15, -8
	v_readfirstlane_b32 s10, v189
	s_and_b32 s18, s14, 7
	s_ashr_i32 s11, s10, 6
	s_or_b32 s15, s15, s18
	s_lshl_b32 s18, s11, 1
	s_ashr_i32 s19, s18, 31
	s_lshl_b64 s[28:29], s[18:19], 15
	s_lshl_b32 s18, s11, 2
	s_ashr_i32 s19, s18, 31
	s_ashr_i32 s10, s10, 1
	s_lshl_b32 s46, s15, 7
	s_lshl_b32 s66, s22, 8
	v_and_b32_e32 v0, 31, v189
	s_lshl_b64 s[74:75], s[18:19], 10
	s_lshl_b32 s18, s11, 12
	s_andn2_b32 s10, s10, 63
	v_lshlrev_b32_e32 v3, 4, v189
	s_ashr_i32 s47, s46, 31
	s_ashr_i32 s67, s66, 31
	s_add_i32 s19, s18, 16
	v_or_b32_e32 v197, s10, v0
	s_lshl_b32 s10, s11, 7
	v_lshlrev_b32_e32 v2, 9, v189
	v_bitop3_b32 v3, v3, 48, v189 bitop3:0x48
	s_lshl_b64 s[20:21], s[46:47], 11
	s_lshl_b64 s[40:41], s[66:67], 6
	s_add_i32 s23, s19, 0x2000
	s_and_b32 s18, s10, 0x80
	s_movk_i32 s10, 0x7800
	v_or_b32_e32 v4, s18, v0
	v_and_or_b32 v0, v2, s10, v3
	v_lshlrev_b32_e32 v10, 4, v189
	v_and_b32_e32 v10, 0x3c0, v10
	v_or_b32_e32 v10, v10, v3
	v_mov_b32_e32 v11, 0
	s_add_u32 s10, s42, s20
	s_addc_u32 s20, s43, s21
	s_add_u32 s28, s10, s28
	s_addc_u32 s29, s20, s29
	s_add_u32 s10, s87, s40
	s_addc_u32 s21, s76, s41
	s_lshl_b32 s11, s11, 11
	s_sub_i32 s20, s19, s11
	s_mov_b32 m0, s20
	v_lshl_add_u64 v[192:193], s[28:29], 0, v[0:1]
	global_load_lds_dwordx4 v0, s[28:29]
	s_add_i32 m0, s20, 0x400
	s_add_u32 s28, s10, s74
	v_lshl_add_u64 v[2:3], v[192:193], 0, s[72:73]
	s_addc_u32 s29, s21, s75
	global_load_lds_dwordx4 v[2:3], off
	v_lshl_add_u64 v[194:195], s[28:29], 0, v[10:11]
	s_mov_b32 m0, s23
	s_mov_b64 s[10:11], 0x8040
	global_load_lds_dwordx4 v[194:195], off
	global_load_lds_dwordx4 v[194:195], off offset:1024
	global_load_lds_dwordx4 v[194:195], off offset:2048
	global_load_lds_dwordx4 v[194:195], off offset:3072
	s_add_i32 m0, s20, 0x6000
	v_lshl_add_u64 v[2:3], v[192:193], 0, 64
	global_load_lds_dwordx4 v[2:3], off
	v_lshl_add_u64 v[2:3], v[192:193], 0, s[10:11]
	s_add_i32 m0, s20, 0x6400
	v_lshrrev_b32_e32 v5, 5, v189
	global_load_lds_dwordx4 v[2:3], off
	s_mov_b32 s100, 0x58000
	s_add_i32 m0, s19, 0x8000
	v_lshl_add_u64 v[2:3], v[194:195], 0, s[100:101]
	global_load_lds_dwordx4 v[2:3], off
	global_load_lds_dwordx4 v[2:3], off offset:1024
	global_load_lds_dwordx4 v[2:3], off offset:2048
	global_load_lds_dwordx4 v[2:3], off offset:3072
	v_bfe_u32 v6, v189, 2, 2
	v_lshl_add_u64 v[194:195], v[2:3], 0, s[100:101]
	v_bfe_u32 v196, v189, 5, 1
	s_waitcnt vmcnt(6)
	s_barrier
	v_bitop3_b32 v2, v5, v6, 1 bitop3:0x6c
	v_lshlrev_b32_e32 v219, 4, v2
	v_bitop3_b32 v2, v196, v6, 2 bitop3:0x36
	v_mov_b32_e32 v66, 0
	v_lshlrev_b32_e32 v218, 6, v197
	v_lshlrev_b32_e32 v0, 6, v4
	v_lshlrev_b32_e32 v220, 4, v2
	s_mov_b32 s23, 0xc000
	s_mov_b32 s28, 0
	s_mov_b32 s21, 0
	v_mov_b32_e32 v67, v66
	v_mov_b32_e32 v68, v66
	v_mov_b32_e32 v69, v66
	v_mov_b32_e32 v70, v66
	v_mov_b32_e32 v71, v66
	v_mov_b32_e32 v72, v66
	v_mov_b32_e32 v73, v66
	v_mov_b32_e32 v74, v66
	v_mov_b32_e32 v75, v66
	v_mov_b32_e32 v76, v66
	v_mov_b32_e32 v77, v66
	v_mov_b32_e32 v78, v66
	v_mov_b32_e32 v79, v66
	v_mov_b32_e32 v80, v66
	v_mov_b32_e32 v81, v66
	v_mov_b32_e32 v82, v66
	v_mov_b32_e32 v83, v66
	v_mov_b32_e32 v84, v66
	v_mov_b32_e32 v85, v66
	v_mov_b32_e32 v86, v66
	v_mov_b32_e32 v87, v66
	v_mov_b32_e32 v88, v66
	v_mov_b32_e32 v89, v66
	s_waitcnt vmcnt(0)
	v_mov_b32_e32 v90, v66
	v_mov_b32_e32 v91, v66
	v_mov_b32_e32 v92, v66
	v_mov_b32_e32 v93, v66
	v_mov_b32_e32 v94, v66
	v_mov_b32_e32 v95, v66
	v_mov_b32_e32 v96, v66
	v_mov_b32_e32 v97, v66
	v_mov_b32_e32 v18, v66
	v_mov_b32_e32 v19, v66
	v_mov_b32_e32 v20, v66
	v_mov_b32_e32 v21, v66
	v_mov_b32_e32 v22, v66
	v_mov_b32_e32 v23, v66
	v_mov_b32_e32 v24, v66
	v_mov_b32_e32 v25, v66
	v_mov_b32_e32 v26, v66
	v_mov_b32_e32 v27, v66
	v_mov_b32_e32 v28, v66
	v_mov_b32_e32 v29, v66
	v_mov_b32_e32 v30, v66
	v_mov_b32_e32 v31, v66
	v_mov_b32_e32 v32, v66
	v_mov_b32_e32 v33, v66
	v_mov_b32_e32 v2, v66
	v_mov_b32_e32 v3, v66
	v_mov_b32_e32 v4, v66
	v_mov_b32_e32 v5, v66
	v_mov_b32_e32 v6, v66
	v_mov_b32_e32 v7, v66
	v_mov_b32_e32 v8, v66
	v_mov_b32_e32 v9, v66
	v_mov_b32_e32 v10, v66
	v_mov_b32_e32 v11, v66
	v_mov_b32_e32 v12, v66
	v_mov_b32_e32 v13, v66
	v_mov_b32_e32 v14, v66
	v_mov_b32_e32 v15, v66
	v_mov_b32_e32 v16, v66
	v_mov_b32_e32 v17, v66
	v_mov_b32_e32 v114, v66
	v_mov_b32_e32 v115, v66
	v_mov_b32_e32 v116, v66
	v_mov_b32_e32 v117, v66
	v_mov_b32_e32 v118, v66
	v_mov_b32_e32 v119, v66
	v_mov_b32_e32 v120, v66
	v_mov_b32_e32 v121, v66
	v_mov_b32_e32 v122, v66
	v_mov_b32_e32 v123, v66
	v_mov_b32_e32 v124, v66
	v_mov_b32_e32 v125, v66
	v_mov_b32_e32 v126, v66
	v_mov_b32_e32 v127, v66
	v_mov_b32_e32 v128, v66
	v_mov_b32_e32 v129, v66
	v_mov_b32_e32 v98, v66
	v_mov_b32_e32 v99, v66
	v_mov_b32_e32 v100, v66
	v_mov_b32_e32 v101, v66
	v_mov_b32_e32 v102, v66
	v_mov_b32_e32 v103, v66
	v_mov_b32_e32 v104, v66
	v_mov_b32_e32 v105, v66
	v_mov_b32_e32 v106, v66
	v_mov_b32_e32 v107, v66
	v_mov_b32_e32 v108, v66
	v_mov_b32_e32 v109, v66
	v_mov_b32_e32 v110, v66
	v_mov_b32_e32 v111, v66
	v_mov_b32_e32 v112, v66
	v_mov_b32_e32 v113, v66
	v_mov_b32_e32 v50, v66
	v_mov_b32_e32 v51, v66
	v_mov_b32_e32 v52, v66
	v_mov_b32_e32 v53, v66
	v_mov_b32_e32 v54, v66
	v_mov_b32_e32 v55, v66
	v_mov_b32_e32 v56, v66
	v_mov_b32_e32 v57, v66
	v_mov_b32_e32 v58, v66
	v_mov_b32_e32 v59, v66
	v_mov_b32_e32 v60, v66
	v_mov_b32_e32 v61, v66
	v_mov_b32_e32 v62, v66
	v_mov_b32_e32 v63, v66
	v_mov_b32_e32 v64, v66
	v_mov_b32_e32 v65, v66
	v_mov_b32_e32 v34, v66
	v_mov_b32_e32 v35, v66
	v_mov_b32_e32 v36, v66
	v_mov_b32_e32 v37, v66
	v_mov_b32_e32 v38, v66
	v_mov_b32_e32 v39, v66
	v_mov_b32_e32 v40, v66
	v_mov_b32_e32 v41, v66
	v_mov_b32_e32 v42, v66
	v_mov_b32_e32 v43, v66
	v_mov_b32_e32 v44, v66
	v_mov_b32_e32 v45, v66
	v_mov_b32_e32 v46, v66
	v_mov_b32_e32 v47, v66
	v_mov_b32_e32 v48, v66
	v_mov_b32_e32 v49, v66
	v_add_u32_e32 v158, 16, v218
	v_add_u32_e32 v170, 16, v0
	v_add_u32_e32 v158, v158, v219
	v_add_u32_e32 v170, v170, v219
	ds_read_b128 v[154:157], v158
	ds_read_b128 v[182:185], v170 offset:8192
	ds_read_b128 v[178:181], v170 offset:10240
	ds_read_b128 v[158:161], v158 offset:2048
	ds_read_b128 v[174:177], v170 offset:12288
	ds_read_b128 v[170:173], v170 offset:14336
; #define LAS __attribute__((address_space(3)))
; DI f32x16 mfma32(bf16x8 a, bf16x8 b, f32x16 c) { return __builtin_amdgcn_mfma_f32_32x32x16_bf16(a, b, c, 0, 0, 0); }
;     ...
;   for (int kt = 0; kt < nk; ++kt) {
;     const int kn = (kt + 2 < nk) ? (kt + 2) : (nk - 1);
;     const LAS char* cur = lds + s0;
;     bf16x8 af[2][2], bfr[2][4];
; #pragma unroll
;     for (int kk = 0; kk < 2; ++kk) {
;       const int xo = kk ? x1 : x0;
;       af[kk][0] = *(const LAS bf16x8*)(cur + a_rd + xo);
;       bfr[kk][0] = *(const LAS bf16x8*)(cur + b_rd + xo);
;       bfr[kk][1] = *(const LAS bf16x8*)(cur + b_rd + 2048 + xo);
;       af[kk][1] = *(const LAS bf16x8*)(cur + a_rd + 2048 + xo);
;       bfr[kk][2] = *(const LAS bf16x8*)(cur + b_rd + 4096 + xo);
;       bfr[kk][3] = *(const LAS bf16x8*)(cur + b_rd + 6144 + xo);
;     }
;     DMA_STEP_(kn, s2);
; #pragma unroll
;     for (int kk = 0; kk < 2; ++kk) {
;       acc[0][0] = mfma32(bfr[kk][0], af[kk][0], acc[0][0]); acc[0][1] = mfma32(bfr[kk][1], af[kk][0], acc[0][1]);
;       acc[1][0] = mfma32(bfr[kk][0], af[kk][1], acc[1][0]); acc[1][1] = mfma32(bfr[kk][1], af[kk][1], acc[1][1]);
;       acc[0][2] = mfma32(bfr[kk][2], af[kk][0], acc[0][2]); acc[0][3] = mfma32(bfr[kk][3], af[kk][0], acc[0][3]);
;       acc[1][2] = mfma32(bfr[kk][2], af[kk][1], acc[1][2]); acc[1][3] = mfma32(bfr[kk][3], af[kk][1], acc[1][3]);
;     }
;     __builtin_amdgcn_sched_group_barrier(0x100, 12, 0);
;     __builtin_amdgcn_sched_group_barrier(0x010, 6, 0);
;     __builtin_amdgcn_sched_group_barrier(0x008, 16, 0);
;     asm volatile("s_waitcnt vmcnt(6) lgkmcnt(0)" ::: "memory");
;     __builtin_amdgcn_s_barrier();
;     asm volatile("" ::: "memory");
;     s0 = (s0 == 2 * STG) ? 0 : s0 + STG;
;     s2 = (s2 == 2 * STG) ? 0 : s2 + STG;
;   }
.LBB0_272:
	s_add_i32 s11, s28, 16
	s_mov_b32 s10, s21
	v_add_u32_e32 v142, s11, v218
	v_add_u32_e32 v150, s11, v0
	s_min_u32 s10, s10, 29
	v_add_u32_e32 v142, v142, v220
	v_add_u32_e32 v150, v150, v220
	s_lshl_b32 s70, s10, 6
	ds_read_b128 v[138:141], v142
	ds_read_b128 v[162:165], v150 offset:8192
	ds_read_b128 v[166:169], v150 offset:10240
	ds_read_b128 v[142:145], v142 offset:2048
	ds_read_b128 v[146:149], v150 offset:12288
	ds_read_b128 v[150:153], v150 offset:14336
	v_lshl_add_u64 v[222:223], v[192:193], 0, s[70:71]
	s_add_i32 s10, s20, s23
	v_lshl_add_u64 v[224:225], v[222:223], 0, s[24:25]
	s_mov_b32 m0, s10
	v_lshl_add_u64 v[222:223], v[222:223], 0, s[38:39]
	s_mul_i32 s100, s70, 0x1600
	s_waitcnt lgkmcnt(6)
	v_mfma_f32_32x32x16_bf16 v[66:81], v[182:185], v[154:157], v[66:81]
	global_load_lds_dwordx4 v[224:225], off
	s_add_i32 m0, s10, 0x400
	v_mfma_f32_32x32x16_bf16 v[82:97], v[178:181], v[154:157], v[82:97]
	global_load_lds_dwordx4 v[222:223], off
	v_lshl_add_u64 v[224:225], v[194:195], 0, s[100:101]
	s_add_i32 s10, s19, s23
	s_add_i32 m0, s10, 0x2000
	v_mfma_f32_32x32x16_bf16 v[18:33], v[182:185], v[158:161], v[18:33]
	global_load_lds_dwordx4 v[224:225], off
	v_mfma_f32_32x32x16_bf16 v[2:17], v[178:181], v[158:161], v[2:17]
	global_load_lds_dwordx4 v[224:225], off offset:1024
	v_mfma_f32_32x32x16_bf16 v[114:129], v[174:177], v[154:157], v[114:129]
	global_load_lds_dwordx4 v[224:225], off offset:2048
	v_mfma_f32_32x32x16_bf16 v[98:113], v[170:173], v[154:157], v[98:113]
	global_load_lds_dwordx4 v[224:225], off offset:3072
	v_mfma_f32_32x32x16_bf16 v[50:65], v[174:177], v[158:161], v[50:65]
	s_add_i32 s10, s28, 0x6000
	s_cmpk_lg_u32 s28, 0xc000
	s_cselect_b32 s28, s10, 0
	s_add_i32 s10, s23, 0x6000
	s_cmpk_lg_u32 s23, 0xc000
	s_cselect_b32 s23, s10, 0
	v_mfma_f32_32x32x16_bf16 v[34:49], v[170:173], v[158:161], v[34:49]
	s_add_i32 s11, s28, 16
	s_waitcnt vmcnt(6) lgkmcnt(0)
	s_barrier
	v_add_u32_e32 v158, s11, v218
	v_add_u32_e32 v170, s11, v0
	v_add_u32_e32 v158, v158, v219
	v_add_u32_e32 v170, v170, v219
	ds_read_b128 v[154:157], v158
	ds_read_b128 v[182:185], v170 offset:8192
	ds_read_b128 v[178:181], v170 offset:10240
	ds_read_b128 v[158:161], v158 offset:2048
	ds_read_b128 v[174:177], v170 offset:12288
	ds_read_b128 v[170:173], v170 offset:14336
	v_mfma_f32_32x32x16_bf16 v[66:81], v[162:165], v[138:141], v[66:81]
	v_mfma_f32_32x32x16_bf16 v[82:97], v[166:169], v[138:141], v[82:97]
	v_mfma_f32_32x32x16_bf16 v[18:33], v[162:165], v[142:145], v[18:33]
	v_mfma_f32_32x32x16_bf16 v[2:17], v[166:169], v[142:145], v[2:17]
	v_mfma_f32_32x32x16_bf16 v[114:129], v[146:149], v[138:141], v[114:129]
	v_mfma_f32_32x32x16_bf16 v[98:113], v[150:153], v[138:141], v[98:113]
	v_mfma_f32_32x32x16_bf16 v[50:65], v[146:149], v[142:145], v[50:65]
	v_mfma_f32_32x32x16_bf16 v[34:49], v[150:153], v[142:145], v[34:49]
	s_add_i32 s11, s28, 16
	s_add_i32 s10, s21, 1
	v_add_u32_e32 v142, s11, v218
	v_add_u32_e32 v150, s11, v0
	s_min_u32 s10, s10, 29
	v_add_u32_e32 v142, v142, v220
	v_add_u32_e32 v150, v150, v220
	s_lshl_b32 s70, s10, 6
	ds_read_b128 v[138:141], v142
	ds_read_b128 v[162:165], v150 offset:8192
	ds_read_b128 v[166:169], v150 offset:10240
	ds_read_b128 v[142:145], v142 offset:2048
	ds_read_b128 v[146:149], v150 offset:12288
	ds_read_b128 v[150:153], v150 offset:14336
	v_lshl_add_u64 v[222:223], v[192:193], 0, s[70:71]
	s_add_i32 s10, s20, s23
	v_lshl_add_u64 v[224:225], v[222:223], 0, s[24:25]
	s_mov_b32 m0, s10
	v_lshl_add_u64 v[222:223], v[222:223], 0, s[38:39]
	s_mul_i32 s100, s70, 0x1600
	s_waitcnt lgkmcnt(6)
	v_mfma_f32_32x32x16_bf16 v[66:81], v[182:185], v[154:157], v[66:81]
	global_load_lds_dwordx4 v[224:225], off
	s_add_i32 m0, s10, 0x400
	v_mfma_f32_32x32x16_bf16 v[82:97], v[178:181], v[154:157], v[82:97]
	global_load_lds_dwordx4 v[222:223], off
	v_lshl_add_u64 v[224:225], v[194:195], 0, s[100:101]
	s_add_i32 s10, s19, s23
	s_add_i32 m0, s10, 0x2000
	v_mfma_f32_32x32x16_bf16 v[18:33], v[182:185], v[158:161], v[18:33]
	global_load_lds_dwordx4 v[224:225], off
	v_mfma_f32_32x32x16_bf16 v[2:17], v[178:181], v[158:161], v[2:17]
	global_load_lds_dwordx4 v[224:225], off offset:1024
	v_mfma_f32_32x32x16_bf16 v[114:129], v[174:177], v[154:157], v[114:129]
	global_load_lds_dwordx4 v[224:225], off offset:2048
	v_mfma_f32_32x32x16_bf16 v[98:113], v[170:173], v[154:157], v[98:113]
	global_load_lds_dwordx4 v[224:225], off offset:3072
	v_mfma_f32_32x32x16_bf16 v[50:65], v[174:177], v[158:161], v[50:65]
	s_add_i32 s10, s28, 0x6000
	s_cmpk_lg_u32 s28, 0xc000
	s_cselect_b32 s28, s10, 0
	s_add_i32 s10, s23, 0x6000
	s_cmpk_lg_u32 s23, 0xc000
	s_cselect_b32 s23, s10, 0
	v_mfma_f32_32x32x16_bf16 v[34:49], v[170:173], v[158:161], v[34:49]
	s_add_i32 s11, s28, 16
	s_waitcnt vmcnt(6) lgkmcnt(0)
	s_barrier
; DI unsigned pk2(float a, float b) { f32x2 v = {a, b}; bf2_t r = __builtin_convertvector(v, bf2_t); return __builtin_bit_cast(unsigned, r); }
; DI f32x16 mfma32(bf16x8 a, bf16x8 b, f32x16 c) { return __builtin_amdgcn_mfma_f32_32x32x16_bf16(a, b, c, 0, 0, 0); }
;     ...
;       acc[0][0] = mfma32(bfr[kk][0], af[kk][0], acc[0][0]); acc[0][1] = mfma32(bfr[kk][1], af[kk][0], acc[0][1]);
;       acc[1][0] = mfma32(bfr[kk][0], af[kk][1], acc[1][0]); acc[1][1] = mfma32(bfr[kk][1], af[kk][1], acc[1][1]);
;       acc[0][2] = mfma32(bfr[kk][2], af[kk][0], acc[0][2]); acc[0][3] = mfma32(bfr[kk][3], af[kk][0], acc[0][3]);
;       acc[1][2] = mfma32(bfr[kk][2], af[kk][1], acc[1][2]); acc[1][3] = mfma32(bfr[kk][3], af[kk][1], acc[1][3]);
;     }
;     __builtin_amdgcn_sched_group_barrier(0x100, 12, 0);
;     __builtin_amdgcn_sched_group_barrier(0x010, 6, 0);
;     __builtin_amdgcn_sched_group_barrier(0x008, 16, 0);
;     asm volatile("s_waitcnt vmcnt(6) lgkmcnt(0)" ::: "memory");
;     __builtin_amdgcn_s_barrier();
;     asm volatile("" ::: "memory");
;     s0 = (s0 == 2 * STG) ? 0 : s0 + STG;
;     s2 = (s2 == 2 * STG) ? 0 : s2 + STG;
;   }
;   asm volatile("s_waitcnt vmcnt(0)" ::: "memory");
;   __builtin_amdgcn_s_barrier();
;   asm volatile("" ::: "memory");
;     ...
;   {
;     const int h = lane >> 5, cl = lane & 31;
; #pragma unroll
;     for (int i = 0; i < 2; ++i)
; #pragma unroll
;       for (int j = 0; j < 4; ++j)
; #pragma unroll
;         for (int g = 0; g < 4; ++g) {
;           u32x2 w; w.x = pk2(acc[i][j][4 * g], acc[i][j][4 * g + 1]); w.y = pk2(acc[i][j][4 * g + 2], acc[i][j][4 * g + 3]);
;           *(u32x2*)(smem + (wr * 64 + i * 32 + cl) * 528 + (wc * 128 + j * 32 + 8 * g + 4 * h) * 2) = w;
;         }
;   }
;   __syncthreads();
;     ...
;     const int L = (mt < 512) ? 2048 : 256;
;     const bool first = (m0 % L) == 0, last = ((m0 + 128) % L) == 0;
;     const float* cw = ea.cw; const float* cb = ea.cb;
; #pragma unroll 1
;     for (int p = 0; p < 2; ++p) {
;       const int j8 = (tid2 & 7) * 8;
;       const int ja0 = (nt * 2 + p) * 64, ja = ja0 + j8;
;       f32x4 wa[4][2], wg[4][2];
	v_add_u32_e32 v158, s11, v218
	v_add_u32_e32 v170, s11, v0
	v_add_u32_e32 v158, v158, v219
	v_add_u32_e32 v170, v170, v219
	ds_read_b128 v[154:157], v158
	ds_read_b128 v[182:185], v170 offset:8192
	ds_read_b128 v[178:181], v170 offset:10240
	ds_read_b128 v[158:161], v158 offset:2048
	ds_read_b128 v[174:177], v170 offset:12288
	ds_read_b128 v[170:173], v170 offset:14336
	v_mfma_f32_32x32x16_bf16 v[66:81], v[162:165], v[138:141], v[66:81]
	v_mfma_f32_32x32x16_bf16 v[82:97], v[166:169], v[138:141], v[82:97]
	v_mfma_f32_32x32x16_bf16 v[18:33], v[162:165], v[142:145], v[18:33]
	v_mfma_f32_32x32x16_bf16 v[2:17], v[166:169], v[142:145], v[2:17]
	v_mfma_f32_32x32x16_bf16 v[114:129], v[146:149], v[138:141], v[114:129]
	v_mfma_f32_32x32x16_bf16 v[98:113], v[150:153], v[138:141], v[98:113]
	v_mfma_f32_32x32x16_bf16 v[50:65], v[146:149], v[142:145], v[50:65]
	v_mfma_f32_32x32x16_bf16 v[34:49], v[150:153], v[142:145], v[34:49]
	s_add_i32 s21, s21, 2
	s_cmp_eq_u32 s21, 32
	s_cbranch_scc0 .LBB0_272
	s_waitcnt lgkmcnt(0)
	v_mul_lo_u32 v0, v197, s55
	v_add_u32_e32 v0, 16, v0
	s_nop 1
	v_cvt_pk_bf16_f32 v66, v66, v67
	v_cvt_pk_bf16_f32 v67, v68, v69
	v_lshlrev_b32_e32 v68, 3, v196
	s_lshl_b32 s10, s18, 1
	v_add3_u32 v0, v0, v68, s10
	v_cvt_pk_bf16_f32 v68, v70, v71
	v_cvt_pk_bf16_f32 v69, v72, v73
	s_waitcnt vmcnt(0)
	s_barrier
	ds_write2_b64 v0, v[66:67], v[68:69] offset1:2
	v_cvt_pk_bf16_f32 v66, v74, v75
	v_cvt_pk_bf16_f32 v67, v76, v77
	v_cvt_pk_bf16_f32 v68, v78, v79
	v_cvt_pk_bf16_f32 v69, v80, v81
	ds_write2_b64 v0, v[66:67], v[68:69] offset0:4 offset1:6
	v_cvt_pk_bf16_f32 v66, v82, v83
	v_cvt_pk_bf16_f32 v67, v84, v85
	v_cvt_pk_bf16_f32 v68, v86, v87
	v_cvt_pk_bf16_f32 v69, v88, v89
	ds_write2_b64 v0, v[66:67], v[68:69] offset0:8 offset1:10
	v_cvt_pk_bf16_f32 v66, v90, v91
	v_cvt_pk_bf16_f32 v67, v92, v93
	v_cvt_pk_bf16_f32 v68, v94, v95
	v_cvt_pk_bf16_f32 v69, v96, v97
	ds_write2_b64 v0, v[66:67], v[68:69] offset0:12 offset1:14
	v_cvt_pk_bf16_f32 v66, v114, v115
	v_cvt_pk_bf16_f32 v67, v116, v117
	v_cvt_pk_bf16_f32 v68, v118, v119
	v_cvt_pk_bf16_f32 v69, v120, v121
	ds_write2_b64 v0, v[66:67], v[68:69] offset0:16 offset1:18
	v_cvt_pk_bf16_f32 v66, v122, v123
	v_cvt_pk_bf16_f32 v67, v124, v125
	v_cvt_pk_bf16_f32 v68, v126, v127
	v_cvt_pk_bf16_f32 v69, v128, v129
	ds_write2_b64 v0, v[66:67], v[68:69] offset0:20 offset1:22
	v_cvt_pk_bf16_f32 v66, v98, v99
	v_cvt_pk_bf16_f32 v67, v100, v101
	v_cvt_pk_bf16_f32 v68, v102, v103
	v_cvt_pk_bf16_f32 v69, v104, v105
	ds_write2_b64 v0, v[66:67], v[68:69] offset0:24 offset1:26
	v_cvt_pk_bf16_f32 v66, v106, v107
	v_cvt_pk_bf16_f32 v67, v108, v109
	v_cvt_pk_bf16_f32 v68, v110, v111
	v_cvt_pk_bf16_f32 v69, v112, v113
	ds_write2_b64 v0, v[66:67], v[68:69] offset0:28 offset1:30
	v_add_u32_e32 v0, 0x4000, v0
	v_cvt_pk_bf16_f32 v2, v2, v3
	v_cvt_pk_bf16_f32 v3, v4, v5
	v_cvt_pk_bf16_f32 v4, v6, v7
	v_cvt_pk_bf16_f32 v5, v8, v9
	ds_write2_b64 v0, v[2:3], v[4:5] offset0:72 offset1:74
	v_cvt_pk_bf16_f32 v2, v10, v11
	v_cvt_pk_bf16_f32 v3, v12, v13
	v_cvt_pk_bf16_f32 v4, v14, v15
	v_cvt_pk_bf16_f32 v5, v16, v17
	ds_write2_b64 v0, v[2:3], v[4:5] offset0:76 offset1:78
	v_cvt_pk_bf16_f32 v2, v50, v51
	v_cvt_pk_bf16_f32 v3, v52, v53
	v_cvt_pk_bf16_f32 v4, v54, v55
	v_cvt_pk_bf16_f32 v5, v56, v57
	s_cmpk_lt_i32 s15, 0x200
	ds_write2_b64 v0, v[2:3], v[4:5] offset0:80 offset1:82
	v_cvt_pk_bf16_f32 v2, v58, v59
	v_cvt_pk_bf16_f32 v3, v60, v61
	v_cvt_pk_bf16_f32 v4, v62, v63
	v_cvt_pk_bf16_f32 v5, v64, v65
	s_cselect_b32 s10, 0x7ff, s78
	v_cvt_pk_bf16_f32 v18, v18, v19
	v_cvt_pk_bf16_f32 v19, v20, v21
	v_cvt_pk_bf16_f32 v20, v22, v23
	v_cvt_pk_bf16_f32 v21, v24, v25
	ds_write2_b64 v0, v[2:3], v[4:5] offset0:84 offset1:86
	v_cvt_pk_bf16_f32 v2, v34, v35
	v_cvt_pk_bf16_f32 v3, v36, v37
	v_cvt_pk_bf16_f32 v4, v38, v39
	v_cvt_pk_bf16_f32 v5, v40, v41
	s_and_b32 s11, s10, s46
	ds_write2_b64 v0, v[18:19], v[20:21] offset0:64 offset1:66
	v_cvt_pk_bf16_f32 v18, v26, v27
	v_cvt_pk_bf16_f32 v19, v28, v29
	v_cvt_pk_bf16_f32 v20, v30, v31
	v_cvt_pk_bf16_f32 v21, v32, v33
	ds_write2_b64 v0, v[2:3], v[4:5] offset0:88 offset1:90
	v_cvt_pk_bf16_f32 v2, v42, v43
	v_cvt_pk_bf16_f32 v3, v44, v45
	v_cvt_pk_bf16_f32 v4, v46, v47
	v_cvt_pk_bf16_f32 v5, v48, v49
	s_cmp_eq_u32 s11, 0
	ds_write2_b64 v0, v[18:19], v[20:21] offset0:68 offset1:70
	ds_write2_b64 v0, v[2:3], v[4:5] offset0:92 offset1:94
	s_waitcnt vmcnt(0) lgkmcnt(0)
	s_barrier
	s_cselect_b64 s[18:19], -1, 0
	s_add_i32 s11, s46, 0x80
	v_lshlrev_b32_e32 v0, 3, v189
	s_and_b32 s10, s11, s10
	v_and_b32_e32 v96, 56, v0
	s_cmp_eq_u32 s10, 0
	v_lshlrev_b32_e32 v0, 1, v96
	s_mov_b32 s40, 0
	s_cselect_b64 s[20:21], -1, 0
	s_lshl_b32 s47, s22, 7
	v_add_u32_e32 v97, 16, v0
	v_lshl_add_u64 v[90:91], s[44:45], 0, v[0:1]
	s_mov_b64 s[28:29], -1
	s_branch .LBB0_275
